# EpiPle epilogue rewritten by hand: all 8 rows loads software-pipelined (3 slots + consumed accumulators), saddr loads, fewer VALU; on top of kl3b
# speedup vs baseline: 1.0099x; 1.0099x over previous
; #define PG8_STAGE(bufoff, gbase, voff) do { _Pragma("unroll") for (int _i = 0; _i < 2; ++_i) \
;         __builtin_amdgcn_global_load_lds((const unsigned*)((const char*)(gbase) + (voff)[_i]), (PG8_LAS unsigned*)(lds + (bufoff) + ldsw + _i * 8192), 16, 0, 0); } while (0)
; #define PG8_LDA(dst, b, h) do { _Pragma("unroll") for (int m = 0; m < 4; ++m) _Pragma("unroll") for (int k = 0; k < 2; ++k) dst[m][k] = *(const PG8_LAS bf16x8*)(lds + PG8_SA(b, h) + aoff + m * 2048 + k * 1024); } while (0)
; #define PG8_LDB(dst, b, h) do { _Pragma("unroll") for (int n = 0; n < 2; ++n) _Pragma("unroll") for (int k = 0; k < 2; ++k) dst[n][k] = *(const PG8_LAS bf16x8*)(lds + PG8_SB(b, h) + boff + n * 2048 + k * 1024); } while (0)
; #define PG8_MMA(ai, bj, At, Bt) do { __builtin_amdgcn_s_setprio(1); _Pragma("unroll") for (int m = 0; m < 4; ++m) _Pragma("unroll") for (int n = 0; n < 2; ++n) _Pragma("unroll") for (int k = 0; k < 2; ++k) \
;         acc[ai][bj][m][n] = __builtin_amdgcn_mfma_f32_16x16x32_bf16(Bt[n][k], At[m][k], acc[ai][bj][m][n], 0, 0, 0); __builtin_amdgcn_s_setprio(0); } while (0)
; #define PG8_WAIT_V(n) asm volatile("s_waitcnt vmcnt(" #n ")" ::: "memory")
; #define PG8_WAIT_L(n) asm volatile("s_waitcnt lgkmcnt(" #n ")" ::: "memory")
; #define PG8_WAIT_V8_UNLESS(flag) asm volatile("s_cmp_lg_i32 %0, 0\n\ts_cbranch_scc1 .Lpg8rx%=\n\ts_waitcnt vmcnt(8)\n.Lpg8rx%=:" :: "s"(__builtin_amdgcn_readfirstlane(flag)) : "scc", "memory")
; #define PG8_BAR __builtin_amdgcn_s_barrier()
; #define PG8_SCHED __builtin_amdgcn_sched_barrier(0)
; template <class Epi, class Sched, bool ALIGN_EPI = false, bool SP2 = false>
; __device__ __forceinline__ void gemm_phase(PG8_LAS unsigned char* lds, const Gemm g, const Sched& S, const Epi& E) {
;     ...
;             PG8_WAIT_V8_UNLESS(rx); PG8_WAIT_L(0); PG8_BAR; PG8_MMA(1, 0, At, B0); PG8_MMA(1, 1, At, B1); PG8_BAR; PG8_SCHED;
;             PG8_STAGE(PG8_SA(0, 1), a2 + hstep, voffA); PG8_SCHED; PG8_LDB(B0, 1, 0); PG8_LDB(B1, 1, 1); PG8_SCHED; PG8_LDA(At, 1, 0);
;             PG8_WAIT_V(8); PG8_WAIT_L(0); PG8_BAR; PG8_MMA(0, 0, At, B0); PG8_MMA(0, 1, At, B1); PG8_BAR; PG8_SCHED;
.Lpg8rx1:
	s_waitcnt lgkmcnt(0)
	s_setprio 1
	s_barrier
	v_mfma_f32_16x16x32_bf16 v[60:63], v[144:147], v[178:181], v[60:63]
	v_mfma_f32_16x16x32_bf16 v[56:59], v[152:155], v[178:181], v[56:59]
	v_mfma_f32_16x16x32_bf16 v[44:47], v[144:147], v[186:189], v[44:47]
	v_mfma_f32_16x16x32_bf16 v[40:43], v[152:155], v[186:189], v[40:43]
	v_mfma_f32_16x16x32_bf16 v[28:31], v[144:147], v[208:211], v[28:31]
	v_mfma_f32_16x16x32_bf16 v[24:27], v[152:155], v[208:211], v[24:27]
	v_mfma_f32_16x16x32_bf16 v[12:15], v[144:147], v[216:219], v[12:15]
	v_mfma_f32_16x16x32_bf16 v[8:11], v[152:155], v[216:219], v[8:11]
	v_mfma_f32_16x16x32_bf16 v[60:63], v[148:151], v[182:185], v[60:63]
	v_mfma_f32_16x16x32_bf16 v[56:59], v[156:159], v[182:185], v[56:59]
	v_mfma_f32_16x16x32_bf16 v[44:47], v[148:151], v[204:207], v[44:47]
	v_mfma_f32_16x16x32_bf16 v[40:43], v[156:159], v[204:207], v[40:43]
	v_mfma_f32_16x16x32_bf16 v[28:31], v[148:151], v[212:215], v[28:31]
	v_mfma_f32_16x16x32_bf16 v[24:27], v[156:159], v[212:215], v[24:27]
	v_mfma_f32_16x16x32_bf16 v[12:15], v[148:151], v[220:223], v[12:15]
	v_mfma_f32_16x16x32_bf16 v[8:11], v[156:159], v[220:223], v[8:11]
	v_mfma_f32_16x16x32_bf16 v[52:55], v[160:163], v[178:181], v[52:55]
	v_mfma_f32_16x16x32_bf16 v[48:51], v[168:171], v[178:181], v[48:51]
	v_mfma_f32_16x16x32_bf16 v[36:39], v[160:163], v[186:189], v[36:39]
	v_mfma_f32_16x16x32_bf16 v[32:35], v[168:171], v[186:189], v[32:35]
	v_mfma_f32_16x16x32_bf16 v[20:23], v[160:163], v[208:211], v[20:23]
	v_mfma_f32_16x16x32_bf16 v[16:19], v[168:171], v[208:211], v[16:19]
	v_mfma_f32_16x16x32_bf16 v[4:7], v[160:163], v[216:219], v[4:7]
	v_mfma_f32_16x16x32_bf16 v[0:3], v[168:171], v[216:219], v[0:3]
	v_mfma_f32_16x16x32_bf16 v[52:55], v[164:167], v[182:185], v[52:55]
	v_mfma_f32_16x16x32_bf16 v[48:51], v[174:177], v[182:185], v[48:51]
	v_mfma_f32_16x16x32_bf16 v[36:39], v[164:167], v[204:207], v[36:39]
	v_mfma_f32_16x16x32_bf16 v[32:35], v[174:177], v[204:207], v[32:35]
	v_mfma_f32_16x16x32_bf16 v[20:23], v[164:167], v[212:215], v[20:23]
	v_mfma_f32_16x16x32_bf16 v[16:19], v[174:177], v[212:215], v[16:19]
	v_mfma_f32_16x16x32_bf16 v[4:7], v[164:167], v[220:223], v[4:7]
	v_mfma_f32_16x16x32_bf16 v[0:3], v[174:177], v[220:223], v[0:3]
	s_setprio 0
	s_barrier
	s_mov_b64 s[98:99], s[30:31]
	s_add_u32 s100, s30, 0x40000
	s_addc_u32 s101, s31, 0
	s_add_i32 s30, 0, 0x18000
	s_add_i32 s31, 0, 0x1c000
	v_add_u32_e32 v156, s30, v172
	v_add_u32_e32 v174, s31, v172
	ds_read_b128 v[144:147], v156
	ds_read_b128 v[148:151], v156 offset:1024
	ds_read_b128 v[152:155], v156 offset:2048
	ds_read_b128 v[156:159], v156 offset:3072
	ds_read_b128 v[160:163], v174
	ds_read_b128 v[164:167], v174 offset:1024
	ds_read_b128 v[168:171], v174 offset:2048
	ds_read_b128 v[174:177], v174 offset:3072
	ds_read_b128 v[178:181], v173 offset:32768
	ds_read_b128 v[182:185], v173 offset:33792
	ds_read_b128 v[186:189], v173 offset:34816
	ds_read_b128 v[204:207], v173 offset:35840
	ds_read_b128 v[208:211], v173 offset:36864
	ds_read_b128 v[212:215], v173 offset:37888
	ds_read_b128 v[216:219], v173 offset:38912
	ds_read_b128 v[220:223], v173 offset:39936
	s_mov_b32 m0, s52
	s_nop 0
	global_load_lds_dwordx4 v132, s[100:101]
	s_mov_b32 m0, s53
	s_nop 0
	global_load_lds_dwordx4 v136, s[100:101]
	s_waitcnt vmcnt(8)
	s_waitcnt lgkmcnt(0)
	s_setprio 1
	s_barrier
	v_mfma_f32_16x16x32_bf16 v[124:127], v[144:147], v[178:181], v[124:127]
	v_mfma_f32_16x16x32_bf16 v[120:123], v[152:155], v[178:181], v[120:123]
	v_mfma_f32_16x16x32_bf16 v[108:111], v[144:147], v[186:189], v[108:111]
	v_mfma_f32_16x16x32_bf16 v[104:107], v[152:155], v[186:189], v[104:107]
	v_mfma_f32_16x16x32_bf16 v[92:95], v[144:147], v[208:211], v[92:95]
	v_mfma_f32_16x16x32_bf16 v[88:91], v[152:155], v[208:211], v[88:91]
	v_mfma_f32_16x16x32_bf16 v[76:79], v[144:147], v[216:219], v[76:79]
	v_mfma_f32_16x16x32_bf16 v[72:75], v[152:155], v[216:219], v[72:75]
	v_mfma_f32_16x16x32_bf16 v[124:127], v[148:151], v[182:185], v[124:127]
	v_mfma_f32_16x16x32_bf16 v[120:123], v[156:159], v[182:185], v[120:123]
	v_mfma_f32_16x16x32_bf16 v[108:111], v[148:151], v[204:207], v[108:111]
	v_mfma_f32_16x16x32_bf16 v[104:107], v[156:159], v[204:207], v[104:107]
	v_mfma_f32_16x16x32_bf16 v[92:95], v[148:151], v[212:215], v[92:95]
	v_mfma_f32_16x16x32_bf16 v[88:91], v[156:159], v[212:215], v[88:91]
	v_mfma_f32_16x16x32_bf16 v[76:79], v[148:151], v[220:223], v[76:79]
	v_mfma_f32_16x16x32_bf16 v[72:75], v[156:159], v[220:223], v[72:75]
	v_mfma_f32_16x16x32_bf16 v[116:119], v[160:163], v[178:181], v[116:119]
	v_mfma_f32_16x16x32_bf16 v[112:115], v[168:171], v[178:181], v[112:115]
	v_mfma_f32_16x16x32_bf16 v[100:103], v[160:163], v[186:189], v[100:103]
	v_mfma_f32_16x16x32_bf16 v[96:99], v[168:171], v[186:189], v[96:99]
	v_mfma_f32_16x16x32_bf16 v[84:87], v[160:163], v[208:211], v[84:87]
	v_mfma_f32_16x16x32_bf16 v[80:83], v[168:171], v[208:211], v[80:83]
	v_mfma_f32_16x16x32_bf16 v[68:71], v[160:163], v[216:219], v[68:71]
	v_mfma_f32_16x16x32_bf16 v[64:67], v[168:171], v[216:219], v[64:67]
	v_mfma_f32_16x16x32_bf16 v[116:119], v[164:167], v[182:185], v[116:119]
	v_mfma_f32_16x16x32_bf16 v[112:115], v[174:177], v[182:185], v[112:115]
	v_mfma_f32_16x16x32_bf16 v[100:103], v[164:167], v[204:207], v[100:103]
	v_mfma_f32_16x16x32_bf16 v[96:99], v[174:177], v[204:207], v[96:99]
	v_mfma_f32_16x16x32_bf16 v[84:87], v[164:167], v[212:215], v[84:87]
	v_mfma_f32_16x16x32_bf16 v[80:83], v[174:177], v[212:215], v[80:83]
	v_mfma_f32_16x16x32_bf16 v[68:71], v[164:167], v[220:223], v[68:71]
	v_mfma_f32_16x16x32_bf16 v[64:67], v[174:177], v[220:223], v[64:67]
	s_setprio 0
	s_barrier
; #define PG8_STAGE(bufoff, gbase, voff) do { _Pragma("unroll") for (int _i = 0; _i < 2; ++_i) \
;         __builtin_amdgcn_global_load_lds((const unsigned*)((const char*)(gbase) + (voff)[_i]), (PG8_LAS unsigned*)(lds + (bufoff) + ldsw + _i * 8192), 16, 0, 0); } while (0)
; #define PG8_LDA(dst, b, h) do { _Pragma("unroll") for (int m = 0; m < 4; ++m) _Pragma("unroll") for (int k = 0; k < 2; ++k) dst[m][k] = *(const PG8_LAS bf16x8*)(lds + PG8_SA(b, h) + aoff + m * 2048 + k * 1024); } while (0)
; #define PG8_MMA(ai, bj, At, Bt) do { __builtin_amdgcn_s_setprio(1); _Pragma("unroll") for (int m = 0; m < 4; ++m) _Pragma("unroll") for (int n = 0; n < 2; ++n) _Pragma("unroll") for (int k = 0; k < 2; ++k) \
;         acc[ai][bj][m][n] = __builtin_amdgcn_mfma_f32_16x16x32_bf16(Bt[n][k], At[m][k], acc[ai][bj][m][n], 0, 0, 0); __builtin_amdgcn_s_setprio(0); } while (0)
; #define PG8_WAIT_V(n) asm volatile("s_waitcnt vmcnt(" #n ")" ::: "memory")
; #define PG8_WAIT_L(n) asm volatile("s_waitcnt lgkmcnt(" #n ")" ::: "memory")
; #define PG8_BAR __builtin_amdgcn_s_barrier()
; #define PG8_SCHED __builtin_amdgcn_sched_barrier(0)
; template <class Epi, class Sched, bool ALIGN_EPI = false, bool SP2 = false>
; __device__ __forceinline__ void gemm_phase(PG8_LAS unsigned char* lds, const Gemm g, const Sched& S, const Epi& E) {
;     ...
;             PG8_STAGE(PG8_SB(1, 0), b3, voffB); PG8_STAGE(PG8_SB(1, 1), b3 + hstep, voffB); PG8_STAGE(PG8_SA(1, 0), a3, voffA); PG8_SCHED; PG8_LDA(At, 1, 1);
;             PG8_WAIT_V(8); PG8_WAIT_L(0); PG8_BAR; PG8_MMA(1, 0, At, B0); PG8_MMA(1, 1, At, B1); PG8_BAR; PG8_SCHED;
;     ...
;         if constexpr (ALIGN_EPI) { if (wr == 0) PG8_BAR; }
	ds_read_b128 v[178:181], v173 offset:49152
	ds_read_b128 v[182:185], v173 offset:50176
	ds_read_b128 v[186:189], v173 offset:51200
	ds_read_b128 v[204:207], v173 offset:52224
	ds_read_b128 v[208:211], v173 offset:53248
	ds_read_b128 v[212:215], v173 offset:54272
	ds_read_b128 v[216:219], v173 offset:55296
	ds_read_b128 v[220:223], v173 offset:56320
	s_add_u32 s100, s28, 0x80
	s_addc_u32 s101, s29, 0
	s_add_u32 s28, s28, 0x40080
	s_addc_u32 s29, s29, 0
	s_add_u32 s98, s98, 0x80
	s_addc_u32 s99, s99, 0
	s_add_i32 m0, s30, s46
	s_nop 0
	global_load_lds_dwordx4 v134, s[100:101]
	s_add_i32 m0, m0, 0x2000
	s_nop 0
	global_load_lds_dwordx4 v138, s[100:101]
	s_add_i32 m0, s31, s46
	s_nop 0
	global_load_lds_dwordx4 v134, s[28:29]
	s_add_i32 m0, m0, 0x2000
	s_nop 0
	global_load_lds_dwordx4 v138, s[28:29]
	s_mov_b32 m0, s54
	s_nop 0
	global_load_lds_dwordx4 v132, s[98:99]
	s_mov_b32 m0, s55
	s_nop 0
	global_load_lds_dwordx4 v136, s[98:99]
	s_waitcnt vmcnt(8)
	s_waitcnt lgkmcnt(0)
	s_setprio 1
	s_barrier
	v_mfma_f32_16x16x32_bf16 v[60:63], v[144:147], v[178:181], v[60:63]
	v_mfma_f32_16x16x32_bf16 v[56:59], v[152:155], v[178:181], v[56:59]
	v_mfma_f32_16x16x32_bf16 v[44:47], v[144:147], v[186:189], v[44:47]
	v_mfma_f32_16x16x32_bf16 v[40:43], v[152:155], v[186:189], v[40:43]
	v_mfma_f32_16x16x32_bf16 v[28:31], v[144:147], v[208:211], v[28:31]
	v_mfma_f32_16x16x32_bf16 v[24:27], v[152:155], v[208:211], v[24:27]
	v_mfma_f32_16x16x32_bf16 v[12:15], v[144:147], v[216:219], v[12:15]
	v_mfma_f32_16x16x32_bf16 v[8:11], v[152:155], v[216:219], v[8:11]
	v_mfma_f32_16x16x32_bf16 v[60:63], v[148:151], v[182:185], v[60:63]
	v_mfma_f32_16x16x32_bf16 v[56:59], v[156:159], v[182:185], v[56:59]
	v_mfma_f32_16x16x32_bf16 v[44:47], v[148:151], v[204:207], v[44:47]
	v_mfma_f32_16x16x32_bf16 v[40:43], v[156:159], v[204:207], v[40:43]
	v_mfma_f32_16x16x32_bf16 v[28:31], v[148:151], v[212:215], v[28:31]
	v_mfma_f32_16x16x32_bf16 v[24:27], v[156:159], v[212:215], v[24:27]
	v_mfma_f32_16x16x32_bf16 v[12:15], v[148:151], v[220:223], v[12:15]
	v_mfma_f32_16x16x32_bf16 v[8:11], v[156:159], v[220:223], v[8:11]
	v_mfma_f32_16x16x32_bf16 v[52:55], v[160:163], v[178:181], v[52:55]
	v_mfma_f32_16x16x32_bf16 v[48:51], v[168:171], v[178:181], v[48:51]
	v_mfma_f32_16x16x32_bf16 v[36:39], v[160:163], v[186:189], v[36:39]
	v_mfma_f32_16x16x32_bf16 v[32:35], v[168:171], v[186:189], v[32:35]
	v_mfma_f32_16x16x32_bf16 v[20:23], v[160:163], v[208:211], v[20:23]
	v_mfma_f32_16x16x32_bf16 v[16:19], v[168:171], v[208:211], v[16:19]
	v_mfma_f32_16x16x32_bf16 v[4:7], v[160:163], v[216:219], v[4:7]
	v_mfma_f32_16x16x32_bf16 v[0:3], v[168:171], v[216:219], v[0:3]
	v_mfma_f32_16x16x32_bf16 v[52:55], v[164:167], v[182:185], v[52:55]
	v_mfma_f32_16x16x32_bf16 v[48:51], v[174:177], v[182:185], v[48:51]
	v_mfma_f32_16x16x32_bf16 v[36:39], v[164:167], v[204:207], v[36:39]
	v_mfma_f32_16x16x32_bf16 v[32:35], v[174:177], v[204:207], v[32:35]
	v_mfma_f32_16x16x32_bf16 v[20:23], v[164:167], v[212:215], v[20:23]
	v_mfma_f32_16x16x32_bf16 v[16:19], v[174:177], v[212:215], v[16:19]
	v_mfma_f32_16x16x32_bf16 v[4:7], v[164:167], v[220:223], v[4:7]
	v_mfma_f32_16x16x32_bf16 v[0:3], v[174:177], v[220:223], v[0:3]
	s_setprio 0
	s_barrier
	s_add_i32 s60, s60, 2
	s_add_u32 vcc_lo, vcc_lo, 0x100
	s_addc_u32 vcc_hi, vcc_hi, 0
	s_cmp_gt_u32 s60, 13
	s_cbranch_scc0 .LBB0_148
	s_and_b64 vcc, exec, s[62:63]
	s_cbranch_vccz .LBB0_151
	s_barrier

; #define PG8_STAGE(bufoff, gbase, voff) do { _Pragma("unroll") for (int _i = 0; _i < 2; ++_i) \
;         __builtin_amdgcn_global_load_lds((const unsigned*)((const char*)(gbase) + (voff)[_i]), (PG8_LAS unsigned*)(lds + (bufoff) + ldsw + _i * 8192), 16, 0, 0); } while (0)
; #define PG8_LDA(dst, b, h) do { _Pragma("unroll") for (int m = 0; m < 4; ++m) _Pragma("unroll") for (int k = 0; k < 2; ++k) dst[m][k] = *(const PG8_LAS bf16x8*)(lds + PG8_SA(b, h) + aoff + m * 2048 + k * 1024); } while (0)
; #define PG8_LDB(dst, b, h) do { _Pragma("unroll") for (int n = 0; n < 2; ++n) _Pragma("unroll") for (int k = 0; k < 2; ++k) dst[n][k] = *(const PG8_LAS bf16x8*)(lds + PG8_SB(b, h) + boff + n * 2048 + k * 1024); } while (0)
; #define PG8_MMA(ai, bj, At, Bt) do { __builtin_amdgcn_s_setprio(1); _Pragma("unroll") for (int m = 0; m < 4; ++m) _Pragma("unroll") for (int n = 0; n < 2; ++n) _Pragma("unroll") for (int k = 0; k < 2; ++k) \
;         acc[ai][bj][m][n] = __builtin_amdgcn_mfma_f32_16x16x32_bf16(Bt[n][k], At[m][k], acc[ai][bj][m][n], 0, 0, 0); __builtin_amdgcn_s_setprio(0); } while (0)
; #define PG8_WAIT_V(n) asm volatile("s_waitcnt vmcnt(" #n ")" ::: "memory")
; #define PG8_WAIT_L(n) asm volatile("s_waitcnt lgkmcnt(" #n ")" ::: "memory")
; #define PG8_WAIT_V8_UNLESS(flag) asm volatile("s_cmp_lg_i32 %0, 0\n\ts_cbranch_scc1 .Lpg8rx%=\n\ts_waitcnt vmcnt(8)\n.Lpg8rx%=:" :: "s"(__builtin_amdgcn_readfirstlane(flag)) : "scc", "memory")
; #define PG8_BAR __builtin_amdgcn_s_barrier()
; #define PG8_SCHED __builtin_amdgcn_sched_barrier(0)
; template <class Epi, class Sched, bool ALIGN_EPI = false, bool SP2 = false>
; __device__ __forceinline__ void gemm_phase(PG8_LAS unsigned char* lds, const Gemm g, const Sched& S, const Epi& E) {
;     ...
;             PG8_WAIT_V8_UNLESS(rx); PG8_WAIT_L(0); PG8_BAR; PG8_MMA(1, 0, At, B0); PG8_MMA(1, 1, At, B1); PG8_BAR; PG8_SCHED;
;             PG8_STAGE(PG8_SA(0, 1), a2 + hstep, voffA); PG8_SCHED; PG8_LDB(B0, 1, 0); PG8_LDB(B1, 1, 1); PG8_SCHED; PG8_LDA(At, 1, 0);
;             PG8_WAIT_V(8); PG8_WAIT_L(0); PG8_BAR; PG8_MMA(0, 0, At, B0); PG8_MMA(0, 1, At, B1); PG8_BAR; PG8_SCHED;
.Lpg8rx3:
	s_waitcnt lgkmcnt(0)
	s_setprio 1
	s_barrier
	v_mfma_f32_16x16x32_bf16 v[60:63], v[120:123], v[164:167], v[60:63]
	v_mfma_f32_16x16x32_bf16 v[56:59], v[132:135], v[164:167], v[56:59]
	v_mfma_f32_16x16x32_bf16 v[44:47], v[120:123], v[172:175], v[44:47]
	v_mfma_f32_16x16x32_bf16 v[40:43], v[132:135], v[172:175], v[40:43]
	v_mfma_f32_16x16x32_bf16 v[28:31], v[120:123], v[180:183], v[28:31]
	v_mfma_f32_16x16x32_bf16 v[24:27], v[132:135], v[180:183], v[24:27]
	v_mfma_f32_16x16x32_bf16 v[12:15], v[120:123], v[188:191], v[12:15]
	v_mfma_f32_16x16x32_bf16 v[8:11], v[132:135], v[188:191], v[8:11]
	v_mfma_f32_16x16x32_bf16 v[60:63], v[128:131], v[168:171], v[60:63]
	v_mfma_f32_16x16x32_bf16 v[56:59], v[136:139], v[168:171], v[56:59]
	v_mfma_f32_16x16x32_bf16 v[44:47], v[128:131], v[176:179], v[44:47]
	v_mfma_f32_16x16x32_bf16 v[40:43], v[136:139], v[176:179], v[40:43]
	v_mfma_f32_16x16x32_bf16 v[28:31], v[128:131], v[184:187], v[28:31]
	v_mfma_f32_16x16x32_bf16 v[24:27], v[136:139], v[184:187], v[24:27]
	v_mfma_f32_16x16x32_bf16 v[12:15], v[128:131], v[214:217], v[12:15]
	v_mfma_f32_16x16x32_bf16 v[8:11], v[136:139], v[214:217], v[8:11]
	v_mfma_f32_16x16x32_bf16 v[52:55], v[140:143], v[164:167], v[52:55]
	v_mfma_f32_16x16x32_bf16 v[48:51], v[156:159], v[164:167], v[48:51]
	v_mfma_f32_16x16x32_bf16 v[36:39], v[140:143], v[172:175], v[36:39]
	v_mfma_f32_16x16x32_bf16 v[32:35], v[156:159], v[172:175], v[32:35]
	v_mfma_f32_16x16x32_bf16 v[20:23], v[140:143], v[180:183], v[20:23]
	v_mfma_f32_16x16x32_bf16 v[16:19], v[156:159], v[180:183], v[16:19]
	v_mfma_f32_16x16x32_bf16 v[4:7], v[140:143], v[188:191], v[4:7]
	v_mfma_f32_16x16x32_bf16 v[0:3], v[156:159], v[188:191], v[0:3]
	v_mfma_f32_16x16x32_bf16 v[52:55], v[144:147], v[168:171], v[52:55]
	v_mfma_f32_16x16x32_bf16 v[48:51], v[160:163], v[168:171], v[48:51]
	v_mfma_f32_16x16x32_bf16 v[36:39], v[144:147], v[176:179], v[36:39]
	v_mfma_f32_16x16x32_bf16 v[32:35], v[160:163], v[176:179], v[32:35]
	v_mfma_f32_16x16x32_bf16 v[20:23], v[144:147], v[184:187], v[20:23]
	v_mfma_f32_16x16x32_bf16 v[16:19], v[160:163], v[184:187], v[16:19]
	v_mfma_f32_16x16x32_bf16 v[4:7], v[144:147], v[214:217], v[4:7]
	v_mfma_f32_16x16x32_bf16 v[0:3], v[160:163], v[214:217], v[0:3]
	s_setprio 0
	s_barrier
	s_mov_b64 s[98:99], s[30:31]
	s_add_u32 s100, s30, 0x40000
	s_addc_u32 s101, s31, 0
	s_add_i32 s30, 0, 0x18000
	s_add_i32 s31, 0, 0x1c000
	v_add_u32_e32 v136, s30, v247
	v_add_u32_e32 v160, s31, v247
	ds_read_b128 v[120:123], v136
	ds_read_b128 v[128:131], v136 offset:1024
	ds_read_b128 v[132:135], v136 offset:2048
	ds_read_b128 v[136:139], v136 offset:3072
	ds_read_b128 v[140:143], v160
	ds_read_b128 v[144:147], v160 offset:1024
	ds_read_b128 v[156:159], v160 offset:2048
	ds_read_b128 v[160:163], v160 offset:3072
	ds_read_b128 v[164:167], v248 offset:32768
	ds_read_b128 v[168:171], v248 offset:33792
	ds_read_b128 v[172:175], v248 offset:34816
	ds_read_b128 v[176:179], v248 offset:35840
	ds_read_b128 v[180:183], v248 offset:36864
	ds_read_b128 v[184:187], v248 offset:37888
	ds_read_b128 v[188:191], v248 offset:38912
	ds_read_b128 v[214:217], v248 offset:39936
	s_mov_b32 m0, s46
	s_nop 0
	global_load_lds_dwordx4 v204, s[100:101]
	s_mov_b32 m0, s48
	s_nop 0
	global_load_lds_dwordx4 v206, s[100:101]
	s_waitcnt vmcnt(8)
	s_waitcnt lgkmcnt(0)
	s_setprio 1
	s_barrier
	v_mfma_f32_16x16x32_bf16 v[152:155], v[120:123], v[164:167], v[152:155]
	v_mfma_f32_16x16x32_bf16 v[148:151], v[132:135], v[164:167], v[148:151]
	v_mfma_f32_16x16x32_bf16 v[108:111], v[120:123], v[172:175], v[108:111]
	v_mfma_f32_16x16x32_bf16 v[104:107], v[132:135], v[172:175], v[104:107]
	v_mfma_f32_16x16x32_bf16 v[92:95], v[120:123], v[180:183], v[92:95]
	v_mfma_f32_16x16x32_bf16 v[88:91], v[132:135], v[180:183], v[88:91]
	v_mfma_f32_16x16x32_bf16 v[76:79], v[120:123], v[188:191], v[76:79]
	v_mfma_f32_16x16x32_bf16 v[72:75], v[132:135], v[188:191], v[72:75]
	v_mfma_f32_16x16x32_bf16 v[152:155], v[128:131], v[168:171], v[152:155]
	v_mfma_f32_16x16x32_bf16 v[148:151], v[136:139], v[168:171], v[148:151]
	v_mfma_f32_16x16x32_bf16 v[108:111], v[128:131], v[176:179], v[108:111]
	v_mfma_f32_16x16x32_bf16 v[104:107], v[136:139], v[176:179], v[104:107]
	v_mfma_f32_16x16x32_bf16 v[92:95], v[128:131], v[184:187], v[92:95]
	v_mfma_f32_16x16x32_bf16 v[88:91], v[136:139], v[184:187], v[88:91]
	v_mfma_f32_16x16x32_bf16 v[76:79], v[128:131], v[214:217], v[76:79]
	v_mfma_f32_16x16x32_bf16 v[72:75], v[136:139], v[214:217], v[72:75]
	v_mfma_f32_16x16x32_bf16 v[124:127], v[140:143], v[164:167], v[124:127]
	v_mfma_f32_16x16x32_bf16 v[112:115], v[156:159], v[164:167], v[112:115]
	v_mfma_f32_16x16x32_bf16 v[100:103], v[140:143], v[172:175], v[100:103]
	v_mfma_f32_16x16x32_bf16 v[96:99], v[156:159], v[172:175], v[96:99]
	v_mfma_f32_16x16x32_bf16 v[84:87], v[140:143], v[180:183], v[84:87]
	v_mfma_f32_16x16x32_bf16 v[80:83], v[156:159], v[180:183], v[80:83]
	v_mfma_f32_16x16x32_bf16 v[68:71], v[140:143], v[188:191], v[68:71]
	v_mfma_f32_16x16x32_bf16 v[64:67], v[156:159], v[188:191], v[64:67]
	v_mfma_f32_16x16x32_bf16 v[124:127], v[144:147], v[168:171], v[124:127]
	v_mfma_f32_16x16x32_bf16 v[112:115], v[160:163], v[168:171], v[112:115]
	v_mfma_f32_16x16x32_bf16 v[100:103], v[144:147], v[176:179], v[100:103]
	v_mfma_f32_16x16x32_bf16 v[96:99], v[160:163], v[176:179], v[96:99]
	v_mfma_f32_16x16x32_bf16 v[84:87], v[144:147], v[184:187], v[84:87]
	v_mfma_f32_16x16x32_bf16 v[80:83], v[160:163], v[184:187], v[80:83]
	v_mfma_f32_16x16x32_bf16 v[68:71], v[144:147], v[214:217], v[68:71]
	v_mfma_f32_16x16x32_bf16 v[64:67], v[160:163], v[214:217], v[64:67]
	s_setprio 0
	s_barrier
; #define PG8_STAGE(bufoff, gbase, voff) do { _Pragma("unroll") for (int _i = 0; _i < 2; ++_i) \
;         __builtin_amdgcn_global_load_lds((const unsigned*)((const char*)(gbase) + (voff)[_i]), (PG8_LAS unsigned*)(lds + (bufoff) + ldsw + _i * 8192), 16, 0, 0); } while (0)
; #define PG8_LDA(dst, b, h) do { _Pragma("unroll") for (int m = 0; m < 4; ++m) _Pragma("unroll") for (int k = 0; k < 2; ++k) dst[m][k] = *(const PG8_LAS bf16x8*)(lds + PG8_SA(b, h) + aoff + m * 2048 + k * 1024); } while (0)
; #define PG8_MMA(ai, bj, At, Bt) do { __builtin_amdgcn_s_setprio(1); _Pragma("unroll") for (int m = 0; m < 4; ++m) _Pragma("unroll") for (int n = 0; n < 2; ++n) _Pragma("unroll") for (int k = 0; k < 2; ++k) \
;         acc[ai][bj][m][n] = __builtin_amdgcn_mfma_f32_16x16x32_bf16(Bt[n][k], At[m][k], acc[ai][bj][m][n], 0, 0, 0); __builtin_amdgcn_s_setprio(0); } while (0)
; #define PG8_WAIT_V(n) asm volatile("s_waitcnt vmcnt(" #n ")" ::: "memory")
; #define PG8_WAIT_L(n) asm volatile("s_waitcnt lgkmcnt(" #n ")" ::: "memory")
; #define PG8_BAR __builtin_amdgcn_s_barrier()
; #define PG8_SCHED __builtin_amdgcn_sched_barrier(0)
; template <class Epi, class Sched, bool ALIGN_EPI = false, bool SP2 = false>
; __device__ __forceinline__ void gemm_phase(PG8_LAS unsigned char* lds, const Gemm g, const Sched& S, const Epi& E) {
;     ...
;             PG8_STAGE(PG8_SB(1, 0), b3, voffB); PG8_STAGE(PG8_SB(1, 1), b3 + hstep, voffB); PG8_STAGE(PG8_SA(1, 0), a3, voffA); PG8_SCHED; PG8_LDA(At, 1, 1);
;             PG8_WAIT_V(8); PG8_WAIT_L(0); PG8_BAR; PG8_MMA(1, 0, At, B0); PG8_MMA(1, 1, At, B1); PG8_BAR; PG8_SCHED;
;     ...
;         if constexpr (ALIGN_EPI) { if (wr == 0) PG8_BAR; }
	ds_read_b128 v[164:167], v248 offset:49152
	ds_read_b128 v[168:171], v248 offset:50176
	ds_read_b128 v[172:175], v248 offset:51200
	ds_read_b128 v[176:179], v248 offset:52224
	ds_read_b128 v[180:183], v248 offset:53248
	ds_read_b128 v[184:187], v248 offset:54272
	ds_read_b128 v[188:191], v248 offset:55296
	ds_read_b128 v[214:217], v248 offset:56320
	s_add_u32 s100, s28, 0x80
	s_addc_u32 s101, s29, 0
	s_add_u32 s28, s28, 0x40080
	s_addc_u32 s29, s29, 0
	s_add_u32 s98, s98, 0x80
	s_addc_u32 s99, s99, 0
	s_add_i32 m0, s30, s39
	s_nop 0
	global_load_lds_dwordx4 v194, s[100:101]
	s_add_i32 m0, m0, 0x2000
	s_nop 0
	global_load_lds_dwordx4 v208, s[100:101]
	s_add_i32 m0, s31, s39
	s_nop 0
	global_load_lds_dwordx4 v194, s[28:29]
	s_add_i32 m0, m0, 0x2000
	s_nop 0
	global_load_lds_dwordx4 v208, s[28:29]
	s_mov_b32 m0, s50
	s_nop 0
	global_load_lds_dwordx4 v204, s[98:99]
	s_mov_b32 m0, s51
	s_nop 0
	global_load_lds_dwordx4 v206, s[98:99]
	s_waitcnt vmcnt(8)
	s_waitcnt lgkmcnt(0)
	s_setprio 1
	s_barrier
	v_mfma_f32_16x16x32_bf16 v[60:63], v[120:123], v[164:167], v[60:63]
	v_mfma_f32_16x16x32_bf16 v[56:59], v[132:135], v[164:167], v[56:59]
	v_mfma_f32_16x16x32_bf16 v[44:47], v[120:123], v[172:175], v[44:47]
	v_mfma_f32_16x16x32_bf16 v[40:43], v[132:135], v[172:175], v[40:43]
	v_mfma_f32_16x16x32_bf16 v[28:31], v[120:123], v[180:183], v[28:31]
	v_mfma_f32_16x16x32_bf16 v[24:27], v[132:135], v[180:183], v[24:27]
	v_mfma_f32_16x16x32_bf16 v[12:15], v[120:123], v[188:191], v[12:15]
	v_mfma_f32_16x16x32_bf16 v[8:11], v[132:135], v[188:191], v[8:11]
	v_mfma_f32_16x16x32_bf16 v[60:63], v[128:131], v[168:171], v[60:63]
	v_mfma_f32_16x16x32_bf16 v[56:59], v[136:139], v[168:171], v[56:59]
	v_mfma_f32_16x16x32_bf16 v[44:47], v[128:131], v[176:179], v[44:47]
	v_mfma_f32_16x16x32_bf16 v[40:43], v[136:139], v[176:179], v[40:43]
	v_mfma_f32_16x16x32_bf16 v[28:31], v[128:131], v[184:187], v[28:31]
	v_mfma_f32_16x16x32_bf16 v[24:27], v[136:139], v[184:187], v[24:27]
	v_mfma_f32_16x16x32_bf16 v[12:15], v[128:131], v[214:217], v[12:15]
	v_mfma_f32_16x16x32_bf16 v[8:11], v[136:139], v[214:217], v[8:11]
	v_mfma_f32_16x16x32_bf16 v[52:55], v[140:143], v[164:167], v[52:55]
	v_mfma_f32_16x16x32_bf16 v[48:51], v[156:159], v[164:167], v[48:51]
	v_mfma_f32_16x16x32_bf16 v[36:39], v[140:143], v[172:175], v[36:39]
	v_mfma_f32_16x16x32_bf16 v[32:35], v[156:159], v[172:175], v[32:35]
	v_mfma_f32_16x16x32_bf16 v[20:23], v[140:143], v[180:183], v[20:23]
	v_mfma_f32_16x16x32_bf16 v[16:19], v[156:159], v[180:183], v[16:19]
	v_mfma_f32_16x16x32_bf16 v[4:7], v[140:143], v[188:191], v[4:7]
	v_mfma_f32_16x16x32_bf16 v[0:3], v[156:159], v[188:191], v[0:3]
	v_mfma_f32_16x16x32_bf16 v[52:55], v[144:147], v[168:171], v[52:55]
	v_mfma_f32_16x16x32_bf16 v[48:51], v[160:163], v[168:171], v[48:51]
	v_mfma_f32_16x16x32_bf16 v[36:39], v[144:147], v[176:179], v[36:39]
	v_mfma_f32_16x16x32_bf16 v[32:35], v[160:163], v[176:179], v[32:35]
	v_mfma_f32_16x16x32_bf16 v[20:23], v[144:147], v[184:187], v[20:23]
	v_mfma_f32_16x16x32_bf16 v[16:19], v[160:163], v[184:187], v[16:19]
	v_mfma_f32_16x16x32_bf16 v[4:7], v[144:147], v[214:217], v[4:7]
	v_mfma_f32_16x16x32_bf16 v[0:3], v[160:163], v[214:217], v[0:3]
	s_setprio 0
	s_barrier
	s_add_i32 s58, s58, 2
	s_add_u32 s62, s62, 0x100
	s_addc_u32 s63, s63, 0
	s_cmp_gt_u32 s58, 13
	s_cbranch_scc0 .LBB0_514
	s_and_b64 vcc, exec, s[14:15]
	s_cbranch_vccz .LBB0_517
	s_barrier

; #define PG8_STAGE(bufoff, gbase, voff) do { _Pragma("unroll") for (int _i = 0; _i < 2; ++_i) \
;         __builtin_amdgcn_global_load_lds((const unsigned*)((const char*)(gbase) + (voff)[_i]), (PG8_LAS unsigned*)(lds + (bufoff) + ldsw + _i * 8192), 16, 0, 0); } while (0)
; #define PG8_LDA(dst, b, h) do { _Pragma("unroll") for (int m = 0; m < 4; ++m) _Pragma("unroll") for (int k = 0; k < 2; ++k) dst[m][k] = *(const PG8_LAS bf16x8*)(lds + PG8_SA(b, h) + aoff + m * 2048 + k * 1024); } while (0)
; #define PG8_LDB(dst, b, h) do { _Pragma("unroll") for (int n = 0; n < 2; ++n) _Pragma("unroll") for (int k = 0; k < 2; ++k) dst[n][k] = *(const PG8_LAS bf16x8*)(lds + PG8_SB(b, h) + boff + n * 2048 + k * 1024); } while (0)
; #define PG8_MMA(ai, bj, At, Bt) do { __builtin_amdgcn_s_setprio(1); _Pragma("unroll") for (int m = 0; m < 4; ++m) _Pragma("unroll") for (int n = 0; n < 2; ++n) _Pragma("unroll") for (int k = 0; k < 2; ++k) \
;         acc[ai][bj][m][n] = __builtin_amdgcn_mfma_f32_16x16x32_bf16(Bt[n][k], At[m][k], acc[ai][bj][m][n], 0, 0, 0); __builtin_amdgcn_s_setprio(0); } while (0)
; #define PG8_WAIT_V(n) asm volatile("s_waitcnt vmcnt(" #n ")" ::: "memory")
; #define PG8_WAIT_L(n) asm volatile("s_waitcnt lgkmcnt(" #n ")" ::: "memory")
; #define PG8_WAIT_V8_UNLESS(flag) asm volatile("s_cmp_lg_i32 %0, 0\n\ts_cbranch_scc1 .Lpg8rx%=\n\ts_waitcnt vmcnt(8)\n.Lpg8rx%=:" :: "s"(__builtin_amdgcn_readfirstlane(flag)) : "scc", "memory")
; #define PG8_BAR __builtin_amdgcn_s_barrier()
; #define PG8_SCHED __builtin_amdgcn_sched_barrier(0)
; template <class Epi, class Sched, bool ALIGN_EPI = false, bool SP2 = false>
; __device__ __forceinline__ void gemm_phase(PG8_LAS unsigned char* lds, const Gemm g, const Sched& S, const Epi& E) {
;     ...
;             PG8_WAIT_V8_UNLESS(rx); PG8_WAIT_L(0); PG8_BAR; PG8_MMA(1, 0, At, B0); PG8_MMA(1, 1, At, B1); PG8_BAR; PG8_SCHED;
;             PG8_STAGE(PG8_SA(0, 1), a2 + hstep, voffA); PG8_SCHED; PG8_LDB(B0, 1, 0); PG8_LDB(B1, 1, 1); PG8_SCHED; PG8_LDA(At, 1, 0);
;             PG8_WAIT_V(8); PG8_WAIT_L(0); PG8_BAR; PG8_MMA(0, 0, At, B0); PG8_MMA(0, 1, At, B1); PG8_BAR; PG8_SCHED;
.Lpg8rx5:
	s_waitcnt lgkmcnt(0)
	s_setprio 1
	s_barrier
	v_mfma_f32_16x16x32_bf16 v[60:63], v[132:135], v[176:179], v[60:63]
	v_mfma_f32_16x16x32_bf16 v[56:59], v[140:143], v[176:179], v[56:59]
	v_mfma_f32_16x16x32_bf16 v[44:47], v[132:135], v[204:207], v[44:47]
	v_mfma_f32_16x16x32_bf16 v[40:43], v[140:143], v[204:207], v[40:43]
	v_mfma_f32_16x16x32_bf16 v[28:31], v[132:135], v[212:215], v[28:31]
	v_mfma_f32_16x16x32_bf16 v[24:27], v[140:143], v[212:215], v[24:27]
	v_mfma_f32_16x16x32_bf16 v[12:15], v[132:135], v[220:223], v[12:15]
	v_mfma_f32_16x16x32_bf16 v[8:11], v[140:143], v[220:223], v[8:11]
	v_mfma_f32_16x16x32_bf16 v[60:63], v[136:139], v[186:189], v[60:63]
	v_mfma_f32_16x16x32_bf16 v[56:59], v[144:147], v[186:189], v[56:59]
	v_mfma_f32_16x16x32_bf16 v[44:47], v[136:139], v[208:211], v[44:47]
	v_mfma_f32_16x16x32_bf16 v[40:43], v[144:147], v[208:211], v[40:43]
	v_mfma_f32_16x16x32_bf16 v[28:31], v[136:139], v[216:219], v[28:31]
	v_mfma_f32_16x16x32_bf16 v[24:27], v[144:147], v[216:219], v[24:27]
	v_mfma_f32_16x16x32_bf16 v[12:15], v[136:139], v[224:227], v[12:15]
	v_mfma_f32_16x16x32_bf16 v[8:11], v[144:147], v[224:227], v[8:11]
	v_mfma_f32_16x16x32_bf16 v[52:55], v[148:151], v[176:179], v[52:55]
	v_mfma_f32_16x16x32_bf16 v[48:51], v[168:171], v[176:179], v[48:51]
	v_mfma_f32_16x16x32_bf16 v[36:39], v[148:151], v[204:207], v[36:39]
	v_mfma_f32_16x16x32_bf16 v[32:35], v[168:171], v[204:207], v[32:35]
	v_mfma_f32_16x16x32_bf16 v[20:23], v[148:151], v[212:215], v[20:23]
	v_mfma_f32_16x16x32_bf16 v[16:19], v[168:171], v[212:215], v[16:19]
	v_mfma_f32_16x16x32_bf16 v[4:7], v[148:151], v[220:223], v[4:7]
	v_mfma_f32_16x16x32_bf16 v[0:3], v[168:171], v[220:223], v[0:3]
	v_mfma_f32_16x16x32_bf16 v[52:55], v[164:167], v[186:189], v[52:55]
	v_mfma_f32_16x16x32_bf16 v[48:51], v[172:175], v[186:189], v[48:51]
	v_mfma_f32_16x16x32_bf16 v[36:39], v[164:167], v[208:211], v[36:39]
	v_mfma_f32_16x16x32_bf16 v[32:35], v[172:175], v[208:211], v[32:35]
	v_mfma_f32_16x16x32_bf16 v[20:23], v[164:167], v[216:219], v[20:23]
	v_mfma_f32_16x16x32_bf16 v[16:19], v[172:175], v[216:219], v[16:19]
	v_mfma_f32_16x16x32_bf16 v[4:7], v[164:167], v[224:227], v[4:7]
	v_mfma_f32_16x16x32_bf16 v[0:3], v[172:175], v[224:227], v[0:3]
	s_setprio 0
	s_barrier
	s_mov_b64 s[98:99], s[30:31]
	s_add_u32 s100, s30, 0x40000
	s_addc_u32 s101, s31, 0
	s_add_i32 s30, 0, 0x18000
	s_add_i32 s31, 0, 0x1c000
	v_add_u32_e32 v144, s30, v183
	v_add_u32_e32 v172, s31, v183
	ds_read_b128 v[132:135], v144
	ds_read_b128 v[136:139], v144 offset:1024
	ds_read_b128 v[140:143], v144 offset:2048
	ds_read_b128 v[144:147], v144 offset:3072
	ds_read_b128 v[148:151], v172
	ds_read_b128 v[164:167], v172 offset:1024
	ds_read_b128 v[168:171], v172 offset:2048
	ds_read_b128 v[172:175], v172 offset:3072
	ds_read_b128 v[176:179], v185 offset:32768
	ds_read_b128 v[186:189], v185 offset:33792
	ds_read_b128 v[204:207], v185 offset:34816
	ds_read_b128 v[208:211], v185 offset:35840
	ds_read_b128 v[212:215], v185 offset:36864
	ds_read_b128 v[216:219], v185 offset:37888
	ds_read_b128 v[220:223], v185 offset:38912
	ds_read_b128 v[224:227], v185 offset:39936
	s_mov_b32 m0, s46
	s_nop 0
	global_load_lds_dwordx4 v152, s[100:101]
	s_mov_b32 m0, s48
	s_nop 0
	global_load_lds_dwordx4 v156, s[100:101]
	s_waitcnt vmcnt(8)
	s_waitcnt lgkmcnt(0)
	s_setprio 1
	s_barrier
	v_mfma_f32_16x16x32_bf16 v[124:127], v[132:135], v[176:179], v[124:127]
	v_mfma_f32_16x16x32_bf16 v[120:123], v[140:143], v[176:179], v[120:123]
	v_mfma_f32_16x16x32_bf16 v[108:111], v[132:135], v[204:207], v[108:111]
	v_mfma_f32_16x16x32_bf16 v[104:107], v[140:143], v[204:207], v[104:107]
	v_mfma_f32_16x16x32_bf16 v[92:95], v[132:135], v[212:215], v[92:95]
	v_mfma_f32_16x16x32_bf16 v[88:91], v[140:143], v[212:215], v[88:91]
	v_mfma_f32_16x16x32_bf16 v[76:79], v[132:135], v[220:223], v[76:79]
	v_mfma_f32_16x16x32_bf16 v[72:75], v[140:143], v[220:223], v[72:75]
	v_mfma_f32_16x16x32_bf16 v[124:127], v[136:139], v[186:189], v[124:127]
	v_mfma_f32_16x16x32_bf16 v[120:123], v[144:147], v[186:189], v[120:123]
	v_mfma_f32_16x16x32_bf16 v[108:111], v[136:139], v[208:211], v[108:111]
	v_mfma_f32_16x16x32_bf16 v[104:107], v[144:147], v[208:211], v[104:107]
	v_mfma_f32_16x16x32_bf16 v[92:95], v[136:139], v[216:219], v[92:95]
	v_mfma_f32_16x16x32_bf16 v[88:91], v[144:147], v[216:219], v[88:91]
	v_mfma_f32_16x16x32_bf16 v[76:79], v[136:139], v[224:227], v[76:79]
	v_mfma_f32_16x16x32_bf16 v[72:75], v[144:147], v[224:227], v[72:75]
	v_mfma_f32_16x16x32_bf16 v[116:119], v[148:151], v[176:179], v[116:119]
	v_mfma_f32_16x16x32_bf16 v[112:115], v[168:171], v[176:179], v[112:115]
	v_mfma_f32_16x16x32_bf16 v[100:103], v[148:151], v[204:207], v[100:103]
	v_mfma_f32_16x16x32_bf16 v[96:99], v[168:171], v[204:207], v[96:99]
	v_mfma_f32_16x16x32_bf16 v[84:87], v[148:151], v[212:215], v[84:87]
	v_mfma_f32_16x16x32_bf16 v[80:83], v[168:171], v[212:215], v[80:83]
	v_mfma_f32_16x16x32_bf16 v[68:71], v[148:151], v[220:223], v[68:71]
	v_mfma_f32_16x16x32_bf16 v[64:67], v[168:171], v[220:223], v[64:67]
	v_mfma_f32_16x16x32_bf16 v[116:119], v[164:167], v[186:189], v[116:119]
	v_mfma_f32_16x16x32_bf16 v[112:115], v[172:175], v[186:189], v[112:115]
	v_mfma_f32_16x16x32_bf16 v[100:103], v[164:167], v[208:211], v[100:103]
	v_mfma_f32_16x16x32_bf16 v[96:99], v[172:175], v[208:211], v[96:99]
	v_mfma_f32_16x16x32_bf16 v[84:87], v[164:167], v[216:219], v[84:87]
	v_mfma_f32_16x16x32_bf16 v[80:83], v[172:175], v[216:219], v[80:83]
	v_mfma_f32_16x16x32_bf16 v[68:71], v[164:167], v[224:227], v[68:71]
	v_mfma_f32_16x16x32_bf16 v[64:67], v[172:175], v[224:227], v[64:67]
	s_setprio 0
	s_barrier
; #define PG8_STAGE(bufoff, gbase, voff) do { _Pragma("unroll") for (int _i = 0; _i < 2; ++_i) \
;         __builtin_amdgcn_global_load_lds((const unsigned*)((const char*)(gbase) + (voff)[_i]), (PG8_LAS unsigned*)(lds + (bufoff) + ldsw + _i * 8192), 16, 0, 0); } while (0)
; #define PG8_LDA(dst, b, h) do { _Pragma("unroll") for (int m = 0; m < 4; ++m) _Pragma("unroll") for (int k = 0; k < 2; ++k) dst[m][k] = *(const PG8_LAS bf16x8*)(lds + PG8_SA(b, h) + aoff + m * 2048 + k * 1024); } while (0)
; #define PG8_MMA(ai, bj, At, Bt) do { __builtin_amdgcn_s_setprio(1); _Pragma("unroll") for (int m = 0; m < 4; ++m) _Pragma("unroll") for (int n = 0; n < 2; ++n) _Pragma("unroll") for (int k = 0; k < 2; ++k) \
;         acc[ai][bj][m][n] = __builtin_amdgcn_mfma_f32_16x16x32_bf16(Bt[n][k], At[m][k], acc[ai][bj][m][n], 0, 0, 0); __builtin_amdgcn_s_setprio(0); } while (0)
; #define PG8_WAIT_V(n) asm volatile("s_waitcnt vmcnt(" #n ")" ::: "memory")
; #define PG8_WAIT_L(n) asm volatile("s_waitcnt lgkmcnt(" #n ")" ::: "memory")
; #define PG8_BAR __builtin_amdgcn_s_barrier()
; #define PG8_SCHED __builtin_amdgcn_sched_barrier(0)
; template <class Epi, class Sched, bool ALIGN_EPI = false, bool SP2 = false>
; __device__ __forceinline__ void gemm_phase(PG8_LAS unsigned char* lds, const Gemm g, const Sched& S, const Epi& E) {
;     ...
;             PG8_STAGE(PG8_SB(1, 0), b3, voffB); PG8_STAGE(PG8_SB(1, 1), b3 + hstep, voffB); PG8_STAGE(PG8_SA(1, 0), a3, voffA); PG8_SCHED; PG8_LDA(At, 1, 1);
;             PG8_WAIT_V(8); PG8_WAIT_L(0); PG8_BAR; PG8_MMA(1, 0, At, B0); PG8_MMA(1, 1, At, B1); PG8_BAR; PG8_SCHED;
;     ...
;         if constexpr (ALIGN_EPI) { if (wr == 0) PG8_BAR; }
	ds_read_b128 v[176:179], v185 offset:49152
	ds_read_b128 v[186:189], v185 offset:50176
	ds_read_b128 v[204:207], v185 offset:51200
	ds_read_b128 v[208:211], v185 offset:52224
	ds_read_b128 v[212:215], v185 offset:53248
	ds_read_b128 v[216:219], v185 offset:54272
	ds_read_b128 v[220:223], v185 offset:55296
	ds_read_b128 v[224:227], v185 offset:56320
	s_add_u32 s100, s28, 0x80
	s_addc_u32 s101, s29, 0
	s_add_u32 s28, s28, 0x40080
	s_addc_u32 s29, s29, 0
	s_add_u32 s98, s98, 0x80
	s_addc_u32 s99, s99, 0
	s_add_i32 m0, s30, s38
	s_nop 0
	global_load_lds_dwordx4 v154, s[100:101]
	s_add_i32 m0, m0, 0x2000
	s_nop 0
	global_load_lds_dwordx4 v158, s[100:101]
	s_add_i32 m0, s31, s38
	s_nop 0
	global_load_lds_dwordx4 v154, s[28:29]
	s_add_i32 m0, m0, 0x2000
	s_nop 0
	global_load_lds_dwordx4 v158, s[28:29]
	s_mov_b32 m0, s50
	s_nop 0
	global_load_lds_dwordx4 v152, s[98:99]
	s_mov_b32 m0, s51
	s_nop 0
	global_load_lds_dwordx4 v156, s[98:99]
	s_waitcnt vmcnt(8)
	s_waitcnt lgkmcnt(0)
	s_setprio 1
	s_barrier
	v_mfma_f32_16x16x32_bf16 v[60:63], v[132:135], v[176:179], v[60:63]
	v_mfma_f32_16x16x32_bf16 v[56:59], v[140:143], v[176:179], v[56:59]
	v_mfma_f32_16x16x32_bf16 v[44:47], v[132:135], v[204:207], v[44:47]
	v_mfma_f32_16x16x32_bf16 v[40:43], v[140:143], v[204:207], v[40:43]
	v_mfma_f32_16x16x32_bf16 v[28:31], v[132:135], v[212:215], v[28:31]
	v_mfma_f32_16x16x32_bf16 v[24:27], v[140:143], v[212:215], v[24:27]
	v_mfma_f32_16x16x32_bf16 v[12:15], v[132:135], v[220:223], v[12:15]
	v_mfma_f32_16x16x32_bf16 v[8:11], v[140:143], v[220:223], v[8:11]
	v_mfma_f32_16x16x32_bf16 v[60:63], v[136:139], v[186:189], v[60:63]
	v_mfma_f32_16x16x32_bf16 v[56:59], v[144:147], v[186:189], v[56:59]
	v_mfma_f32_16x16x32_bf16 v[44:47], v[136:139], v[208:211], v[44:47]
	v_mfma_f32_16x16x32_bf16 v[40:43], v[144:147], v[208:211], v[40:43]
	v_mfma_f32_16x16x32_bf16 v[28:31], v[136:139], v[216:219], v[28:31]
	v_mfma_f32_16x16x32_bf16 v[24:27], v[144:147], v[216:219], v[24:27]
	v_mfma_f32_16x16x32_bf16 v[12:15], v[136:139], v[224:227], v[12:15]
	v_mfma_f32_16x16x32_bf16 v[8:11], v[144:147], v[224:227], v[8:11]
	v_mfma_f32_16x16x32_bf16 v[52:55], v[148:151], v[176:179], v[52:55]
	v_mfma_f32_16x16x32_bf16 v[48:51], v[168:171], v[176:179], v[48:51]
	v_mfma_f32_16x16x32_bf16 v[36:39], v[148:151], v[204:207], v[36:39]
	v_mfma_f32_16x16x32_bf16 v[32:35], v[168:171], v[204:207], v[32:35]
	v_mfma_f32_16x16x32_bf16 v[20:23], v[148:151], v[212:215], v[20:23]
	v_mfma_f32_16x16x32_bf16 v[16:19], v[168:171], v[212:215], v[16:19]
	v_mfma_f32_16x16x32_bf16 v[4:7], v[148:151], v[220:223], v[4:7]
	v_mfma_f32_16x16x32_bf16 v[0:3], v[168:171], v[220:223], v[0:3]
	v_mfma_f32_16x16x32_bf16 v[52:55], v[164:167], v[186:189], v[52:55]
	v_mfma_f32_16x16x32_bf16 v[48:51], v[172:175], v[186:189], v[48:51]
	v_mfma_f32_16x16x32_bf16 v[36:39], v[164:167], v[208:211], v[36:39]
	v_mfma_f32_16x16x32_bf16 v[32:35], v[172:175], v[208:211], v[32:35]
	v_mfma_f32_16x16x32_bf16 v[20:23], v[164:167], v[216:219], v[20:23]
	v_mfma_f32_16x16x32_bf16 v[16:19], v[172:175], v[216:219], v[16:19]
	v_mfma_f32_16x16x32_bf16 v[4:7], v[164:167], v[224:227], v[4:7]
	v_mfma_f32_16x16x32_bf16 v[0:3], v[172:175], v[224:227], v[0:3]
	s_setprio 0
	s_barrier
	s_add_i32 s58, s58, 2
	s_add_u32 s40, s40, 0x100
	s_addc_u32 s41, s41, 0
	s_cmp_gt_u32 s58, 13
	s_cbranch_scc0 .LBB0_611
	s_and_b64 vcc, exec, s[8:9]
	s_cbranch_vccz .LBB0_614
	s_barrier

; #define PG8_STAGE(bufoff, gbase, voff) do { _Pragma("unroll") for (int _i = 0; _i < 2; ++_i) \
;         __builtin_amdgcn_global_load_lds((const unsigned*)((const char*)(gbase) + (voff)[_i]), (PG8_LAS unsigned*)(lds + (bufoff) + ldsw + _i * 8192), 16, 0, 0); } while (0)
; #define PG8_LDA(dst, b, h) do { _Pragma("unroll") for (int m = 0; m < 4; ++m) _Pragma("unroll") for (int k = 0; k < 2; ++k) dst[m][k] = *(const PG8_LAS bf16x8*)(lds + PG8_SA(b, h) + aoff + m * 2048 + k * 1024); } while (0)
; #define PG8_LDB(dst, b, h) do { _Pragma("unroll") for (int n = 0; n < 2; ++n) _Pragma("unroll") for (int k = 0; k < 2; ++k) dst[n][k] = *(const PG8_LAS bf16x8*)(lds + PG8_SB(b, h) + boff + n * 2048 + k * 1024); } while (0)
; #define PG8_MMA(ai, bj, At, Bt) do { __builtin_amdgcn_s_setprio(1); _Pragma("unroll") for (int m = 0; m < 4; ++m) _Pragma("unroll") for (int n = 0; n < 2; ++n) _Pragma("unroll") for (int k = 0; k < 2; ++k) \
;         acc[ai][bj][m][n] = __builtin_amdgcn_mfma_f32_16x16x32_bf16(Bt[n][k], At[m][k], acc[ai][bj][m][n], 0, 0, 0); __builtin_amdgcn_s_setprio(0); } while (0)
; #define PG8_WAIT_V(n) asm volatile("s_waitcnt vmcnt(" #n ")" ::: "memory")
; #define PG8_WAIT_L(n) asm volatile("s_waitcnt lgkmcnt(" #n ")" ::: "memory")
; #define PG8_WAIT_V8_UNLESS(flag) asm volatile("s_cmp_lg_i32 %0, 0\n\ts_cbranch_scc1 .Lpg8rx%=\n\ts_waitcnt vmcnt(8)\n.Lpg8rx%=:" :: "s"(__builtin_amdgcn_readfirstlane(flag)) : "scc", "memory")
; #define PG8_BAR __builtin_amdgcn_s_barrier()
; #define PG8_SCHED __builtin_amdgcn_sched_barrier(0)
; template <class Epi, class Sched, bool ALIGN_EPI = false, bool SP2 = false>
; __device__ __forceinline__ void gemm_phase(PG8_LAS unsigned char* lds, const Gemm g, const Sched& S, const Epi& E) {
;     ...
;             PG8_WAIT_V8_UNLESS(rx); PG8_WAIT_L(0); PG8_BAR; PG8_MMA(1, 0, At, B0); PG8_MMA(1, 1, At, B1); PG8_BAR; PG8_SCHED;
;             PG8_STAGE(PG8_SA(0, 1), a2 + hstep, voffA); PG8_SCHED; PG8_LDB(B0, 1, 0); PG8_LDB(B1, 1, 1); PG8_SCHED; PG8_LDA(At, 1, 0);
;             PG8_WAIT_V(8); PG8_WAIT_L(0); PG8_BAR; PG8_MMA(0, 0, At, B0); PG8_MMA(0, 1, At, B1); PG8_BAR; PG8_SCHED;
.Lpg8rx7:
	s_waitcnt lgkmcnt(0)
	s_setprio 1
	s_barrier
	v_mfma_f32_16x16x32_bf16 v[60:63], v[120:123], v[164:167], v[60:63]
	v_mfma_f32_16x16x32_bf16 v[56:59], v[132:135], v[164:167], v[56:59]
	v_mfma_f32_16x16x32_bf16 v[44:47], v[120:123], v[172:175], v[44:47]
	v_mfma_f32_16x16x32_bf16 v[40:43], v[132:135], v[172:175], v[40:43]
	v_mfma_f32_16x16x32_bf16 v[28:31], v[120:123], v[180:183], v[28:31]
	v_mfma_f32_16x16x32_bf16 v[24:27], v[132:135], v[180:183], v[24:27]
	v_mfma_f32_16x16x32_bf16 v[12:15], v[120:123], v[188:191], v[12:15]
	v_mfma_f32_16x16x32_bf16 v[8:11], v[132:135], v[188:191], v[8:11]
	v_mfma_f32_16x16x32_bf16 v[60:63], v[128:131], v[168:171], v[60:63]
	v_mfma_f32_16x16x32_bf16 v[56:59], v[136:139], v[168:171], v[56:59]
	v_mfma_f32_16x16x32_bf16 v[44:47], v[128:131], v[176:179], v[44:47]
	v_mfma_f32_16x16x32_bf16 v[40:43], v[136:139], v[176:179], v[40:43]
	v_mfma_f32_16x16x32_bf16 v[28:31], v[128:131], v[184:187], v[28:31]
	v_mfma_f32_16x16x32_bf16 v[24:27], v[136:139], v[184:187], v[24:27]
	v_mfma_f32_16x16x32_bf16 v[12:15], v[128:131], v[214:217], v[12:15]
	v_mfma_f32_16x16x32_bf16 v[8:11], v[136:139], v[214:217], v[8:11]
	v_mfma_f32_16x16x32_bf16 v[52:55], v[140:143], v[164:167], v[52:55]
	v_mfma_f32_16x16x32_bf16 v[48:51], v[156:159], v[164:167], v[48:51]
	v_mfma_f32_16x16x32_bf16 v[36:39], v[140:143], v[172:175], v[36:39]
	v_mfma_f32_16x16x32_bf16 v[32:35], v[156:159], v[172:175], v[32:35]
	v_mfma_f32_16x16x32_bf16 v[20:23], v[140:143], v[180:183], v[20:23]
	v_mfma_f32_16x16x32_bf16 v[16:19], v[156:159], v[180:183], v[16:19]
	v_mfma_f32_16x16x32_bf16 v[4:7], v[140:143], v[188:191], v[4:7]
	v_mfma_f32_16x16x32_bf16 v[0:3], v[156:159], v[188:191], v[0:3]
	v_mfma_f32_16x16x32_bf16 v[52:55], v[144:147], v[168:171], v[52:55]
	v_mfma_f32_16x16x32_bf16 v[48:51], v[160:163], v[168:171], v[48:51]
	v_mfma_f32_16x16x32_bf16 v[36:39], v[144:147], v[176:179], v[36:39]
	v_mfma_f32_16x16x32_bf16 v[32:35], v[160:163], v[176:179], v[32:35]
	v_mfma_f32_16x16x32_bf16 v[20:23], v[144:147], v[184:187], v[20:23]
	v_mfma_f32_16x16x32_bf16 v[16:19], v[160:163], v[184:187], v[16:19]
	v_mfma_f32_16x16x32_bf16 v[4:7], v[144:147], v[214:217], v[4:7]
	v_mfma_f32_16x16x32_bf16 v[0:3], v[160:163], v[214:217], v[0:3]
	s_setprio 0
	s_barrier
	s_mov_b64 s[98:99], s[30:31]
	s_add_u32 s100, s30, 0x100000
	s_addc_u32 s101, s31, 0
	s_add_i32 s30, 0, 0x18000
	s_add_i32 s31, 0, 0x1c000
	v_add_u32_e32 v136, s30, v247
	v_add_u32_e32 v160, s31, v247
	ds_read_b128 v[120:123], v136
	ds_read_b128 v[128:131], v136 offset:1024
	ds_read_b128 v[132:135], v136 offset:2048
	ds_read_b128 v[136:139], v136 offset:3072
	ds_read_b128 v[140:143], v160
	ds_read_b128 v[144:147], v160 offset:1024
	ds_read_b128 v[156:159], v160 offset:2048
	ds_read_b128 v[160:163], v160 offset:3072
	ds_read_b128 v[164:167], v248 offset:32768
	ds_read_b128 v[168:171], v248 offset:33792
	ds_read_b128 v[172:175], v248 offset:34816
	ds_read_b128 v[176:179], v248 offset:35840
	ds_read_b128 v[180:183], v248 offset:36864
	ds_read_b128 v[184:187], v248 offset:37888
	ds_read_b128 v[188:191], v248 offset:38912
	ds_read_b128 v[214:217], v248 offset:39936
	s_mov_b32 m0, s43
	s_nop 0
	global_load_lds_dwordx4 v204, s[100:101]
	s_mov_b32 m0, s44
	s_nop 0
	global_load_lds_dwordx4 v206, s[100:101]
	s_waitcnt vmcnt(8)
	s_waitcnt lgkmcnt(0)
	s_setprio 1
	s_barrier
	v_mfma_f32_16x16x32_bf16 v[152:155], v[120:123], v[164:167], v[152:155]
	v_mfma_f32_16x16x32_bf16 v[148:151], v[132:135], v[164:167], v[148:151]
	v_mfma_f32_16x16x32_bf16 v[108:111], v[120:123], v[172:175], v[108:111]
	v_mfma_f32_16x16x32_bf16 v[104:107], v[132:135], v[172:175], v[104:107]
	v_mfma_f32_16x16x32_bf16 v[92:95], v[120:123], v[180:183], v[92:95]
	v_mfma_f32_16x16x32_bf16 v[88:91], v[132:135], v[180:183], v[88:91]
	v_mfma_f32_16x16x32_bf16 v[76:79], v[120:123], v[188:191], v[76:79]
	v_mfma_f32_16x16x32_bf16 v[72:75], v[132:135], v[188:191], v[72:75]
	v_mfma_f32_16x16x32_bf16 v[152:155], v[128:131], v[168:171], v[152:155]
	v_mfma_f32_16x16x32_bf16 v[148:151], v[136:139], v[168:171], v[148:151]
	v_mfma_f32_16x16x32_bf16 v[108:111], v[128:131], v[176:179], v[108:111]
	v_mfma_f32_16x16x32_bf16 v[104:107], v[136:139], v[176:179], v[104:107]
	v_mfma_f32_16x16x32_bf16 v[92:95], v[128:131], v[184:187], v[92:95]
	v_mfma_f32_16x16x32_bf16 v[88:91], v[136:139], v[184:187], v[88:91]
	v_mfma_f32_16x16x32_bf16 v[76:79], v[128:131], v[214:217], v[76:79]
	v_mfma_f32_16x16x32_bf16 v[72:75], v[136:139], v[214:217], v[72:75]
	v_mfma_f32_16x16x32_bf16 v[124:127], v[140:143], v[164:167], v[124:127]
	v_mfma_f32_16x16x32_bf16 v[112:115], v[156:159], v[164:167], v[112:115]
	v_mfma_f32_16x16x32_bf16 v[100:103], v[140:143], v[172:175], v[100:103]
	v_mfma_f32_16x16x32_bf16 v[96:99], v[156:159], v[172:175], v[96:99]
	v_mfma_f32_16x16x32_bf16 v[84:87], v[140:143], v[180:183], v[84:87]
	v_mfma_f32_16x16x32_bf16 v[80:83], v[156:159], v[180:183], v[80:83]
	v_mfma_f32_16x16x32_bf16 v[68:71], v[140:143], v[188:191], v[68:71]
	v_mfma_f32_16x16x32_bf16 v[64:67], v[156:159], v[188:191], v[64:67]
	v_mfma_f32_16x16x32_bf16 v[124:127], v[144:147], v[168:171], v[124:127]
	v_mfma_f32_16x16x32_bf16 v[112:115], v[160:163], v[168:171], v[112:115]
	v_mfma_f32_16x16x32_bf16 v[100:103], v[144:147], v[176:179], v[100:103]
	v_mfma_f32_16x16x32_bf16 v[96:99], v[160:163], v[176:179], v[96:99]
	v_mfma_f32_16x16x32_bf16 v[84:87], v[144:147], v[184:187], v[84:87]
	v_mfma_f32_16x16x32_bf16 v[80:83], v[160:163], v[184:187], v[80:83]
	v_mfma_f32_16x16x32_bf16 v[68:71], v[144:147], v[214:217], v[68:71]
	v_mfma_f32_16x16x32_bf16 v[64:67], v[160:163], v[214:217], v[64:67]
	s_setprio 0
	s_barrier
; #define PG8_STAGE(bufoff, gbase, voff) do { _Pragma("unroll") for (int _i = 0; _i < 2; ++_i) \
;         __builtin_amdgcn_global_load_lds((const unsigned*)((const char*)(gbase) + (voff)[_i]), (PG8_LAS unsigned*)(lds + (bufoff) + ldsw + _i * 8192), 16, 0, 0); } while (0)
; #define PG8_LDA(dst, b, h) do { _Pragma("unroll") for (int m = 0; m < 4; ++m) _Pragma("unroll") for (int k = 0; k < 2; ++k) dst[m][k] = *(const PG8_LAS bf16x8*)(lds + PG8_SA(b, h) + aoff + m * 2048 + k * 1024); } while (0)
; #define PG8_MMA(ai, bj, At, Bt) do { __builtin_amdgcn_s_setprio(1); _Pragma("unroll") for (int m = 0; m < 4; ++m) _Pragma("unroll") for (int n = 0; n < 2; ++n) _Pragma("unroll") for (int k = 0; k < 2; ++k) \
;         acc[ai][bj][m][n] = __builtin_amdgcn_mfma_f32_16x16x32_bf16(Bt[n][k], At[m][k], acc[ai][bj][m][n], 0, 0, 0); __builtin_amdgcn_s_setprio(0); } while (0)
; #define PG8_WAIT_V(n) asm volatile("s_waitcnt vmcnt(" #n ")" ::: "memory")
; #define PG8_WAIT_L(n) asm volatile("s_waitcnt lgkmcnt(" #n ")" ::: "memory")
; #define PG8_BAR __builtin_amdgcn_s_barrier()
; #define PG8_SCHED __builtin_amdgcn_sched_barrier(0)
; template <class Epi, class Sched, bool ALIGN_EPI = false, bool SP2 = false>
; __device__ __forceinline__ void gemm_phase(PG8_LAS unsigned char* lds, const Gemm g, const Sched& S, const Epi& E) {
;     ...
;             PG8_STAGE(PG8_SB(1, 0), b3, voffB); PG8_STAGE(PG8_SB(1, 1), b3 + hstep, voffB); PG8_STAGE(PG8_SA(1, 0), a3, voffA); PG8_SCHED; PG8_LDA(At, 1, 1);
;             PG8_WAIT_V(8); PG8_WAIT_L(0); PG8_BAR; PG8_MMA(1, 0, At, B0); PG8_MMA(1, 1, At, B1); PG8_BAR; PG8_SCHED;
;     ...
;         if constexpr (ALIGN_EPI) { if (wr == 0) PG8_BAR; }
	ds_read_b128 v[164:167], v248 offset:49152
	ds_read_b128 v[168:171], v248 offset:50176
	ds_read_b128 v[172:175], v248 offset:51200
	ds_read_b128 v[176:179], v248 offset:52224
	ds_read_b128 v[180:183], v248 offset:53248
	ds_read_b128 v[184:187], v248 offset:54272
	ds_read_b128 v[188:191], v248 offset:55296
	ds_read_b128 v[214:217], v248 offset:56320
	s_add_u32 s100, s28, 0x80
	s_addc_u32 s101, s29, 0
	s_add_u32 s28, s28, 0x100080
	s_addc_u32 s29, s29, 0
	s_add_u32 s98, s98, 0x80
	s_addc_u32 s99, s99, 0
	s_add_i32 m0, s30, s39
	s_nop 0
	global_load_lds_dwordx4 v194, s[100:101]
	s_add_i32 m0, m0, 0x2000
	s_nop 0
	global_load_lds_dwordx4 v208, s[100:101]
	s_add_i32 m0, s31, s39
	s_nop 0
	global_load_lds_dwordx4 v194, s[28:29]
	s_add_i32 m0, m0, 0x2000
	s_nop 0
	global_load_lds_dwordx4 v208, s[28:29]
	s_mov_b32 m0, s46
	s_nop 0
	global_load_lds_dwordx4 v204, s[98:99]
	s_mov_b32 m0, s48
	s_nop 0
	global_load_lds_dwordx4 v206, s[98:99]
	s_waitcnt vmcnt(8)
	s_waitcnt lgkmcnt(0)
	s_setprio 1
	s_barrier
	v_mfma_f32_16x16x32_bf16 v[60:63], v[120:123], v[164:167], v[60:63]
	v_mfma_f32_16x16x32_bf16 v[56:59], v[132:135], v[164:167], v[56:59]
	v_mfma_f32_16x16x32_bf16 v[44:47], v[120:123], v[172:175], v[44:47]
	v_mfma_f32_16x16x32_bf16 v[40:43], v[132:135], v[172:175], v[40:43]
	v_mfma_f32_16x16x32_bf16 v[28:31], v[120:123], v[180:183], v[28:31]
	v_mfma_f32_16x16x32_bf16 v[24:27], v[132:135], v[180:183], v[24:27]
	v_mfma_f32_16x16x32_bf16 v[12:15], v[120:123], v[188:191], v[12:15]
	v_mfma_f32_16x16x32_bf16 v[8:11], v[132:135], v[188:191], v[8:11]
	v_mfma_f32_16x16x32_bf16 v[60:63], v[128:131], v[168:171], v[60:63]
	v_mfma_f32_16x16x32_bf16 v[56:59], v[136:139], v[168:171], v[56:59]
	v_mfma_f32_16x16x32_bf16 v[44:47], v[128:131], v[176:179], v[44:47]
	v_mfma_f32_16x16x32_bf16 v[40:43], v[136:139], v[176:179], v[40:43]
	v_mfma_f32_16x16x32_bf16 v[28:31], v[128:131], v[184:187], v[28:31]
	v_mfma_f32_16x16x32_bf16 v[24:27], v[136:139], v[184:187], v[24:27]
	v_mfma_f32_16x16x32_bf16 v[12:15], v[128:131], v[214:217], v[12:15]
	v_mfma_f32_16x16x32_bf16 v[8:11], v[136:139], v[214:217], v[8:11]
	v_mfma_f32_16x16x32_bf16 v[52:55], v[140:143], v[164:167], v[52:55]
	v_mfma_f32_16x16x32_bf16 v[48:51], v[156:159], v[164:167], v[48:51]
	v_mfma_f32_16x16x32_bf16 v[36:39], v[140:143], v[172:175], v[36:39]
	v_mfma_f32_16x16x32_bf16 v[32:35], v[156:159], v[172:175], v[32:35]
	v_mfma_f32_16x16x32_bf16 v[20:23], v[140:143], v[180:183], v[20:23]
	v_mfma_f32_16x16x32_bf16 v[16:19], v[156:159], v[180:183], v[16:19]
	v_mfma_f32_16x16x32_bf16 v[4:7], v[140:143], v[188:191], v[4:7]
	v_mfma_f32_16x16x32_bf16 v[0:3], v[156:159], v[188:191], v[0:3]
	v_mfma_f32_16x16x32_bf16 v[52:55], v[144:147], v[168:171], v[52:55]
	v_mfma_f32_16x16x32_bf16 v[48:51], v[160:163], v[168:171], v[48:51]
	v_mfma_f32_16x16x32_bf16 v[36:39], v[144:147], v[176:179], v[36:39]
	v_mfma_f32_16x16x32_bf16 v[32:35], v[160:163], v[176:179], v[32:35]
	v_mfma_f32_16x16x32_bf16 v[20:23], v[144:147], v[184:187], v[20:23]
	v_mfma_f32_16x16x32_bf16 v[16:19], v[160:163], v[184:187], v[16:19]
	v_mfma_f32_16x16x32_bf16 v[4:7], v[144:147], v[214:217], v[4:7]
	v_mfma_f32_16x16x32_bf16 v[0:3], v[160:163], v[214:217], v[0:3]
	s_setprio 0
	s_barrier
	s_add_i32 s56, s56, 2
	s_add_u32 s40, s40, 0x100
	s_addc_u32 s41, s41, 0
	s_cmp_gt_u32 s56, 61
	s_cbranch_scc0 .LBB0_965
	s_and_b64 vcc, exec, s[10:11]
	s_cbranch_vccz .LBB0_968
	s_barrier

; #define PG8_STAGE(bufoff, gbase, voff) do { _Pragma("unroll") for (int _i = 0; _i < 2; ++_i) \
;         __builtin_amdgcn_global_load_lds((const unsigned*)((const char*)(gbase) + (voff)[_i]), (PG8_LAS unsigned*)(lds + (bufoff) + ldsw + _i * 8192), 16, 0, 0); } while (0)
; #define PG8_LDA(dst, b, h) do { _Pragma("unroll") for (int m = 0; m < 4; ++m) _Pragma("unroll") for (int k = 0; k < 2; ++k) dst[m][k] = *(const PG8_LAS bf16x8*)(lds + PG8_SA(b, h) + aoff + m * 2048 + k * 1024); } while (0)
; #define PG8_LDB(dst, b, h) do { _Pragma("unroll") for (int n = 0; n < 2; ++n) _Pragma("unroll") for (int k = 0; k < 2; ++k) dst[n][k] = *(const PG8_LAS bf16x8*)(lds + PG8_SB(b, h) + boff + n * 2048 + k * 1024); } while (0)
; #define PG8_MMA(ai, bj, At, Bt) do { __builtin_amdgcn_s_setprio(1); _Pragma("unroll") for (int m = 0; m < 4; ++m) _Pragma("unroll") for (int n = 0; n < 2; ++n) _Pragma("unroll") for (int k = 0; k < 2; ++k) \
;         acc[ai][bj][m][n] = __builtin_amdgcn_mfma_f32_16x16x32_bf16(Bt[n][k], At[m][k], acc[ai][bj][m][n], 0, 0, 0); __builtin_amdgcn_s_setprio(0); } while (0)
; #define PG8_WAIT_V(n) asm volatile("s_waitcnt vmcnt(" #n ")" ::: "memory")
; #define PG8_WAIT_L(n) asm volatile("s_waitcnt lgkmcnt(" #n ")" ::: "memory")
; #define PG8_WAIT_V8_UNLESS(flag) asm volatile("s_cmp_lg_i32 %0, 0\n\ts_cbranch_scc1 .Lpg8rx%=\n\ts_waitcnt vmcnt(8)\n.Lpg8rx%=:" :: "s"(__builtin_amdgcn_readfirstlane(flag)) : "scc", "memory")
; #define PG8_BAR __builtin_amdgcn_s_barrier()
; #define PG8_SCHED __builtin_amdgcn_sched_barrier(0)
; template <class Epi, class Sched, bool ALIGN_EPI = false, bool SP2 = false>
; __device__ __forceinline__ void gemm_phase(PG8_LAS unsigned char* lds, const Gemm g, const Sched& S, const Epi& E) {
;     ...
;             PG8_WAIT_V8_UNLESS(rx); PG8_WAIT_L(0); PG8_BAR; PG8_MMA(1, 0, At, B0); PG8_MMA(1, 1, At, B1); PG8_BAR; PG8_SCHED;
;             PG8_STAGE(PG8_SA(0, 1), a2 + hstep, voffA); PG8_SCHED; PG8_LDB(B0, 1, 0); PG8_LDB(B1, 1, 1); PG8_SCHED; PG8_LDA(At, 1, 0);
;             PG8_WAIT_V(8); PG8_WAIT_L(0); PG8_BAR; PG8_MMA(0, 0, At, B0); PG8_MMA(0, 1, At, B1); PG8_BAR; PG8_SCHED;
.Lpg8rx9:
	s_waitcnt lgkmcnt(0)
	s_setprio 1
	s_barrier
	v_mfma_f32_16x16x32_bf16 v[60:63], v[140:143], v[172:175], v[60:63]
	v_mfma_f32_16x16x32_bf16 v[56:59], v[148:151], v[172:175], v[56:59]
	v_mfma_f32_16x16x32_bf16 v[44:47], v[140:143], v[180:183], v[44:47]
	v_mfma_f32_16x16x32_bf16 v[40:43], v[148:151], v[180:183], v[40:43]
	v_mfma_f32_16x16x32_bf16 v[28:31], v[140:143], v[188:191], v[28:31]
	v_mfma_f32_16x16x32_bf16 v[24:27], v[148:151], v[188:191], v[24:27]
	v_mfma_f32_16x16x32_bf16 v[12:15], v[140:143], v[208:211], v[12:15]
	v_mfma_f32_16x16x32_bf16 v[8:11], v[148:151], v[208:211], v[8:11]
	v_mfma_f32_16x16x32_bf16 v[60:63], v[144:147], v[176:179], v[60:63]
	v_mfma_f32_16x16x32_bf16 v[56:59], v[152:155], v[176:179], v[56:59]
	v_mfma_f32_16x16x32_bf16 v[44:47], v[144:147], v[184:187], v[44:47]
	v_mfma_f32_16x16x32_bf16 v[40:43], v[152:155], v[184:187], v[40:43]
	v_mfma_f32_16x16x32_bf16 v[28:31], v[144:147], v[204:207], v[28:31]
	v_mfma_f32_16x16x32_bf16 v[24:27], v[152:155], v[204:207], v[24:27]
	v_mfma_f32_16x16x32_bf16 v[12:15], v[144:147], v[212:215], v[12:15]
	v_mfma_f32_16x16x32_bf16 v[8:11], v[152:155], v[212:215], v[8:11]
	v_mfma_f32_16x16x32_bf16 v[52:55], v[156:159], v[172:175], v[52:55]
	v_mfma_f32_16x16x32_bf16 v[48:51], v[164:167], v[172:175], v[48:51]
	v_mfma_f32_16x16x32_bf16 v[36:39], v[156:159], v[180:183], v[36:39]
	v_mfma_f32_16x16x32_bf16 v[32:35], v[164:167], v[180:183], v[32:35]
	v_mfma_f32_16x16x32_bf16 v[20:23], v[156:159], v[188:191], v[20:23]
	v_mfma_f32_16x16x32_bf16 v[16:19], v[164:167], v[188:191], v[16:19]
	v_mfma_f32_16x16x32_bf16 v[4:7], v[156:159], v[208:211], v[4:7]
	v_mfma_f32_16x16x32_bf16 v[0:3], v[164:167], v[208:211], v[0:3]
	v_mfma_f32_16x16x32_bf16 v[52:55], v[160:163], v[176:179], v[52:55]
	v_mfma_f32_16x16x32_bf16 v[48:51], v[168:171], v[176:179], v[48:51]
	v_mfma_f32_16x16x32_bf16 v[36:39], v[160:163], v[184:187], v[36:39]
	v_mfma_f32_16x16x32_bf16 v[32:35], v[168:171], v[184:187], v[32:35]
	v_mfma_f32_16x16x32_bf16 v[20:23], v[160:163], v[204:207], v[20:23]
	v_mfma_f32_16x16x32_bf16 v[16:19], v[168:171], v[204:207], v[16:19]
	v_mfma_f32_16x16x32_bf16 v[4:7], v[160:163], v[212:215], v[4:7]
	v_mfma_f32_16x16x32_bf16 v[0:3], v[168:171], v[212:215], v[0:3]
	s_setprio 0
	s_barrier
	s_add_u32 s24, s24, s8
	s_addc_u32 s25, s25, s9
	s_mov_b32 m0, s46
	v_lshl_add_u64 v[140:141], s[24:25], 0, v[128:129]
	global_load_lds_dwordx4 v[140:141], off
	v_lshl_add_u64 v[140:141], s[24:25], 0, v[130:131]
	s_mov_b32 m0, s48
	s_nop 0
	global_load_lds_dwordx4 v[140:141], off
	s_add_i32 s24, 0, 0x18000
	s_add_i32 s25, 0, 0x1c000
	v_add_u32_e32 v152, s24, v138
	v_add_u32_e32 v168, s25, v138
	ds_read_b128 v[140:143], v152
	ds_read_b128 v[144:147], v152 offset:1024
	ds_read_b128 v[148:151], v152 offset:2048
	ds_read_b128 v[152:155], v152 offset:3072
	ds_read_b128 v[156:159], v168
	ds_read_b128 v[160:163], v168 offset:1024
	ds_read_b128 v[164:167], v168 offset:2048
	ds_read_b128 v[168:171], v168 offset:3072
	ds_read_b128 v[172:175], v139 offset:32768
	ds_read_b128 v[176:179], v139 offset:33792
	ds_read_b128 v[180:183], v139 offset:34816
	ds_read_b128 v[184:187], v139 offset:35840
	ds_read_b128 v[188:191], v139 offset:36864
	ds_read_b128 v[204:207], v139 offset:37888
	ds_read_b128 v[208:211], v139 offset:38912
	ds_read_b128 v[212:215], v139 offset:39936
	s_waitcnt vmcnt(8)
	s_waitcnt lgkmcnt(0)
	s_setprio 1
	s_barrier
	v_mfma_f32_16x16x32_bf16 v[120:123], v[140:143], v[172:175], v[120:123]
	v_mfma_f32_16x16x32_bf16 v[124:127], v[148:151], v[172:175], v[124:127]
	v_mfma_f32_16x16x32_bf16 v[108:111], v[140:143], v[180:183], v[108:111]
	v_mfma_f32_16x16x32_bf16 v[104:107], v[148:151], v[180:183], v[104:107]
	v_mfma_f32_16x16x32_bf16 v[92:95], v[140:143], v[188:191], v[92:95]
	v_mfma_f32_16x16x32_bf16 v[88:91], v[148:151], v[188:191], v[88:91]
	v_mfma_f32_16x16x32_bf16 v[76:79], v[140:143], v[208:211], v[76:79]
	v_mfma_f32_16x16x32_bf16 v[72:75], v[148:151], v[208:211], v[72:75]
	v_mfma_f32_16x16x32_bf16 v[120:123], v[144:147], v[176:179], v[120:123]
	v_mfma_f32_16x16x32_bf16 v[124:127], v[152:155], v[176:179], v[124:127]
	v_mfma_f32_16x16x32_bf16 v[108:111], v[144:147], v[184:187], v[108:111]
	v_mfma_f32_16x16x32_bf16 v[104:107], v[152:155], v[184:187], v[104:107]
	v_mfma_f32_16x16x32_bf16 v[92:95], v[144:147], v[204:207], v[92:95]
	v_mfma_f32_16x16x32_bf16 v[88:91], v[152:155], v[204:207], v[88:91]
	v_mfma_f32_16x16x32_bf16 v[76:79], v[144:147], v[212:215], v[76:79]
	v_mfma_f32_16x16x32_bf16 v[72:75], v[152:155], v[212:215], v[72:75]
	v_mfma_f32_16x16x32_bf16 v[116:119], v[156:159], v[172:175], v[116:119]
	v_mfma_f32_16x16x32_bf16 v[112:115], v[164:167], v[172:175], v[112:115]
	v_mfma_f32_16x16x32_bf16 v[100:103], v[156:159], v[180:183], v[100:103]
	v_mfma_f32_16x16x32_bf16 v[96:99], v[164:167], v[180:183], v[96:99]
	v_mfma_f32_16x16x32_bf16 v[84:87], v[156:159], v[188:191], v[84:87]
	v_mfma_f32_16x16x32_bf16 v[80:83], v[164:167], v[188:191], v[80:83]
	v_mfma_f32_16x16x32_bf16 v[68:71], v[156:159], v[208:211], v[68:71]
	v_mfma_f32_16x16x32_bf16 v[64:67], v[164:167], v[208:211], v[64:67]
	v_mfma_f32_16x16x32_bf16 v[116:119], v[160:163], v[176:179], v[116:119]
	v_mfma_f32_16x16x32_bf16 v[112:115], v[168:171], v[176:179], v[112:115]
	v_mfma_f32_16x16x32_bf16 v[100:103], v[160:163], v[184:187], v[100:103]
	v_mfma_f32_16x16x32_bf16 v[96:99], v[168:171], v[184:187], v[96:99]
	v_mfma_f32_16x16x32_bf16 v[84:87], v[160:163], v[204:207], v[84:87]
	v_mfma_f32_16x16x32_bf16 v[80:83], v[168:171], v[204:207], v[80:83]
	v_mfma_f32_16x16x32_bf16 v[68:71], v[160:163], v[212:215], v[68:71]
	v_mfma_f32_16x16x32_bf16 v[64:67], v[168:171], v[212:215], v[64:67]
	s_setprio 0
	s_barrier
; #define PG8_STAGE(bufoff, gbase, voff) do { _Pragma("unroll") for (int _i = 0; _i < 2; ++_i) \
;         __builtin_amdgcn_global_load_lds((const unsigned*)((const char*)(gbase) + (voff)[_i]), (PG8_LAS unsigned*)(lds + (bufoff) + ldsw + _i * 8192), 16, 0, 0); } while (0)
; #define PG8_LDA(dst, b, h) do { _Pragma("unroll") for (int m = 0; m < 4; ++m) _Pragma("unroll") for (int k = 0; k < 2; ++k) dst[m][k] = *(const PG8_LAS bf16x8*)(lds + PG8_SA(b, h) + aoff + m * 2048 + k * 1024); } while (0)
; #define PG8_MMA(ai, bj, At, Bt) do { __builtin_amdgcn_s_setprio(1); _Pragma("unroll") for (int m = 0; m < 4; ++m) _Pragma("unroll") for (int n = 0; n < 2; ++n) _Pragma("unroll") for (int k = 0; k < 2; ++k) \
;         acc[ai][bj][m][n] = __builtin_amdgcn_mfma_f32_16x16x32_bf16(Bt[n][k], At[m][k], acc[ai][bj][m][n], 0, 0, 0); __builtin_amdgcn_s_setprio(0); } while (0)
; #define PG8_WAIT_V(n) asm volatile("s_waitcnt vmcnt(" #n ")" ::: "memory")
; #define PG8_WAIT_L(n) asm volatile("s_waitcnt lgkmcnt(" #n ")" ::: "memory")
; #define PG8_BAR __builtin_amdgcn_s_barrier()
; #define PG8_SCHED __builtin_amdgcn_sched_barrier(0)
; template <class Epi, class Sched, bool ALIGN_EPI = false, bool SP2 = false>
; __device__ __forceinline__ void gemm_phase(PG8_LAS unsigned char* lds, const Gemm g, const Sched& S, const Epi& E) {
;     ...
;             PG8_STAGE(PG8_SB(1, 0), b3, voffB); PG8_STAGE(PG8_SB(1, 1), b3 + hstep, voffB); PG8_STAGE(PG8_SA(1, 0), a3, voffA); PG8_SCHED; PG8_LDA(At, 1, 1);
;             PG8_WAIT_V(8); PG8_WAIT_L(0); PG8_BAR; PG8_MMA(1, 0, At, B0); PG8_MMA(1, 1, At, B1); PG8_BAR; PG8_SCHED;
;     ...
;         if constexpr (ALIGN_EPI) { if (wr == 0) PG8_BAR; }
	s_add_i32 s24, s24, s34
	v_lshl_add_u64 v[172:173], v[216:217], 0, s[74:75]
	s_mov_b32 m0, s24
	s_nop 0
	global_load_lds_dwordx4 v[172:173], off
	v_lshl_add_u64 v[172:173], v[218:219], 0, s[74:75]
	s_add_i32 m0, s24, 0x2000
	s_add_i32 s24, s25, s34
	global_load_lds_dwordx4 v[172:173], off
	v_lshl_add_u64 v[172:173], v[220:221], 0, s[74:75]
	s_mov_b32 m0, s24
	s_nop 0
	global_load_lds_dwordx4 v[172:173], off
	v_lshl_add_u64 v[172:173], v[222:223], 0, s[74:75]
	s_add_i32 m0, s24, 0x2000
	s_nop 0
	global_load_lds_dwordx4 v[172:173], off
	v_lshl_add_u64 v[172:173], v[224:225], 0, s[74:75]
	s_mov_b32 m0, s53
	s_nop 0
	global_load_lds_dwordx4 v[172:173], off
	v_lshl_add_u64 v[172:173], v[226:227], 0, s[74:75]
	s_mov_b32 m0, s54
	s_nop 0
	global_load_lds_dwordx4 v[172:173], off
	ds_read_b128 v[172:175], v139 offset:49152
	ds_read_b128 v[176:179], v139 offset:50176
	ds_read_b128 v[180:183], v139 offset:51200
	ds_read_b128 v[184:187], v139 offset:52224
	ds_read_b128 v[188:191], v139 offset:53248
	ds_read_b128 v[204:207], v139 offset:54272
	ds_read_b128 v[208:211], v139 offset:55296
	ds_read_b128 v[212:215], v139 offset:56320
	s_waitcnt vmcnt(8)
	s_waitcnt lgkmcnt(0)
	s_setprio 1
	s_barrier
	v_mfma_f32_16x16x32_bf16 v[60:63], v[140:143], v[172:175], v[60:63]
	v_mfma_f32_16x16x32_bf16 v[56:59], v[148:151], v[172:175], v[56:59]
	v_mfma_f32_16x16x32_bf16 v[44:47], v[140:143], v[180:183], v[44:47]
	v_mfma_f32_16x16x32_bf16 v[40:43], v[148:151], v[180:183], v[40:43]
	v_mfma_f32_16x16x32_bf16 v[28:31], v[140:143], v[188:191], v[28:31]
	v_mfma_f32_16x16x32_bf16 v[24:27], v[148:151], v[188:191], v[24:27]
	v_mfma_f32_16x16x32_bf16 v[12:15], v[140:143], v[208:211], v[12:15]
	v_mfma_f32_16x16x32_bf16 v[8:11], v[148:151], v[208:211], v[8:11]
	v_mfma_f32_16x16x32_bf16 v[60:63], v[144:147], v[176:179], v[60:63]
	v_mfma_f32_16x16x32_bf16 v[56:59], v[152:155], v[176:179], v[56:59]
	v_mfma_f32_16x16x32_bf16 v[44:47], v[144:147], v[184:187], v[44:47]
	v_mfma_f32_16x16x32_bf16 v[40:43], v[152:155], v[184:187], v[40:43]
	v_mfma_f32_16x16x32_bf16 v[28:31], v[144:147], v[204:207], v[28:31]
	v_mfma_f32_16x16x32_bf16 v[24:27], v[152:155], v[204:207], v[24:27]
	v_mfma_f32_16x16x32_bf16 v[12:15], v[144:147], v[212:215], v[12:15]
	v_mfma_f32_16x16x32_bf16 v[8:11], v[152:155], v[212:215], v[8:11]
	v_mfma_f32_16x16x32_bf16 v[52:55], v[156:159], v[172:175], v[52:55]
	v_mfma_f32_16x16x32_bf16 v[48:51], v[164:167], v[172:175], v[48:51]
	v_mfma_f32_16x16x32_bf16 v[36:39], v[156:159], v[180:183], v[36:39]
	v_mfma_f32_16x16x32_bf16 v[32:35], v[164:167], v[180:183], v[32:35]
	v_mfma_f32_16x16x32_bf16 v[20:23], v[156:159], v[188:191], v[20:23]
	v_mfma_f32_16x16x32_bf16 v[16:19], v[164:167], v[188:191], v[16:19]
	v_mfma_f32_16x16x32_bf16 v[4:7], v[156:159], v[208:211], v[4:7]
	v_mfma_f32_16x16x32_bf16 v[0:3], v[164:167], v[208:211], v[0:3]
	v_mfma_f32_16x16x32_bf16 v[52:55], v[160:163], v[176:179], v[52:55]
	v_mfma_f32_16x16x32_bf16 v[48:51], v[168:171], v[176:179], v[48:51]
	v_mfma_f32_16x16x32_bf16 v[36:39], v[160:163], v[184:187], v[36:39]
	v_mfma_f32_16x16x32_bf16 v[32:35], v[168:171], v[184:187], v[32:35]
	v_mfma_f32_16x16x32_bf16 v[20:23], v[160:163], v[204:207], v[20:23]
	v_mfma_f32_16x16x32_bf16 v[16:19], v[168:171], v[204:207], v[16:19]
	v_mfma_f32_16x16x32_bf16 v[4:7], v[160:163], v[212:215], v[4:7]
	v_mfma_f32_16x16x32_bf16 v[0:3], v[168:171], v[212:215], v[0:3]
	s_setprio 0
	s_barrier
	s_add_u32 s22, s22, 0x100
	s_addc_u32 s23, s23, 0
	s_add_u32 s60, s60, 0x100
	s_addc_u32 s61, s61, 0
	s_cmp_ge_i32 s62, s51
	s_mov_b32 s24, s62
	s_cbranch_scc0 .LBB0_1091
.LBB0_1092:
	s_and_b64 vcc, exec, s[16:17]
	s_cbranch_vccz .LBB0_1094
	s_barrier

; #define PG8_STAGE(bufoff, gbase, voff) do { _Pragma("unroll") for (int _i = 0; _i < 2; ++_i) \
;         __builtin_amdgcn_global_load_lds((const unsigned*)((const char*)(gbase) + (voff)[_i]), (PG8_LAS unsigned*)(lds + (bufoff) + ldsw + _i * 8192), 16, 0, 0); } while (0)
; #define PG8_LDA(dst, b, h) do { _Pragma("unroll") for (int m = 0; m < 4; ++m) _Pragma("unroll") for (int k = 0; k < 2; ++k) dst[m][k] = *(const PG8_LAS bf16x8*)(lds + PG8_SA(b, h) + aoff + m * 2048 + k * 1024); } while (0)
; #define PG8_LDB(dst, b, h) do { _Pragma("unroll") for (int n = 0; n < 2; ++n) _Pragma("unroll") for (int k = 0; k < 2; ++k) dst[n][k] = *(const PG8_LAS bf16x8*)(lds + PG8_SB(b, h) + boff + n * 2048 + k * 1024); } while (0)
; #define PG8_MMA(ai, bj, At, Bt) do { __builtin_amdgcn_s_setprio(1); _Pragma("unroll") for (int m = 0; m < 4; ++m) _Pragma("unroll") for (int n = 0; n < 2; ++n) _Pragma("unroll") for (int k = 0; k < 2; ++k) \
;         acc[ai][bj][m][n] = __builtin_amdgcn_mfma_f32_16x16x32_bf16(Bt[n][k], At[m][k], acc[ai][bj][m][n], 0, 0, 0); __builtin_amdgcn_s_setprio(0); } while (0)
; #define PG8_WAIT_V(n) asm volatile("s_waitcnt vmcnt(" #n ")" ::: "memory")
; #define PG8_WAIT_L(n) asm volatile("s_waitcnt lgkmcnt(" #n ")" ::: "memory")
; #define PG8_WAIT_V8_UNLESS(flag) asm volatile("s_cmp_lg_i32 %0, 0\n\ts_cbranch_scc1 .Lpg8rx%=\n\ts_waitcnt vmcnt(8)\n.Lpg8rx%=:" :: "s"(__builtin_amdgcn_readfirstlane(flag)) : "scc", "memory")
; #define PG8_BAR __builtin_amdgcn_s_barrier()
; #define PG8_SCHED __builtin_amdgcn_sched_barrier(0)
; template <class Epi, class Sched, bool ALIGN_EPI = false, bool SP2 = false>
; __device__ __forceinline__ void gemm_phase(PG8_LAS unsigned char* lds, const Gemm g, const Sched& S, const Epi& E) {
;     ...
;             PG8_WAIT_V8_UNLESS(rx); PG8_WAIT_L(0); PG8_BAR; PG8_MMA(1, 0, At, B0); PG8_MMA(1, 1, At, B1); PG8_BAR; PG8_SCHED;
;             PG8_STAGE(PG8_SA(0, 1), a2 + hstep, voffA); PG8_SCHED; PG8_LDB(B0, 1, 0); PG8_LDB(B1, 1, 1); PG8_SCHED; PG8_LDA(At, 1, 0);
;             PG8_WAIT_V(8); PG8_WAIT_L(0); PG8_BAR; PG8_MMA(0, 0, At, B0); PG8_MMA(0, 1, At, B1); PG8_BAR; PG8_SCHED;
.Lpg8rx11:
	s_waitcnt lgkmcnt(0)
	s_setprio 1
	s_barrier
	v_mfma_f32_16x16x32_bf16 v[60:63], v[132:135], v[180:183], v[60:63]
	v_mfma_f32_16x16x32_bf16 v[56:59], v[140:143], v[180:183], v[56:59]
	v_mfma_f32_16x16x32_bf16 v[44:47], v[132:135], v[188:191], v[44:47]
	v_mfma_f32_16x16x32_bf16 v[40:43], v[140:143], v[188:191], v[40:43]
	v_mfma_f32_16x16x32_bf16 v[28:31], v[132:135], v[208:211], v[28:31]
	v_mfma_f32_16x16x32_bf16 v[24:27], v[140:143], v[208:211], v[24:27]
	v_mfma_f32_16x16x32_bf16 v[12:15], v[132:135], v[216:219], v[12:15]
	v_mfma_f32_16x16x32_bf16 v[8:11], v[140:143], v[216:219], v[8:11]
	v_mfma_f32_16x16x32_bf16 v[60:63], v[136:139], v[184:187], v[60:63]
	v_mfma_f32_16x16x32_bf16 v[56:59], v[144:147], v[184:187], v[56:59]
	v_mfma_f32_16x16x32_bf16 v[44:47], v[136:139], v[204:207], v[44:47]
	v_mfma_f32_16x16x32_bf16 v[40:43], v[144:147], v[204:207], v[40:43]
	v_mfma_f32_16x16x32_bf16 v[28:31], v[136:139], v[212:215], v[28:31]
	v_mfma_f32_16x16x32_bf16 v[24:27], v[144:147], v[212:215], v[24:27]
	v_mfma_f32_16x16x32_bf16 v[12:15], v[136:139], v[220:223], v[12:15]
	v_mfma_f32_16x16x32_bf16 v[8:11], v[144:147], v[220:223], v[8:11]
	v_mfma_f32_16x16x32_bf16 v[52:55], v[160:163], v[180:183], v[52:55]
	v_mfma_f32_16x16x32_bf16 v[48:51], v[168:171], v[180:183], v[48:51]
	v_mfma_f32_16x16x32_bf16 v[36:39], v[160:163], v[188:191], v[36:39]
	v_mfma_f32_16x16x32_bf16 v[32:35], v[168:171], v[188:191], v[32:35]
	v_mfma_f32_16x16x32_bf16 v[20:23], v[160:163], v[208:211], v[20:23]
	v_mfma_f32_16x16x32_bf16 v[16:19], v[168:171], v[208:211], v[16:19]
	v_mfma_f32_16x16x32_bf16 v[4:7], v[160:163], v[216:219], v[4:7]
	v_mfma_f32_16x16x32_bf16 v[0:3], v[168:171], v[216:219], v[0:3]
	v_mfma_f32_16x16x32_bf16 v[52:55], v[164:167], v[184:187], v[52:55]
	v_mfma_f32_16x16x32_bf16 v[48:51], v[176:179], v[184:187], v[48:51]
	v_mfma_f32_16x16x32_bf16 v[36:39], v[164:167], v[204:207], v[36:39]
	v_mfma_f32_16x16x32_bf16 v[32:35], v[176:179], v[204:207], v[32:35]
	v_mfma_f32_16x16x32_bf16 v[20:23], v[164:167], v[212:215], v[20:23]
	v_mfma_f32_16x16x32_bf16 v[16:19], v[176:179], v[212:215], v[16:19]
	v_mfma_f32_16x16x32_bf16 v[4:7], v[164:167], v[220:223], v[4:7]
	v_mfma_f32_16x16x32_bf16 v[0:3], v[176:179], v[220:223], v[0:3]
	s_setprio 0
	s_barrier
	s_mov_b64 s[98:99], s[30:31]
	s_add_u32 s100, s30, 0x40000
	s_addc_u32 s101, s31, 0
	s_add_i32 s30, 0, 0x18000
	s_add_i32 s31, 0, 0x1c000
	v_add_u32_e32 v144, s30, v174
	v_add_u32_e32 v176, s31, v174
	ds_read_b128 v[132:135], v144
	ds_read_b128 v[136:139], v144 offset:1024
	ds_read_b128 v[140:143], v144 offset:2048
	ds_read_b128 v[144:147], v144 offset:3072
	ds_read_b128 v[160:163], v176
	ds_read_b128 v[164:167], v176 offset:1024
	ds_read_b128 v[168:171], v176 offset:2048
	ds_read_b128 v[176:179], v176 offset:3072
	ds_read_b128 v[180:183], v175 offset:32768
	ds_read_b128 v[184:187], v175 offset:33792
	ds_read_b128 v[188:191], v175 offset:34816
	ds_read_b128 v[204:207], v175 offset:35840
	ds_read_b128 v[208:211], v175 offset:36864
	ds_read_b128 v[212:215], v175 offset:37888
	ds_read_b128 v[216:219], v175 offset:38912
	ds_read_b128 v[220:223], v175 offset:39936
	s_mov_b32 m0, s50
	s_nop 0
	global_load_lds_dwordx4 v148, s[100:101]
	s_mov_b32 m0, s51
	s_nop 0
	global_load_lds_dwordx4 v152, s[100:101]
	s_waitcnt vmcnt(8)
	s_waitcnt lgkmcnt(0)
	s_setprio 1
	s_barrier
	v_mfma_f32_16x16x32_bf16 v[124:127], v[132:135], v[180:183], v[124:127]
	v_mfma_f32_16x16x32_bf16 v[120:123], v[140:143], v[180:183], v[120:123]
	v_mfma_f32_16x16x32_bf16 v[108:111], v[132:135], v[188:191], v[108:111]
	v_mfma_f32_16x16x32_bf16 v[104:107], v[140:143], v[188:191], v[104:107]
	v_mfma_f32_16x16x32_bf16 v[92:95], v[132:135], v[208:211], v[92:95]
	v_mfma_f32_16x16x32_bf16 v[88:91], v[140:143], v[208:211], v[88:91]
	v_mfma_f32_16x16x32_bf16 v[76:79], v[132:135], v[216:219], v[76:79]
	v_mfma_f32_16x16x32_bf16 v[72:75], v[140:143], v[216:219], v[72:75]
	v_mfma_f32_16x16x32_bf16 v[124:127], v[136:139], v[184:187], v[124:127]
	v_mfma_f32_16x16x32_bf16 v[120:123], v[144:147], v[184:187], v[120:123]
	v_mfma_f32_16x16x32_bf16 v[108:111], v[136:139], v[204:207], v[108:111]
	v_mfma_f32_16x16x32_bf16 v[104:107], v[144:147], v[204:207], v[104:107]
	v_mfma_f32_16x16x32_bf16 v[92:95], v[136:139], v[212:215], v[92:95]
	v_mfma_f32_16x16x32_bf16 v[88:91], v[144:147], v[212:215], v[88:91]
	v_mfma_f32_16x16x32_bf16 v[76:79], v[136:139], v[220:223], v[76:79]
	v_mfma_f32_16x16x32_bf16 v[72:75], v[144:147], v[220:223], v[72:75]
	v_mfma_f32_16x16x32_bf16 v[116:119], v[160:163], v[180:183], v[116:119]
	v_mfma_f32_16x16x32_bf16 v[112:115], v[168:171], v[180:183], v[112:115]
	v_mfma_f32_16x16x32_bf16 v[100:103], v[160:163], v[188:191], v[100:103]
	v_mfma_f32_16x16x32_bf16 v[96:99], v[168:171], v[188:191], v[96:99]
	v_mfma_f32_16x16x32_bf16 v[84:87], v[160:163], v[208:211], v[84:87]
	v_mfma_f32_16x16x32_bf16 v[80:83], v[168:171], v[208:211], v[80:83]
	v_mfma_f32_16x16x32_bf16 v[68:71], v[160:163], v[216:219], v[68:71]
	v_mfma_f32_16x16x32_bf16 v[64:67], v[168:171], v[216:219], v[64:67]
	v_mfma_f32_16x16x32_bf16 v[116:119], v[164:167], v[184:187], v[116:119]
	v_mfma_f32_16x16x32_bf16 v[112:115], v[176:179], v[184:187], v[112:115]
	v_mfma_f32_16x16x32_bf16 v[100:103], v[164:167], v[204:207], v[100:103]
	v_mfma_f32_16x16x32_bf16 v[96:99], v[176:179], v[204:207], v[96:99]
	v_mfma_f32_16x16x32_bf16 v[84:87], v[164:167], v[212:215], v[84:87]
	v_mfma_f32_16x16x32_bf16 v[80:83], v[176:179], v[212:215], v[80:83]
	v_mfma_f32_16x16x32_bf16 v[68:71], v[164:167], v[220:223], v[68:71]
	v_mfma_f32_16x16x32_bf16 v[64:67], v[176:179], v[220:223], v[64:67]
	s_setprio 0
	s_barrier
; #define PG8_STAGE(bufoff, gbase, voff) do { _Pragma("unroll") for (int _i = 0; _i < 2; ++_i) \
;         __builtin_amdgcn_global_load_lds((const unsigned*)((const char*)(gbase) + (voff)[_i]), (PG8_LAS unsigned*)(lds + (bufoff) + ldsw + _i * 8192), 16, 0, 0); } while (0)
; #define PG8_LDA(dst, b, h) do { _Pragma("unroll") for (int m = 0; m < 4; ++m) _Pragma("unroll") for (int k = 0; k < 2; ++k) dst[m][k] = *(const PG8_LAS bf16x8*)(lds + PG8_SA(b, h) + aoff + m * 2048 + k * 1024); } while (0)
; #define PG8_WAIT_V(n) asm volatile("s_waitcnt vmcnt(" #n ")" ::: "memory")
; #define PG8_WAIT_L(n) asm volatile("s_waitcnt lgkmcnt(" #n ")" ::: "memory")
; #define PG8_BAR __builtin_amdgcn_s_barrier()
; #define PG8_SCHED __builtin_amdgcn_sched_barrier(0)
;     __device__ __forceinline__ void operator()(const f32x4 (&acc)[2][2][4][2], const Unit& u, int wr, int wc, int fr, int fq) const {
;         const int row0 = u.pm * BM + wr * 64 + fr, col0 = u.pn * BM + wc * 32 + 8 * fq;
; #pragma unroll
;         for (int ai = 0; ai < 2; ++ai)
; #pragma unroll
;           for (int mh = 0; mh < 2; ++mh) {
;             u32x4 rv[2][2], pw[2][2]; f32x4 p[2];
; #pragma unroll
;             for (int mm = 0; mm < 2; ++mm) { const int rowl = row0 + ai * HALF + (2 * mh + mm) * 16; p[mm] = *(const f32x4*)(ssq_in + (size_t)rowl * 16 + 4 * fq);
; #pragma unroll
;                 for (int bj = 0; bj < 2; ++bj) { const size_t off = (size_t)rowl * DMODEL + col0 + bj * HALF; rv[mm][bj] = *(const u32x4*)(Rin + off); pw[mm][bj] = *(const u32x4*)(PP + off); } }
; #pragma unroll
;             for (int mm = 0; mm < 2; ++mm) { const int m = 2 * mh + mm; const int row = row0 + ai * HALF + m * 16; float part = 0.f;
;                 float sr = (p[mm][0] + p[mm][1]) + (p[mm][2] + p[mm][3]); sr += __shfl_xor(sr, 16); sr += __shfl_xor(sr, 32); const float r = __builtin_amdgcn_rsqf(sr * (1.0f / DMODEL) + RMS_EPS);
; template <class Epi, class Sched, bool ALIGN_EPI = false, bool SP2 = false>
; __device__ __forceinline__ void gemm_phase(PG8_LAS unsigned char* lds, const Gemm g, const Sched& S, const Epi& E) {
;     ...
;             PG8_STAGE(PG8_SB(1, 0), b3, voffB); PG8_STAGE(PG8_SB(1, 1), b3 + hstep, voffB); PG8_STAGE(PG8_SA(1, 0), a3, voffA); PG8_SCHED; PG8_LDA(At, 1, 1);
;             PG8_WAIT_V(8); PG8_WAIT_L(0); PG8_BAR; PG8_MMA(1, 0, At, B0); PG8_MMA(1, 1, At, B1); PG8_BAR; PG8_SCHED;
	ds_read_b128 v[180:183], v175 offset:49152
	ds_read_b128 v[184:187], v175 offset:50176
	ds_read_b128 v[188:191], v175 offset:51200
	ds_read_b128 v[204:207], v175 offset:52224
	ds_read_b128 v[208:211], v175 offset:53248
	ds_read_b128 v[212:215], v175 offset:54272
	ds_read_b128 v[216:219], v175 offset:55296
	ds_read_b128 v[220:223], v175 offset:56320
	s_add_u32 s100, s28, 0x80
	s_addc_u32 s101, s29, 0
	s_add_u32 s28, s28, 0x40080
	s_addc_u32 s29, s29, 0
	s_add_u32 s98, s98, 0x80
	s_addc_u32 s99, s99, 0
	s_add_i32 m0, s30, s35
	s_nop 0
	global_load_lds_dwordx4 v150, s[100:101]
	s_add_i32 m0, m0, 0x2000
	s_nop 0
	global_load_lds_dwordx4 v154, s[100:101]
	s_add_i32 m0, s31, s35
	s_nop 0
	global_load_lds_dwordx4 v150, s[28:29]
	s_add_i32 m0, m0, 0x2000
	s_nop 0
	global_load_lds_dwordx4 v154, s[28:29]
	s_mov_b32 m0, s52
	s_nop 0
	global_load_lds_dwordx4 v148, s[98:99]
	s_mov_b32 m0, s53
	s_nop 0
	global_load_lds_dwordx4 v152, s[98:99]
	s_waitcnt vmcnt(8)
	s_waitcnt lgkmcnt(0)
	s_setprio 1
	s_barrier
	v_mfma_f32_16x16x32_bf16 v[60:63], v[132:135], v[180:183], v[60:63]
	v_mfma_f32_16x16x32_bf16 v[56:59], v[140:143], v[180:183], v[56:59]
	v_mfma_f32_16x16x32_bf16 v[44:47], v[132:135], v[188:191], v[44:47]
	v_mfma_f32_16x16x32_bf16 v[40:43], v[140:143], v[188:191], v[40:43]
	v_mfma_f32_16x16x32_bf16 v[28:31], v[132:135], v[208:211], v[28:31]
	v_mfma_f32_16x16x32_bf16 v[24:27], v[140:143], v[208:211], v[24:27]
	v_mfma_f32_16x16x32_bf16 v[12:15], v[132:135], v[216:219], v[12:15]
	v_mfma_f32_16x16x32_bf16 v[8:11], v[140:143], v[216:219], v[8:11]
	v_mfma_f32_16x16x32_bf16 v[60:63], v[136:139], v[184:187], v[60:63]
	v_mfma_f32_16x16x32_bf16 v[56:59], v[144:147], v[184:187], v[56:59]
	v_mfma_f32_16x16x32_bf16 v[44:47], v[136:139], v[204:207], v[44:47]
	v_mfma_f32_16x16x32_bf16 v[40:43], v[144:147], v[204:207], v[40:43]
	v_mfma_f32_16x16x32_bf16 v[28:31], v[136:139], v[212:215], v[28:31]
	v_mfma_f32_16x16x32_bf16 v[24:27], v[144:147], v[212:215], v[24:27]
	v_mfma_f32_16x16x32_bf16 v[12:15], v[136:139], v[220:223], v[12:15]
	v_mfma_f32_16x16x32_bf16 v[8:11], v[144:147], v[220:223], v[8:11]
	v_mfma_f32_16x16x32_bf16 v[52:55], v[160:163], v[180:183], v[52:55]
	v_mfma_f32_16x16x32_bf16 v[48:51], v[168:171], v[180:183], v[48:51]
	v_mfma_f32_16x16x32_bf16 v[36:39], v[160:163], v[188:191], v[36:39]
	v_mfma_f32_16x16x32_bf16 v[32:35], v[168:171], v[188:191], v[32:35]
	v_mfma_f32_16x16x32_bf16 v[20:23], v[160:163], v[208:211], v[20:23]
	v_mfma_f32_16x16x32_bf16 v[16:19], v[168:171], v[208:211], v[16:19]
	v_mfma_f32_16x16x32_bf16 v[4:7], v[160:163], v[216:219], v[4:7]
	v_mfma_f32_16x16x32_bf16 v[0:3], v[168:171], v[216:219], v[0:3]
	v_mfma_f32_16x16x32_bf16 v[52:55], v[164:167], v[184:187], v[52:55]
	v_mfma_f32_16x16x32_bf16 v[48:51], v[176:179], v[184:187], v[48:51]
	v_mfma_f32_16x16x32_bf16 v[36:39], v[164:167], v[204:207], v[36:39]
	v_mfma_f32_16x16x32_bf16 v[32:35], v[176:179], v[204:207], v[32:35]
	v_mfma_f32_16x16x32_bf16 v[20:23], v[164:167], v[212:215], v[20:23]
	v_mfma_f32_16x16x32_bf16 v[16:19], v[176:179], v[212:215], v[16:19]
	v_mfma_f32_16x16x32_bf16 v[4:7], v[164:167], v[220:223], v[4:7]
	v_mfma_f32_16x16x32_bf16 v[0:3], v[176:179], v[220:223], v[0:3]
	s_setprio 0
	s_barrier
	s_add_i32 s59, s59, 2
	s_add_u32 vcc_lo, vcc_lo, 0x100
	s_addc_u32 vcc_hi, vcc_hi, 0
	s_cmp_gt_u32 s59, 13
	s_cbranch_scc0 .LBB0_1133
	s_and_b64 vcc, exec, s[14:15]
	s_cbranch_vccz .LBB0_1136
	s_barrier
.LBB0_1136:
	v_readfirstlane_b32 s19, v192
	v_and_b32_e32 v247, 15, v192
	s_bfe_u32 s17, s19, 0x20006
	s_lshr_b32 s19, s19, 8
	s_lshl_b32 s19, s19, 6
	s_lshl_b32 s27, s40, 8
	s_add_i32 s19, s19, s27
	v_add_u32_e32 v247, s19, v247
	v_bfe_u32 v252, v192, 4, 2
	s_lshl_b32 s27, s26, 8
	s_lshl_b32 s28, s17, 5
	s_or_b32 s27, s27, s28
	v_lshl_or_b32 v253, v252, 3, s27
	v_lshlrev_b32_e32 v172, 11, v247
	v_lshl_add_u32 v172, v253, 1, v172
	v_lshlrev_b32_e32 v194, 6, v247
	v_lshl_add_u32 v173, v252, 4, v194
	s_lshl_b32 s28, s26, 4
	s_lshl_b32 s29, s17, 2
	s_add_i32 s28, s28, s29
	v_add_u32_e32 v194, s28, v194
	v_cmp_eq_u32_e32 vcc, 0, v252
	v_xor_b32_e32 v236, 16, v241
	v_xor_b32_e32 v237, 32, v241
	v_lshlrev_b32_e32 v236, 2, v236
	v_lshlrev_b32_e32 v237, 2, v237
	v_mov_b32_e32 v250, v172
	v_mov_b32_e32 v251, v173
	global_load_dwordx4 v[128:131], v251, s[10:11]
	global_load_dwordx4 v[132:135], v250, s[6:7]
	global_load_dwordx4 v[140:143], v250, s[2:3]
	global_load_dwordx4 v[136:139], v250, s[6:7] offset:256
	global_load_dwordx4 v[144:147], v250, s[2:3] offset:256
	v_add_u32_e32 v250, 0x8000, v172
	v_add_u32_e32 v251, 0x400, v173
	global_load_dwordx4 v[160:163], v251, s[10:11]
	global_load_dwordx4 v[164:167], v250, s[6:7]
	global_load_dwordx4 v[176:179], v250, s[2:3]
	global_load_dwordx4 v[168:171], v250, s[6:7] offset:256
	global_load_dwordx4 v[180:183], v250, s[2:3] offset:256
	v_add_u32_e32 v250, 0x10000, v172
	v_add_u32_e32 v251, 0x800, v173
	global_load_dwordx4 v[184:187], v251, s[10:11]
	global_load_dwordx4 v[188:191], v250, s[6:7]
	global_load_dwordx4 v[208:211], v250, s[2:3]
	global_load_dwordx4 v[204:207], v250, s[6:7] offset:256
	global_load_dwordx4 v[212:215], v250, s[2:3] offset:256
	s_waitcnt vmcnt(10)
	v_add_f32_e32 v247, v128, v129
	v_add_f32_e32 v252, v130, v131
	v_add_f32_e32 v247, v247, v252
	ds_bpermute_b32 v252, v236, v247
	s_waitcnt lgkmcnt(0)
	v_add_f32_e32 v247, v247, v252
	ds_bpermute_b32 v252, v237, v247
	s_waitcnt lgkmcnt(0)
; __device__ __forceinline__ u32x4 pack8(const f32x4 v0, const f32x4 v1) { u32x4 w; w.x = cvt_pk_bf16(v0[0], v0[1]); w.y = cvt_pk_bf16(v0[2], v0[3]); w.z = cvt_pk_bf16(v1[0], v1[1]); w.w = cvt_pk_bf16(v1[2], v1[3]); return w; }
; __device__ __forceinline__ float sumsq8(const f32x4 a, const f32x4 b) { return ((a[0] * a[0] + a[1] * a[1]) + (a[2] * a[2] + a[3] * a[3])) + ((b[0] * b[0] + b[1] * b[1]) + (b[2] * b[2] + b[3] * b[3])); }
; __device__ __forceinline__ void unpack8(const u32x4 w, f32x4& a, f32x4& b) { a = (f32x4){bf_lo(w.x), bf_hi(w.x), bf_lo(w.y), bf_hi(w.y)}; b = (f32x4){bf_lo(w.z), bf_hi(w.z), bf_lo(w.w), bf_hi(w.w)}; }
;     __device__ __forceinline__ void operator()(const f32x4 (&acc)[2][2][4][2], const Unit& u, int wr, int wc, int fr, int fq) const {
;     ...
;             for (int mm = 0; mm < 2; ++mm) { const int rowl = row0 + ai * HALF + (2 * mh + mm) * 16; p[mm] = *(const f32x4*)(ssq_in + (size_t)rowl * 16 + 4 * fq);
; #pragma unroll
;                 for (int bj = 0; bj < 2; ++bj) { const size_t off = (size_t)rowl * DMODEL + col0 + bj * HALF; rv[mm][bj] = *(const u32x4*)(Rin + off); pw[mm][bj] = *(const u32x4*)(PP + off); } }
; #pragma unroll
;             for (int mm = 0; mm < 2; ++mm) { const int m = 2 * mh + mm; const int row = row0 + ai * HALF + m * 16; float part = 0.f;
;                 float sr = (p[mm][0] + p[mm][1]) + (p[mm][2] + p[mm][3]); sr += __shfl_xor(sr, 16); sr += __shfl_xor(sr, 32); const float r = __builtin_amdgcn_rsqf(sr * (1.0f / DMODEL) + RMS_EPS);
; #pragma unroll
;                 for (int bj = 0; bj < 2; ++bj) { f32x4 r0, r1, p0, p1; unpack8(rv[mm][bj], r0, r1); unpack8(pw[mm][bj], p0, p1);
;                     f32x4 g0 = acc[ai][bj][m][0] * r, g1 = acc[ai][bj][m][1] * r;
; #pragma unroll
;                     for (int e = 0; e < 4; ++e) { g0[e] = __builtin_amdgcn_rcpf(1.f + __builtin_amdgcn_exp2f(-1.4426950408889634f * g0[e])); g1[e] = __builtin_amdgcn_rcpf(1.f + __builtin_amdgcn_exp2f(-1.4426950408889634f * g1[e])); }
;                     const f32x4 h0 = r0 + g0 * p0, h1 = r1 + g1 * p1; part += sumsq8(h0, h1);
;                     *(u32x4*)(XBo + (size_t)row * DMODEL + col0 + bj * HALF) = pack8(h0, h1); }
;                 part += __shfl_xor(part, 16); part += __shfl_xor(part, 32);
;                 if (fq == 0) ssq_out[(size_t)row * 16 + u.pn * 4 + wc] = part; }
	v_add_f32_e32 v247, v247, v252
	v_fmamk_f32 v247, v247, 0x3a800000, v193
	v_rsq_f32_e32 v247, v247
	s_nop 0
	v_mul_f32_e32 v253, 0xbfb8aa3b, v247
	v_mul_f32_e32 v124, v124, v253
	v_mul_f32_e32 v125, v125, v253
	v_mul_f32_e32 v126, v126, v253
	v_mul_f32_e32 v127, v127, v253
	v_exp_f32_e32 v124, v124
	v_exp_f32_e32 v125, v125
	v_exp_f32_e32 v126, v126
	v_exp_f32_e32 v127, v127
	v_add_f32_e32 v124, 1.0, v124
	v_add_f32_e32 v125, 1.0, v125
	v_add_f32_e32 v126, 1.0, v126
	v_add_f32_e32 v127, 1.0, v127
	v_rcp_f32_e32 v124, v124
	v_rcp_f32_e32 v125, v125
	v_rcp_f32_e32 v126, v126
	v_rcp_f32_e32 v127, v127
	v_lshlrev_b32_e32 v224, 16, v132
	v_and_b32_e32 v225, 0xffff0000, v132
	v_lshlrev_b32_e32 v226, 16, v133
	v_and_b32_e32 v227, 0xffff0000, v133
	v_lshlrev_b32_e32 v228, 16, v140
	v_and_b32_e32 v229, 0xffff0000, v140
	v_lshlrev_b32_e32 v230, 16, v141
	v_and_b32_e32 v231, 0xffff0000, v141
	v_fma_f32 v124, v124, v228, v224
	v_fma_f32 v125, v125, v229, v225
	v_fma_f32 v126, v126, v230, v226
	v_fma_f32 v127, v127, v231, v227
	v_mul_f32_e32 v232, v125, v125
	v_mul_f32_e32 v233, v127, v127
	v_fmac_f32_e32 v232, v124, v124
	v_fmac_f32_e32 v233, v126, v126
	v_add_f32_e32 v234, v232, v233
	v_mul_f32_e32 v120, v120, v253
	v_mul_f32_e32 v121, v121, v253
	v_mul_f32_e32 v122, v122, v253
	v_mul_f32_e32 v123, v123, v253
	v_exp_f32_e32 v120, v120
	v_exp_f32_e32 v121, v121
	v_exp_f32_e32 v122, v122
	v_exp_f32_e32 v123, v123
	v_add_f32_e32 v120, 1.0, v120
	v_add_f32_e32 v121, 1.0, v121
	v_add_f32_e32 v122, 1.0, v122
	v_add_f32_e32 v123, 1.0, v123
	v_rcp_f32_e32 v120, v120
	v_rcp_f32_e32 v121, v121
	v_rcp_f32_e32 v122, v122
	v_rcp_f32_e32 v123, v123
	v_lshlrev_b32_e32 v224, 16, v134
	v_and_b32_e32 v225, 0xffff0000, v134
	v_lshlrev_b32_e32 v226, 16, v135
	v_and_b32_e32 v227, 0xffff0000, v135
	v_lshlrev_b32_e32 v228, 16, v142
	v_and_b32_e32 v229, 0xffff0000, v142
	v_lshlrev_b32_e32 v230, 16, v143
	v_and_b32_e32 v231, 0xffff0000, v143
	v_fma_f32 v120, v120, v228, v224
	v_fma_f32 v121, v121, v229, v225
	v_fma_f32 v122, v122, v230, v226
	v_fma_f32 v123, v123, v231, v227
	v_mul_f32_e32 v232, v121, v121
	v_mul_f32_e32 v233, v123, v123
	v_fmac_f32_e32 v232, v120, v120
	v_fmac_f32_e32 v233, v122, v122
	v_add_f32_e32 v235, v232, v233
	v_cvt_pk_bf16_f32 v124, v124, v125
	v_cvt_pk_bf16_f32 v125, v126, v127
	v_cvt_pk_bf16_f32 v126, v120, v121
	v_cvt_pk_bf16_f32 v127, v122, v123
	v_mov_b32_e32 v250, v172
	global_store_dwordx4 v250, v[124:127], s[0:1]
	v_mul_f32_e32 v116, v116, v253
	v_mul_f32_e32 v117, v117, v253
	v_mul_f32_e32 v118, v118, v253
	v_mul_f32_e32 v119, v119, v253
	v_exp_f32_e32 v116, v116
	v_exp_f32_e32 v117, v117
	v_exp_f32_e32 v118, v118
	v_exp_f32_e32 v119, v119
	v_add_f32_e32 v116, 1.0, v116
	v_add_f32_e32 v117, 1.0, v117
	v_add_f32_e32 v118, 1.0, v118
	v_add_f32_e32 v119, 1.0, v119
	v_rcp_f32_e32 v116, v116
	v_rcp_f32_e32 v117, v117
	v_rcp_f32_e32 v118, v118
	v_rcp_f32_e32 v119, v119
	v_lshlrev_b32_e32 v224, 16, v136
	v_and_b32_e32 v225, 0xffff0000, v136
	v_lshlrev_b32_e32 v226, 16, v137
	v_and_b32_e32 v227, 0xffff0000, v137
	v_lshlrev_b32_e32 v228, 16, v144
	v_and_b32_e32 v229, 0xffff0000, v144
	v_lshlrev_b32_e32 v230, 16, v145
	v_and_b32_e32 v231, 0xffff0000, v145
	v_fma_f32 v116, v116, v228, v224
	v_fma_f32 v117, v117, v229, v225
	v_fma_f32 v118, v118, v230, v226
	v_fma_f32 v119, v119, v231, v227
	v_mul_f32_e32 v232, v117, v117
	v_mul_f32_e32 v233, v119, v119
	v_fmac_f32_e32 v232, v116, v116
	v_fmac_f32_e32 v233, v118, v118
	v_add_f32_e32 v248, v232, v233
	v_mul_f32_e32 v112, v112, v253
	v_mul_f32_e32 v113, v113, v253
	v_mul_f32_e32 v114, v114, v253
	v_mul_f32_e32 v115, v115, v253
	v_exp_f32_e32 v112, v112
	v_exp_f32_e32 v113, v113
	v_exp_f32_e32 v114, v114
	v_exp_f32_e32 v115, v115
	v_add_f32_e32 v112, 1.0, v112
	v_add_f32_e32 v113, 1.0, v113
	v_add_f32_e32 v114, 1.0, v114
	v_add_f32_e32 v115, 1.0, v115
	v_rcp_f32_e32 v112, v112
	v_rcp_f32_e32 v113, v113
	v_rcp_f32_e32 v114, v114
	v_rcp_f32_e32 v115, v115
	v_lshlrev_b32_e32 v224, 16, v138
	v_and_b32_e32 v225, 0xffff0000, v138
	v_lshlrev_b32_e32 v226, 16, v139
	v_and_b32_e32 v227, 0xffff0000, v139
	v_lshlrev_b32_e32 v228, 16, v146
	v_and_b32_e32 v229, 0xffff0000, v146
	v_lshlrev_b32_e32 v230, 16, v147
	v_and_b32_e32 v231, 0xffff0000, v147
	v_fma_f32 v112, v112, v228, v224
	v_fma_f32 v113, v113, v229, v225
	v_fma_f32 v114, v114, v230, v226
	v_fma_f32 v115, v115, v231, v227
	v_mul_f32_e32 v232, v113, v113
	v_mul_f32_e32 v233, v115, v115
	v_fmac_f32_e32 v232, v112, v112
	v_fmac_f32_e32 v233, v114, v114
	v_add_f32_e32 v249, v232, v233
	v_cvt_pk_bf16_f32 v116, v116, v117
	v_cvt_pk_bf16_f32 v117, v118, v119
	v_cvt_pk_bf16_f32 v118, v112, v113
	v_cvt_pk_bf16_f32 v119, v114, v115
	global_store_dwordx4 v250, v[116:119], s[0:1] offset:256
	v_add_f32_e32 v234, v234, v235
	v_add_f32_e32 v248, v248, v249
	v_add_f32_e32 v247, v234, v248
	ds_bpermute_b32 v252, v236, v247
	v_mov_b32_e32 v251, v194
	s_waitcnt lgkmcnt(0)
	v_add_f32_e32 v247, v247, v252
	ds_bpermute_b32 v252, v237, v247
	s_waitcnt lgkmcnt(0)
	v_add_f32_e32 v247, v247, v252
	s_and_saveexec_b64 s[28:29], vcc
	global_store_dword v251, v247, s[12:13]
	s_or_b64 exec, exec, s[28:29]
	v_add_u32_e32 v250, 0x18000, v172
	v_add_u32_e32 v251, 0xc00, v173
	global_load_dwordx4 v[128:131], v251, s[10:11]
	global_load_dwordx4 v[132:135], v250, s[6:7]
	global_load_dwordx4 v[140:143], v250, s[2:3]
	global_load_dwordx4 v[136:139], v250, s[6:7] offset:256
	global_load_dwordx4 v[144:147], v250, s[2:3] offset:256
	v_add_u32_e32 v250, 0x40000, v172
	v_add_u32_e32 v251, 0x2000, v173
	global_load_dwordx4 v[124:127], v251, s[10:11]
	global_load_dwordx4 v[120:123], v250, s[6:7]
	global_load_dwordx4 v[112:115], v250, s[2:3]
	global_load_dwordx4 v[116:119], v250, s[6:7] offset:256
	global_load_dwordx4 v[216:219], v250, s[2:3] offset:256
	s_waitcnt vmcnt(18)
; __device__ __forceinline__ u32x4 pack8(const f32x4 v0, const f32x4 v1) { u32x4 w; w.x = cvt_pk_bf16(v0[0], v0[1]); w.y = cvt_pk_bf16(v0[2], v0[3]); w.z = cvt_pk_bf16(v1[0], v1[1]); w.w = cvt_pk_bf16(v1[2], v1[3]); return w; }
; __device__ __forceinline__ float sumsq8(const f32x4 a, const f32x4 b) { return ((a[0] * a[0] + a[1] * a[1]) + (a[2] * a[2] + a[3] * a[3])) + ((b[0] * b[0] + b[1] * b[1]) + (b[2] * b[2] + b[3] * b[3])); }
; __device__ __forceinline__ void unpack8(const u32x4 w, f32x4& a, f32x4& b) { a = (f32x4){bf_lo(w.x), bf_hi(w.x), bf_lo(w.y), bf_hi(w.y)}; b = (f32x4){bf_lo(w.z), bf_hi(w.z), bf_lo(w.w), bf_hi(w.w)}; }
;     __device__ __forceinline__ void operator()(const f32x4 (&acc)[2][2][4][2], const Unit& u, int wr, int wc, int fr, int fq) const {
;     ...
;             for (int mm = 0; mm < 2; ++mm) { const int rowl = row0 + ai * HALF + (2 * mh + mm) * 16; p[mm] = *(const f32x4*)(ssq_in + (size_t)rowl * 16 + 4 * fq);
; #pragma unroll
;                 for (int bj = 0; bj < 2; ++bj) { const size_t off = (size_t)rowl * DMODEL + col0 + bj * HALF; rv[mm][bj] = *(const u32x4*)(Rin + off); pw[mm][bj] = *(const u32x4*)(PP + off); } }
; #pragma unroll
;             for (int mm = 0; mm < 2; ++mm) { const int m = 2 * mh + mm; const int row = row0 + ai * HALF + m * 16; float part = 0.f;
;                 float sr = (p[mm][0] + p[mm][1]) + (p[mm][2] + p[mm][3]); sr += __shfl_xor(sr, 16); sr += __shfl_xor(sr, 32); const float r = __builtin_amdgcn_rsqf(sr * (1.0f / DMODEL) + RMS_EPS);
; #pragma unroll
;                 for (int bj = 0; bj < 2; ++bj) { f32x4 r0, r1, p0, p1; unpack8(rv[mm][bj], r0, r1); unpack8(pw[mm][bj], p0, p1);
;                     f32x4 g0 = acc[ai][bj][m][0] * r, g1 = acc[ai][bj][m][1] * r;
; #pragma unroll
;                     for (int e = 0; e < 4; ++e) { g0[e] = __builtin_amdgcn_rcpf(1.f + __builtin_amdgcn_exp2f(-1.4426950408889634f * g0[e])); g1[e] = __builtin_amdgcn_rcpf(1.f + __builtin_amdgcn_exp2f(-1.4426950408889634f * g1[e])); }
;                     const f32x4 h0 = r0 + g0 * p0, h1 = r1 + g1 * p1; part += sumsq8(h0, h1);
;                     *(u32x4*)(XBo + (size_t)row * DMODEL + col0 + bj * HALF) = pack8(h0, h1); }
;                 part += __shfl_xor(part, 16); part += __shfl_xor(part, 32);
;                 if (fq == 0) ssq_out[(size_t)row * 16 + u.pn * 4 + wc] = part; }
	v_add_f32_e32 v247, v160, v161
	v_add_f32_e32 v252, v162, v163
	v_add_f32_e32 v247, v247, v252
	ds_bpermute_b32 v252, v236, v247
	s_waitcnt lgkmcnt(0)
	v_add_f32_e32 v247, v247, v252
	ds_bpermute_b32 v252, v237, v247
	s_waitcnt lgkmcnt(0)
	v_add_f32_e32 v247, v247, v252
	v_fmamk_f32 v247, v247, 0x3a800000, v193
	v_rsq_f32_e32 v247, v247
	s_nop 0
	v_mul_f32_e32 v253, 0xbfb8aa3b, v247
	v_mul_f32_e32 v108, v108, v253
	v_mul_f32_e32 v109, v109, v253
	v_mul_f32_e32 v110, v110, v253
	v_mul_f32_e32 v111, v111, v253
	v_exp_f32_e32 v108, v108
	v_exp_f32_e32 v109, v109
	v_exp_f32_e32 v110, v110
	v_exp_f32_e32 v111, v111
	v_add_f32_e32 v108, 1.0, v108
	v_add_f32_e32 v109, 1.0, v109
	v_add_f32_e32 v110, 1.0, v110
	v_add_f32_e32 v111, 1.0, v111
	v_rcp_f32_e32 v108, v108
	v_rcp_f32_e32 v109, v109
	v_rcp_f32_e32 v110, v110
	v_rcp_f32_e32 v111, v111
	v_lshlrev_b32_e32 v224, 16, v164
	v_and_b32_e32 v225, 0xffff0000, v164
	v_lshlrev_b32_e32 v226, 16, v165
	v_and_b32_e32 v227, 0xffff0000, v165
	v_lshlrev_b32_e32 v228, 16, v176
	v_and_b32_e32 v229, 0xffff0000, v176
	v_lshlrev_b32_e32 v230, 16, v177
	v_and_b32_e32 v231, 0xffff0000, v177
	v_fma_f32 v108, v108, v228, v224
	v_fma_f32 v109, v109, v229, v225
	v_fma_f32 v110, v110, v230, v226
	v_fma_f32 v111, v111, v231, v227
	v_mul_f32_e32 v232, v109, v109
	v_mul_f32_e32 v233, v111, v111
	v_fmac_f32_e32 v232, v108, v108
	v_fmac_f32_e32 v233, v110, v110
	v_add_f32_e32 v234, v232, v233
	v_mul_f32_e32 v104, v104, v253
	v_mul_f32_e32 v105, v105, v253
	v_mul_f32_e32 v106, v106, v253
	v_mul_f32_e32 v107, v107, v253
	v_exp_f32_e32 v104, v104
	v_exp_f32_e32 v105, v105
	v_exp_f32_e32 v106, v106
	v_exp_f32_e32 v107, v107
	v_add_f32_e32 v104, 1.0, v104
	v_add_f32_e32 v105, 1.0, v105
	v_add_f32_e32 v106, 1.0, v106
	v_add_f32_e32 v107, 1.0, v107
	v_rcp_f32_e32 v104, v104
	v_rcp_f32_e32 v105, v105
	v_rcp_f32_e32 v106, v106
	v_rcp_f32_e32 v107, v107
	v_lshlrev_b32_e32 v224, 16, v166
	v_and_b32_e32 v225, 0xffff0000, v166
	v_lshlrev_b32_e32 v226, 16, v167
	v_and_b32_e32 v227, 0xffff0000, v167
	v_lshlrev_b32_e32 v228, 16, v178
	v_and_b32_e32 v229, 0xffff0000, v178
	v_lshlrev_b32_e32 v230, 16, v179
	v_and_b32_e32 v231, 0xffff0000, v179
	v_fma_f32 v104, v104, v228, v224
	v_fma_f32 v105, v105, v229, v225
	v_fma_f32 v106, v106, v230, v226
	v_fma_f32 v107, v107, v231, v227
	v_mul_f32_e32 v232, v105, v105
	v_mul_f32_e32 v233, v107, v107
	v_fmac_f32_e32 v232, v104, v104
	v_fmac_f32_e32 v233, v106, v106
	v_add_f32_e32 v235, v232, v233
	v_cvt_pk_bf16_f32 v108, v108, v109
	v_cvt_pk_bf16_f32 v109, v110, v111
	v_cvt_pk_bf16_f32 v110, v104, v105
	v_cvt_pk_bf16_f32 v111, v106, v107
	v_add_u32_e32 v250, 0x8000, v172
	global_store_dwordx4 v250, v[108:111], s[0:1]
	v_mul_f32_e32 v100, v100, v253
	v_mul_f32_e32 v101, v101, v253
	v_mul_f32_e32 v102, v102, v253
	v_mul_f32_e32 v103, v103, v253
	v_exp_f32_e32 v100, v100
	v_exp_f32_e32 v101, v101
	v_exp_f32_e32 v102, v102
	v_exp_f32_e32 v103, v103
	v_add_f32_e32 v100, 1.0, v100
	v_add_f32_e32 v101, 1.0, v101
	v_add_f32_e32 v102, 1.0, v102
	v_add_f32_e32 v103, 1.0, v103
	v_rcp_f32_e32 v100, v100
	v_rcp_f32_e32 v101, v101
	v_rcp_f32_e32 v102, v102
	v_rcp_f32_e32 v103, v103
	v_lshlrev_b32_e32 v224, 16, v168
	v_and_b32_e32 v225, 0xffff0000, v168
	v_lshlrev_b32_e32 v226, 16, v169
	v_and_b32_e32 v227, 0xffff0000, v169
	v_lshlrev_b32_e32 v228, 16, v180
	v_and_b32_e32 v229, 0xffff0000, v180
	v_lshlrev_b32_e32 v230, 16, v181
	v_and_b32_e32 v231, 0xffff0000, v181
	v_fma_f32 v100, v100, v228, v224
	v_fma_f32 v101, v101, v229, v225
	v_fma_f32 v102, v102, v230, v226
	v_fma_f32 v103, v103, v231, v227
	v_mul_f32_e32 v232, v101, v101
	v_mul_f32_e32 v233, v103, v103
	v_fmac_f32_e32 v232, v100, v100
	v_fmac_f32_e32 v233, v102, v102
	v_add_f32_e32 v248, v232, v233
	v_mul_f32_e32 v96, v96, v253
	v_mul_f32_e32 v97, v97, v253
	v_mul_f32_e32 v98, v98, v253
	v_mul_f32_e32 v99, v99, v253
	v_exp_f32_e32 v96, v96
	v_exp_f32_e32 v97, v97
	v_exp_f32_e32 v98, v98
	v_exp_f32_e32 v99, v99
	v_add_f32_e32 v96, 1.0, v96
	v_add_f32_e32 v97, 1.0, v97
	v_add_f32_e32 v98, 1.0, v98
	v_add_f32_e32 v99, 1.0, v99
	v_rcp_f32_e32 v96, v96
	v_rcp_f32_e32 v97, v97
	v_rcp_f32_e32 v98, v98
	v_rcp_f32_e32 v99, v99
	v_lshlrev_b32_e32 v224, 16, v170
	v_and_b32_e32 v225, 0xffff0000, v170
	v_lshlrev_b32_e32 v226, 16, v171
	v_and_b32_e32 v227, 0xffff0000, v171
	v_lshlrev_b32_e32 v228, 16, v182
	v_and_b32_e32 v229, 0xffff0000, v182
	v_lshlrev_b32_e32 v230, 16, v183
	v_and_b32_e32 v231, 0xffff0000, v183
	v_fma_f32 v96, v96, v228, v224
	v_fma_f32 v97, v97, v229, v225
	v_fma_f32 v98, v98, v230, v226
	v_fma_f32 v99, v99, v231, v227
	v_mul_f32_e32 v232, v97, v97
	v_mul_f32_e32 v233, v99, v99
	v_fmac_f32_e32 v232, v96, v96
	v_fmac_f32_e32 v233, v98, v98
	v_add_f32_e32 v249, v232, v233
	v_cvt_pk_bf16_f32 v100, v100, v101
	v_cvt_pk_bf16_f32 v101, v102, v103
	v_cvt_pk_bf16_f32 v102, v96, v97
	v_cvt_pk_bf16_f32 v103, v98, v99
	global_store_dwordx4 v250, v[100:103], s[0:1] offset:256
	v_add_f32_e32 v234, v234, v235
	v_add_f32_e32 v248, v248, v249
	v_add_f32_e32 v247, v234, v248
	ds_bpermute_b32 v252, v236, v247
	v_add_u32_e32 v251, 0x400, v194
	s_waitcnt lgkmcnt(0)
	v_add_f32_e32 v247, v247, v252
	ds_bpermute_b32 v252, v237, v247
	s_waitcnt lgkmcnt(0)
	v_add_f32_e32 v247, v247, v252
	s_and_saveexec_b64 s[28:29], vcc
	global_store_dword v251, v247, s[12:13]
	s_or_b64 exec, exec, s[28:29]
	v_add_u32_e32 v250, 0x48000, v172
	v_add_u32_e32 v251, 0x2400, v173
	global_load_dwordx4 v[160:163], v251, s[10:11]
	global_load_dwordx4 v[164:167], v250, s[6:7]
	global_load_dwordx4 v[176:179], v250, s[2:3]
	global_load_dwordx4 v[168:171], v250, s[6:7] offset:256
	global_load_dwordx4 v[180:183], v250, s[2:3] offset:256
	v_add_u32_e32 v250, 0x50000, v172
	v_add_u32_e32 v251, 0x2800, v173
	global_load_dwordx4 v[108:111], v251, s[10:11]
	global_load_dwordx4 v[104:107], v250, s[6:7]
	global_load_dwordx4 v[96:99], v250, s[2:3]
	global_load_dwordx4 v[100:103], v250, s[6:7] offset:256
	global_load_dwordx4 v[220:223], v250, s[2:3] offset:256
	s_waitcnt vmcnt(26)
; __device__ __forceinline__ u32x4 pack8(const f32x4 v0, const f32x4 v1) { u32x4 w; w.x = cvt_pk_bf16(v0[0], v0[1]); w.y = cvt_pk_bf16(v0[2], v0[3]); w.z = cvt_pk_bf16(v1[0], v1[1]); w.w = cvt_pk_bf16(v1[2], v1[3]); return w; }
; __device__ __forceinline__ float sumsq8(const f32x4 a, const f32x4 b) { return ((a[0] * a[0] + a[1] * a[1]) + (a[2] * a[2] + a[3] * a[3])) + ((b[0] * b[0] + b[1] * b[1]) + (b[2] * b[2] + b[3] * b[3])); }
; __device__ __forceinline__ void unpack8(const u32x4 w, f32x4& a, f32x4& b) { a = (f32x4){bf_lo(w.x), bf_hi(w.x), bf_lo(w.y), bf_hi(w.y)}; b = (f32x4){bf_lo(w.z), bf_hi(w.z), bf_lo(w.w), bf_hi(w.w)}; }
;     __device__ __forceinline__ void operator()(const f32x4 (&acc)[2][2][4][2], const Unit& u, int wr, int wc, int fr, int fq) const {
;     ...
;             for (int mm = 0; mm < 2; ++mm) { const int rowl = row0 + ai * HALF + (2 * mh + mm) * 16; p[mm] = *(const f32x4*)(ssq_in + (size_t)rowl * 16 + 4 * fq);
; #pragma unroll
;                 for (int bj = 0; bj < 2; ++bj) { const size_t off = (size_t)rowl * DMODEL + col0 + bj * HALF; rv[mm][bj] = *(const u32x4*)(Rin + off); pw[mm][bj] = *(const u32x4*)(PP + off); } }
; #pragma unroll
;             for (int mm = 0; mm < 2; ++mm) { const int m = 2 * mh + mm; const int row = row0 + ai * HALF + m * 16; float part = 0.f;
;                 float sr = (p[mm][0] + p[mm][1]) + (p[mm][2] + p[mm][3]); sr += __shfl_xor(sr, 16); sr += __shfl_xor(sr, 32); const float r = __builtin_amdgcn_rsqf(sr * (1.0f / DMODEL) + RMS_EPS);
; #pragma unroll
;                 for (int bj = 0; bj < 2; ++bj) { f32x4 r0, r1, p0, p1; unpack8(rv[mm][bj], r0, r1); unpack8(pw[mm][bj], p0, p1);
;                     f32x4 g0 = acc[ai][bj][m][0] * r, g1 = acc[ai][bj][m][1] * r;
; #pragma unroll
;                     for (int e = 0; e < 4; ++e) { g0[e] = __builtin_amdgcn_rcpf(1.f + __builtin_amdgcn_exp2f(-1.4426950408889634f * g0[e])); g1[e] = __builtin_amdgcn_rcpf(1.f + __builtin_amdgcn_exp2f(-1.4426950408889634f * g1[e])); }
;                     const f32x4 h0 = r0 + g0 * p0, h1 = r1 + g1 * p1; part += sumsq8(h0, h1);
;                     *(u32x4*)(XBo + (size_t)row * DMODEL + col0 + bj * HALF) = pack8(h0, h1); }
;                 part += __shfl_xor(part, 16); part += __shfl_xor(part, 32);
;                 if (fq == 0) ssq_out[(size_t)row * 16 + u.pn * 4 + wc] = part; }
	v_add_f32_e32 v247, v184, v185
	v_add_f32_e32 v252, v186, v187
	v_add_f32_e32 v247, v247, v252
	ds_bpermute_b32 v252, v236, v247
	s_waitcnt lgkmcnt(0)
	v_add_f32_e32 v247, v247, v252
	ds_bpermute_b32 v252, v237, v247
	s_waitcnt lgkmcnt(0)
	v_add_f32_e32 v247, v247, v252
	v_fmamk_f32 v247, v247, 0x3a800000, v193
	v_rsq_f32_e32 v247, v247
	s_nop 0
	v_mul_f32_e32 v253, 0xbfb8aa3b, v247
	v_mul_f32_e32 v92, v92, v253
	v_mul_f32_e32 v93, v93, v253
	v_mul_f32_e32 v94, v94, v253
	v_mul_f32_e32 v95, v95, v253
	v_exp_f32_e32 v92, v92
	v_exp_f32_e32 v93, v93
	v_exp_f32_e32 v94, v94
	v_exp_f32_e32 v95, v95
	v_add_f32_e32 v92, 1.0, v92
	v_add_f32_e32 v93, 1.0, v93
	v_add_f32_e32 v94, 1.0, v94
	v_add_f32_e32 v95, 1.0, v95
	v_rcp_f32_e32 v92, v92
	v_rcp_f32_e32 v93, v93
	v_rcp_f32_e32 v94, v94
	v_rcp_f32_e32 v95, v95
	v_lshlrev_b32_e32 v224, 16, v188
	v_and_b32_e32 v225, 0xffff0000, v188
	v_lshlrev_b32_e32 v226, 16, v189
	v_and_b32_e32 v227, 0xffff0000, v189
	v_lshlrev_b32_e32 v228, 16, v208
	v_and_b32_e32 v229, 0xffff0000, v208
	v_lshlrev_b32_e32 v230, 16, v209
	v_and_b32_e32 v231, 0xffff0000, v209
	v_fma_f32 v92, v92, v228, v224
	v_fma_f32 v93, v93, v229, v225
	v_fma_f32 v94, v94, v230, v226
	v_fma_f32 v95, v95, v231, v227
	v_mul_f32_e32 v232, v93, v93
	v_mul_f32_e32 v233, v95, v95
	v_fmac_f32_e32 v232, v92, v92
	v_fmac_f32_e32 v233, v94, v94
	v_add_f32_e32 v234, v232, v233
	v_mul_f32_e32 v88, v88, v253
	v_mul_f32_e32 v89, v89, v253
	v_mul_f32_e32 v90, v90, v253
	v_mul_f32_e32 v91, v91, v253
	v_exp_f32_e32 v88, v88
	v_exp_f32_e32 v89, v89
	v_exp_f32_e32 v90, v90
	v_exp_f32_e32 v91, v91
	v_add_f32_e32 v88, 1.0, v88
	v_add_f32_e32 v89, 1.0, v89
	v_add_f32_e32 v90, 1.0, v90
	v_add_f32_e32 v91, 1.0, v91
	v_rcp_f32_e32 v88, v88
	v_rcp_f32_e32 v89, v89
	v_rcp_f32_e32 v90, v90
	v_rcp_f32_e32 v91, v91
	v_lshlrev_b32_e32 v224, 16, v190
	v_and_b32_e32 v225, 0xffff0000, v190
	v_lshlrev_b32_e32 v226, 16, v191
	v_and_b32_e32 v227, 0xffff0000, v191
	v_lshlrev_b32_e32 v228, 16, v210
	v_and_b32_e32 v229, 0xffff0000, v210
	v_lshlrev_b32_e32 v230, 16, v211
	v_and_b32_e32 v231, 0xffff0000, v211
	v_fma_f32 v88, v88, v228, v224
	v_fma_f32 v89, v89, v229, v225
	v_fma_f32 v90, v90, v230, v226
	v_fma_f32 v91, v91, v231, v227
	v_mul_f32_e32 v232, v89, v89
	v_mul_f32_e32 v233, v91, v91
	v_fmac_f32_e32 v232, v88, v88
	v_fmac_f32_e32 v233, v90, v90
	v_add_f32_e32 v235, v232, v233
	v_cvt_pk_bf16_f32 v92, v92, v93
	v_cvt_pk_bf16_f32 v93, v94, v95
	v_cvt_pk_bf16_f32 v94, v88, v89
	v_cvt_pk_bf16_f32 v95, v90, v91
	v_add_u32_e32 v250, 0x10000, v172
	global_store_dwordx4 v250, v[92:95], s[0:1]
	v_mul_f32_e32 v84, v84, v253
	v_mul_f32_e32 v85, v85, v253
	v_mul_f32_e32 v86, v86, v253
	v_mul_f32_e32 v87, v87, v253
	v_exp_f32_e32 v84, v84
	v_exp_f32_e32 v85, v85
	v_exp_f32_e32 v86, v86
	v_exp_f32_e32 v87, v87
	v_add_f32_e32 v84, 1.0, v84
	v_add_f32_e32 v85, 1.0, v85
	v_add_f32_e32 v86, 1.0, v86
	v_add_f32_e32 v87, 1.0, v87
	v_rcp_f32_e32 v84, v84
	v_rcp_f32_e32 v85, v85
	v_rcp_f32_e32 v86, v86
	v_rcp_f32_e32 v87, v87
	v_lshlrev_b32_e32 v224, 16, v204
	v_and_b32_e32 v225, 0xffff0000, v204
	v_lshlrev_b32_e32 v226, 16, v205
	v_and_b32_e32 v227, 0xffff0000, v205
	v_lshlrev_b32_e32 v228, 16, v212
	v_and_b32_e32 v229, 0xffff0000, v212
	v_lshlrev_b32_e32 v230, 16, v213
	v_and_b32_e32 v231, 0xffff0000, v213
	v_fma_f32 v84, v84, v228, v224
	v_fma_f32 v85, v85, v229, v225
	v_fma_f32 v86, v86, v230, v226
	v_fma_f32 v87, v87, v231, v227
	v_mul_f32_e32 v232, v85, v85
	v_mul_f32_e32 v233, v87, v87
	v_fmac_f32_e32 v232, v84, v84
	v_fmac_f32_e32 v233, v86, v86
	v_add_f32_e32 v248, v232, v233
	v_mul_f32_e32 v80, v80, v253
	v_mul_f32_e32 v81, v81, v253
	v_mul_f32_e32 v82, v82, v253
	v_mul_f32_e32 v83, v83, v253
	v_exp_f32_e32 v80, v80
	v_exp_f32_e32 v81, v81
	v_exp_f32_e32 v82, v82
	v_exp_f32_e32 v83, v83
	v_add_f32_e32 v80, 1.0, v80
	v_add_f32_e32 v81, 1.0, v81
	v_add_f32_e32 v82, 1.0, v82
	v_add_f32_e32 v83, 1.0, v83
	v_rcp_f32_e32 v80, v80
	v_rcp_f32_e32 v81, v81
	v_rcp_f32_e32 v82, v82
	v_rcp_f32_e32 v83, v83
	v_lshlrev_b32_e32 v224, 16, v206
	v_and_b32_e32 v225, 0xffff0000, v206
	v_lshlrev_b32_e32 v226, 16, v207
	v_and_b32_e32 v227, 0xffff0000, v207
	v_lshlrev_b32_e32 v228, 16, v214
	v_and_b32_e32 v229, 0xffff0000, v214
	v_lshlrev_b32_e32 v230, 16, v215
	v_and_b32_e32 v231, 0xffff0000, v215
	v_fma_f32 v80, v80, v228, v224
	v_fma_f32 v81, v81, v229, v225
	v_fma_f32 v82, v82, v230, v226
	v_fma_f32 v83, v83, v231, v227
	v_mul_f32_e32 v232, v81, v81
	v_mul_f32_e32 v233, v83, v83
	v_fmac_f32_e32 v232, v80, v80
	v_fmac_f32_e32 v233, v82, v82
	v_add_f32_e32 v249, v232, v233
	v_cvt_pk_bf16_f32 v84, v84, v85
	v_cvt_pk_bf16_f32 v85, v86, v87
	v_cvt_pk_bf16_f32 v86, v80, v81
	v_cvt_pk_bf16_f32 v87, v82, v83
	global_store_dwordx4 v250, v[84:87], s[0:1] offset:256
	v_add_f32_e32 v234, v234, v235
	v_add_f32_e32 v248, v248, v249
	v_add_f32_e32 v247, v234, v248
	ds_bpermute_b32 v252, v236, v247
	v_add_u32_e32 v251, 0x800, v194
	s_waitcnt lgkmcnt(0)
	v_add_f32_e32 v247, v247, v252
	ds_bpermute_b32 v252, v237, v247
	s_waitcnt lgkmcnt(0)
	v_add_f32_e32 v247, v247, v252
	s_and_saveexec_b64 s[28:29], vcc
	global_store_dword v251, v247, s[12:13]
	s_or_b64 exec, exec, s[28:29]
	v_add_u32_e32 v250, 0x58000, v172
	v_add_u32_e32 v251, 0x2c00, v173
	global_load_dwordx4 v[184:187], v251, s[10:11]
	global_load_dwordx4 v[188:191], v250, s[6:7]
	global_load_dwordx4 v[208:211], v250, s[2:3]
	global_load_dwordx4 v[204:207], v250, s[6:7] offset:256
	global_load_dwordx4 v[212:215], v250, s[2:3] offset:256
	s_waitcnt vmcnt(26)
	v_add_f32_e32 v247, v128, v129
	v_add_f32_e32 v252, v130, v131
	v_add_f32_e32 v247, v247, v252
	ds_bpermute_b32 v252, v236, v247
	s_waitcnt lgkmcnt(0)
; __device__ __forceinline__ u32x4 pack8(const f32x4 v0, const f32x4 v1) { u32x4 w; w.x = cvt_pk_bf16(v0[0], v0[1]); w.y = cvt_pk_bf16(v0[2], v0[3]); w.z = cvt_pk_bf16(v1[0], v1[1]); w.w = cvt_pk_bf16(v1[2], v1[3]); return w; }
; __device__ __forceinline__ float sumsq8(const f32x4 a, const f32x4 b) { return ((a[0] * a[0] + a[1] * a[1]) + (a[2] * a[2] + a[3] * a[3])) + ((b[0] * b[0] + b[1] * b[1]) + (b[2] * b[2] + b[3] * b[3])); }
; __device__ __forceinline__ void unpack8(const u32x4 w, f32x4& a, f32x4& b) { a = (f32x4){bf_lo(w.x), bf_hi(w.x), bf_lo(w.y), bf_hi(w.y)}; b = (f32x4){bf_lo(w.z), bf_hi(w.z), bf_lo(w.w), bf_hi(w.w)}; }
;     __device__ __forceinline__ void operator()(const f32x4 (&acc)[2][2][4][2], const Unit& u, int wr, int wc, int fr, int fq) const {
;     ...
;             for (int mm = 0; mm < 2; ++mm) { const int rowl = row0 + ai * HALF + (2 * mh + mm) * 16; p[mm] = *(const f32x4*)(ssq_in + (size_t)rowl * 16 + 4 * fq);
; #pragma unroll
;                 for (int bj = 0; bj < 2; ++bj) { const size_t off = (size_t)rowl * DMODEL + col0 + bj * HALF; rv[mm][bj] = *(const u32x4*)(Rin + off); pw[mm][bj] = *(const u32x4*)(PP + off); } }
; #pragma unroll
;             for (int mm = 0; mm < 2; ++mm) { const int m = 2 * mh + mm; const int row = row0 + ai * HALF + m * 16; float part = 0.f;
;                 float sr = (p[mm][0] + p[mm][1]) + (p[mm][2] + p[mm][3]); sr += __shfl_xor(sr, 16); sr += __shfl_xor(sr, 32); const float r = __builtin_amdgcn_rsqf(sr * (1.0f / DMODEL) + RMS_EPS);
; #pragma unroll
;                 for (int bj = 0; bj < 2; ++bj) { f32x4 r0, r1, p0, p1; unpack8(rv[mm][bj], r0, r1); unpack8(pw[mm][bj], p0, p1);
;                     f32x4 g0 = acc[ai][bj][m][0] * r, g1 = acc[ai][bj][m][1] * r;
; #pragma unroll
;                     for (int e = 0; e < 4; ++e) { g0[e] = __builtin_amdgcn_rcpf(1.f + __builtin_amdgcn_exp2f(-1.4426950408889634f * g0[e])); g1[e] = __builtin_amdgcn_rcpf(1.f + __builtin_amdgcn_exp2f(-1.4426950408889634f * g1[e])); }
;                     const f32x4 h0 = r0 + g0 * p0, h1 = r1 + g1 * p1; part += sumsq8(h0, h1);
;                     *(u32x4*)(XBo + (size_t)row * DMODEL + col0 + bj * HALF) = pack8(h0, h1); }
;                 part += __shfl_xor(part, 16); part += __shfl_xor(part, 32);
;                 if (fq == 0) ssq_out[(size_t)row * 16 + u.pn * 4 + wc] = part; }
	v_add_f32_e32 v247, v247, v252
	ds_bpermute_b32 v252, v237, v247
	s_waitcnt lgkmcnt(0)
	v_add_f32_e32 v247, v247, v252
	v_fmamk_f32 v247, v247, 0x3a800000, v193
	v_rsq_f32_e32 v247, v247
	s_nop 0
	v_mul_f32_e32 v253, 0xbfb8aa3b, v247
	v_mul_f32_e32 v76, v76, v253
	v_mul_f32_e32 v77, v77, v253
	v_mul_f32_e32 v78, v78, v253
	v_mul_f32_e32 v79, v79, v253
	v_exp_f32_e32 v76, v76
	v_exp_f32_e32 v77, v77
	v_exp_f32_e32 v78, v78
	v_exp_f32_e32 v79, v79
	v_add_f32_e32 v76, 1.0, v76
	v_add_f32_e32 v77, 1.0, v77
	v_add_f32_e32 v78, 1.0, v78
	v_add_f32_e32 v79, 1.0, v79
	v_rcp_f32_e32 v76, v76
	v_rcp_f32_e32 v77, v77
	v_rcp_f32_e32 v78, v78
	v_rcp_f32_e32 v79, v79
	v_lshlrev_b32_e32 v224, 16, v132
	v_and_b32_e32 v225, 0xffff0000, v132
	v_lshlrev_b32_e32 v226, 16, v133
	v_and_b32_e32 v227, 0xffff0000, v133
	v_lshlrev_b32_e32 v228, 16, v140
	v_and_b32_e32 v229, 0xffff0000, v140
	v_lshlrev_b32_e32 v230, 16, v141
	v_and_b32_e32 v231, 0xffff0000, v141
	v_fma_f32 v76, v76, v228, v224
	v_fma_f32 v77, v77, v229, v225
	v_fma_f32 v78, v78, v230, v226
	v_fma_f32 v79, v79, v231, v227
	v_mul_f32_e32 v232, v77, v77
	v_mul_f32_e32 v233, v79, v79
	v_fmac_f32_e32 v232, v76, v76
	v_fmac_f32_e32 v233, v78, v78
	v_add_f32_e32 v234, v232, v233
	v_mul_f32_e32 v72, v72, v253
	v_mul_f32_e32 v73, v73, v253
	v_mul_f32_e32 v74, v74, v253
	v_mul_f32_e32 v75, v75, v253
	v_exp_f32_e32 v72, v72
	v_exp_f32_e32 v73, v73
	v_exp_f32_e32 v74, v74
	v_exp_f32_e32 v75, v75
	v_add_f32_e32 v72, 1.0, v72
	v_add_f32_e32 v73, 1.0, v73
	v_add_f32_e32 v74, 1.0, v74
	v_add_f32_e32 v75, 1.0, v75
	v_rcp_f32_e32 v72, v72
	v_rcp_f32_e32 v73, v73
	v_rcp_f32_e32 v74, v74
	v_rcp_f32_e32 v75, v75
	v_lshlrev_b32_e32 v224, 16, v134
	v_and_b32_e32 v225, 0xffff0000, v134
	v_lshlrev_b32_e32 v226, 16, v135
	v_and_b32_e32 v227, 0xffff0000, v135
	v_lshlrev_b32_e32 v228, 16, v142
	v_and_b32_e32 v229, 0xffff0000, v142
	v_lshlrev_b32_e32 v230, 16, v143
	v_and_b32_e32 v231, 0xffff0000, v143
	v_fma_f32 v72, v72, v228, v224
	v_fma_f32 v73, v73, v229, v225
	v_fma_f32 v74, v74, v230, v226
	v_fma_f32 v75, v75, v231, v227
	v_mul_f32_e32 v232, v73, v73
	v_mul_f32_e32 v233, v75, v75
	v_fmac_f32_e32 v232, v72, v72
	v_fmac_f32_e32 v233, v74, v74
	v_add_f32_e32 v235, v232, v233
	v_cvt_pk_bf16_f32 v76, v76, v77
	v_cvt_pk_bf16_f32 v77, v78, v79
	v_cvt_pk_bf16_f32 v78, v72, v73
	v_cvt_pk_bf16_f32 v79, v74, v75
	v_add_u32_e32 v250, 0x18000, v172
	global_store_dwordx4 v250, v[76:79], s[0:1]
	v_mul_f32_e32 v68, v68, v253
	v_mul_f32_e32 v69, v69, v253
	v_mul_f32_e32 v70, v70, v253
	v_mul_f32_e32 v71, v71, v253
	v_exp_f32_e32 v68, v68
	v_exp_f32_e32 v69, v69
	v_exp_f32_e32 v70, v70
	v_exp_f32_e32 v71, v71
	v_add_f32_e32 v68, 1.0, v68
	v_add_f32_e32 v69, 1.0, v69
	v_add_f32_e32 v70, 1.0, v70
	v_add_f32_e32 v71, 1.0, v71
	v_rcp_f32_e32 v68, v68
	v_rcp_f32_e32 v69, v69
	v_rcp_f32_e32 v70, v70
	v_rcp_f32_e32 v71, v71
	v_lshlrev_b32_e32 v224, 16, v136
	v_and_b32_e32 v225, 0xffff0000, v136
	v_lshlrev_b32_e32 v226, 16, v137
	v_and_b32_e32 v227, 0xffff0000, v137
	v_lshlrev_b32_e32 v228, 16, v144
	v_and_b32_e32 v229, 0xffff0000, v144
	v_lshlrev_b32_e32 v230, 16, v145
	v_and_b32_e32 v231, 0xffff0000, v145
	v_fma_f32 v68, v68, v228, v224
	v_fma_f32 v69, v69, v229, v225
	v_fma_f32 v70, v70, v230, v226
	v_fma_f32 v71, v71, v231, v227
	v_mul_f32_e32 v232, v69, v69
	v_mul_f32_e32 v233, v71, v71
	v_fmac_f32_e32 v232, v68, v68
	v_fmac_f32_e32 v233, v70, v70
	v_add_f32_e32 v248, v232, v233
	v_mul_f32_e32 v64, v64, v253
	v_mul_f32_e32 v65, v65, v253
	v_mul_f32_e32 v66, v66, v253
	v_mul_f32_e32 v67, v67, v253
	v_exp_f32_e32 v64, v64
	v_exp_f32_e32 v65, v65
	v_exp_f32_e32 v66, v66
	v_exp_f32_e32 v67, v67
	v_add_f32_e32 v64, 1.0, v64
	v_add_f32_e32 v65, 1.0, v65
	v_add_f32_e32 v66, 1.0, v66
	v_add_f32_e32 v67, 1.0, v67
	v_rcp_f32_e32 v64, v64
	v_rcp_f32_e32 v65, v65
	v_rcp_f32_e32 v66, v66
	v_rcp_f32_e32 v67, v67
	v_lshlrev_b32_e32 v224, 16, v138
	v_and_b32_e32 v225, 0xffff0000, v138
	v_lshlrev_b32_e32 v226, 16, v139
	v_and_b32_e32 v227, 0xffff0000, v139
	v_lshlrev_b32_e32 v228, 16, v146
	v_and_b32_e32 v229, 0xffff0000, v146
	v_lshlrev_b32_e32 v230, 16, v147
	v_and_b32_e32 v231, 0xffff0000, v147
	v_fma_f32 v64, v64, v228, v224
	v_fma_f32 v65, v65, v229, v225
	v_fma_f32 v66, v66, v230, v226
	v_fma_f32 v67, v67, v231, v227
	v_mul_f32_e32 v232, v65, v65
	v_mul_f32_e32 v233, v67, v67
	v_fmac_f32_e32 v232, v64, v64
	v_fmac_f32_e32 v233, v66, v66
	v_add_f32_e32 v249, v232, v233
	v_cvt_pk_bf16_f32 v68, v68, v69
	v_cvt_pk_bf16_f32 v69, v70, v71
	v_cvt_pk_bf16_f32 v70, v64, v65
	v_cvt_pk_bf16_f32 v71, v66, v67
	global_store_dwordx4 v250, v[68:71], s[0:1] offset:256
	v_add_f32_e32 v234, v234, v235
	v_add_f32_e32 v248, v248, v249
	v_add_f32_e32 v247, v234, v248
	ds_bpermute_b32 v252, v236, v247
	v_add_u32_e32 v251, 0xc00, v194
	s_waitcnt lgkmcnt(0)
	v_add_f32_e32 v247, v247, v252
	ds_bpermute_b32 v252, v237, v247
	s_waitcnt lgkmcnt(0)
	v_add_f32_e32 v247, v247, v252
	s_and_saveexec_b64 s[28:29], vcc
	global_store_dword v251, v247, s[12:13]
	s_or_b64 exec, exec, s[28:29]
	s_waitcnt vmcnt(24)
	v_add_f32_e32 v247, v124, v125
	v_add_f32_e32 v252, v126, v127
	v_add_f32_e32 v247, v247, v252
	ds_bpermute_b32 v252, v236, v247
	s_waitcnt lgkmcnt(0)
	v_add_f32_e32 v247, v247, v252
	ds_bpermute_b32 v252, v237, v247
	s_waitcnt lgkmcnt(0)
; __device__ __forceinline__ u32x4 pack8(const f32x4 v0, const f32x4 v1) { u32x4 w; w.x = cvt_pk_bf16(v0[0], v0[1]); w.y = cvt_pk_bf16(v0[2], v0[3]); w.z = cvt_pk_bf16(v1[0], v1[1]); w.w = cvt_pk_bf16(v1[2], v1[3]); return w; }
; __device__ __forceinline__ float sumsq8(const f32x4 a, const f32x4 b) { return ((a[0] * a[0] + a[1] * a[1]) + (a[2] * a[2] + a[3] * a[3])) + ((b[0] * b[0] + b[1] * b[1]) + (b[2] * b[2] + b[3] * b[3])); }
; __device__ __forceinline__ void unpack8(const u32x4 w, f32x4& a, f32x4& b) { a = (f32x4){bf_lo(w.x), bf_hi(w.x), bf_lo(w.y), bf_hi(w.y)}; b = (f32x4){bf_lo(w.z), bf_hi(w.z), bf_lo(w.w), bf_hi(w.w)}; }
;     __device__ __forceinline__ void operator()(const f32x4 (&acc)[2][2][4][2], const Unit& u, int wr, int wc, int fr, int fq) const {
;     ...
;             for (int mm = 0; mm < 2; ++mm) { const int rowl = row0 + ai * HALF + (2 * mh + mm) * 16; p[mm] = *(const f32x4*)(ssq_in + (size_t)rowl * 16 + 4 * fq);
; #pragma unroll
;                 for (int bj = 0; bj < 2; ++bj) { const size_t off = (size_t)rowl * DMODEL + col0 + bj * HALF; rv[mm][bj] = *(const u32x4*)(Rin + off); pw[mm][bj] = *(const u32x4*)(PP + off); } }
; #pragma unroll
;             for (int mm = 0; mm < 2; ++mm) { const int m = 2 * mh + mm; const int row = row0 + ai * HALF + m * 16; float part = 0.f;
;                 float sr = (p[mm][0] + p[mm][1]) + (p[mm][2] + p[mm][3]); sr += __shfl_xor(sr, 16); sr += __shfl_xor(sr, 32); const float r = __builtin_amdgcn_rsqf(sr * (1.0f / DMODEL) + RMS_EPS);
; #pragma unroll
;                 for (int bj = 0; bj < 2; ++bj) { f32x4 r0, r1, p0, p1; unpack8(rv[mm][bj], r0, r1); unpack8(pw[mm][bj], p0, p1);
;                     f32x4 g0 = acc[ai][bj][m][0] * r, g1 = acc[ai][bj][m][1] * r;
; #pragma unroll
;                     for (int e = 0; e < 4; ++e) { g0[e] = __builtin_amdgcn_rcpf(1.f + __builtin_amdgcn_exp2f(-1.4426950408889634f * g0[e])); g1[e] = __builtin_amdgcn_rcpf(1.f + __builtin_amdgcn_exp2f(-1.4426950408889634f * g1[e])); }
;                     const f32x4 h0 = r0 + g0 * p0, h1 = r1 + g1 * p1; part += sumsq8(h0, h1);
;                     *(u32x4*)(XBo + (size_t)row * DMODEL + col0 + bj * HALF) = pack8(h0, h1); }
;                 part += __shfl_xor(part, 16); part += __shfl_xor(part, 32);
;                 if (fq == 0) ssq_out[(size_t)row * 16 + u.pn * 4 + wc] = part; }
	v_add_f32_e32 v247, v247, v252
	v_fmamk_f32 v247, v247, 0x3a800000, v193
	v_rsq_f32_e32 v247, v247
	s_nop 0
	v_mul_f32_e32 v253, 0xbfb8aa3b, v247
	v_mul_f32_e32 v60, v60, v253
	v_mul_f32_e32 v61, v61, v253
	v_mul_f32_e32 v62, v62, v253
	v_mul_f32_e32 v63, v63, v253
	v_exp_f32_e32 v60, v60
	v_exp_f32_e32 v61, v61
	v_exp_f32_e32 v62, v62
	v_exp_f32_e32 v63, v63
	v_add_f32_e32 v60, 1.0, v60
	v_add_f32_e32 v61, 1.0, v61
	v_add_f32_e32 v62, 1.0, v62
	v_add_f32_e32 v63, 1.0, v63
	v_rcp_f32_e32 v60, v60
	v_rcp_f32_e32 v61, v61
	v_rcp_f32_e32 v62, v62
	v_rcp_f32_e32 v63, v63
	v_lshlrev_b32_e32 v224, 16, v120
	v_and_b32_e32 v225, 0xffff0000, v120
	v_lshlrev_b32_e32 v226, 16, v121
	v_and_b32_e32 v227, 0xffff0000, v121
	v_lshlrev_b32_e32 v228, 16, v112
	v_and_b32_e32 v229, 0xffff0000, v112
	v_lshlrev_b32_e32 v230, 16, v113
	v_and_b32_e32 v231, 0xffff0000, v113
	v_fma_f32 v60, v60, v228, v224
	v_fma_f32 v61, v61, v229, v225
	v_fma_f32 v62, v62, v230, v226
	v_fma_f32 v63, v63, v231, v227
	v_mul_f32_e32 v232, v61, v61
	v_mul_f32_e32 v233, v63, v63
	v_fmac_f32_e32 v232, v60, v60
	v_fmac_f32_e32 v233, v62, v62
	v_add_f32_e32 v234, v232, v233
	v_mul_f32_e32 v56, v56, v253
	v_mul_f32_e32 v57, v57, v253
	v_mul_f32_e32 v58, v58, v253
	v_mul_f32_e32 v59, v59, v253
	v_exp_f32_e32 v56, v56
	v_exp_f32_e32 v57, v57
	v_exp_f32_e32 v58, v58
	v_exp_f32_e32 v59, v59
	v_add_f32_e32 v56, 1.0, v56
	v_add_f32_e32 v57, 1.0, v57
	v_add_f32_e32 v58, 1.0, v58
	v_add_f32_e32 v59, 1.0, v59
	v_rcp_f32_e32 v56, v56
	v_rcp_f32_e32 v57, v57
	v_rcp_f32_e32 v58, v58
	v_rcp_f32_e32 v59, v59
	v_lshlrev_b32_e32 v224, 16, v122
	v_and_b32_e32 v225, 0xffff0000, v122
	v_lshlrev_b32_e32 v226, 16, v123
	v_and_b32_e32 v227, 0xffff0000, v123
	v_lshlrev_b32_e32 v228, 16, v114
	v_and_b32_e32 v229, 0xffff0000, v114
	v_lshlrev_b32_e32 v230, 16, v115
	v_and_b32_e32 v231, 0xffff0000, v115
	v_fma_f32 v56, v56, v228, v224
	v_fma_f32 v57, v57, v229, v225
	v_fma_f32 v58, v58, v230, v226
	v_fma_f32 v59, v59, v231, v227
	v_mul_f32_e32 v232, v57, v57
	v_mul_f32_e32 v233, v59, v59
	v_fmac_f32_e32 v232, v56, v56
	v_fmac_f32_e32 v233, v58, v58
	v_add_f32_e32 v235, v232, v233
	v_cvt_pk_bf16_f32 v60, v60, v61
	v_cvt_pk_bf16_f32 v61, v62, v63
	v_cvt_pk_bf16_f32 v62, v56, v57
	v_cvt_pk_bf16_f32 v63, v58, v59
	v_add_u32_e32 v250, 0x40000, v172
	global_store_dwordx4 v250, v[60:63], s[0:1]
	v_mul_f32_e32 v52, v52, v253
	v_mul_f32_e32 v53, v53, v253
	v_mul_f32_e32 v54, v54, v253
	v_mul_f32_e32 v55, v55, v253
	v_exp_f32_e32 v52, v52
	v_exp_f32_e32 v53, v53
	v_exp_f32_e32 v54, v54
	v_exp_f32_e32 v55, v55
	v_add_f32_e32 v52, 1.0, v52
	v_add_f32_e32 v53, 1.0, v53
	v_add_f32_e32 v54, 1.0, v54
	v_add_f32_e32 v55, 1.0, v55
	v_rcp_f32_e32 v52, v52
	v_rcp_f32_e32 v53, v53
	v_rcp_f32_e32 v54, v54
	v_rcp_f32_e32 v55, v55
	v_lshlrev_b32_e32 v224, 16, v116
	v_and_b32_e32 v225, 0xffff0000, v116
	v_lshlrev_b32_e32 v226, 16, v117
	v_and_b32_e32 v227, 0xffff0000, v117
	v_lshlrev_b32_e32 v228, 16, v216
	v_and_b32_e32 v229, 0xffff0000, v216
	v_lshlrev_b32_e32 v230, 16, v217
	v_and_b32_e32 v231, 0xffff0000, v217
	v_fma_f32 v52, v52, v228, v224
	v_fma_f32 v53, v53, v229, v225
	v_fma_f32 v54, v54, v230, v226
	v_fma_f32 v55, v55, v231, v227
	v_mul_f32_e32 v232, v53, v53
	v_mul_f32_e32 v233, v55, v55
	v_fmac_f32_e32 v232, v52, v52
	v_fmac_f32_e32 v233, v54, v54
	v_add_f32_e32 v248, v232, v233
	v_mul_f32_e32 v48, v48, v253
	v_mul_f32_e32 v49, v49, v253
	v_mul_f32_e32 v50, v50, v253
	v_mul_f32_e32 v51, v51, v253
	v_exp_f32_e32 v48, v48
	v_exp_f32_e32 v49, v49
	v_exp_f32_e32 v50, v50
	v_exp_f32_e32 v51, v51
	v_add_f32_e32 v48, 1.0, v48
	v_add_f32_e32 v49, 1.0, v49
	v_add_f32_e32 v50, 1.0, v50
	v_add_f32_e32 v51, 1.0, v51
	v_rcp_f32_e32 v48, v48
	v_rcp_f32_e32 v49, v49
	v_rcp_f32_e32 v50, v50
	v_rcp_f32_e32 v51, v51
	v_lshlrev_b32_e32 v224, 16, v118
	v_and_b32_e32 v225, 0xffff0000, v118
	v_lshlrev_b32_e32 v226, 16, v119
	v_and_b32_e32 v227, 0xffff0000, v119
	v_lshlrev_b32_e32 v228, 16, v218
	v_and_b32_e32 v229, 0xffff0000, v218
	v_lshlrev_b32_e32 v230, 16, v219
	v_and_b32_e32 v231, 0xffff0000, v219
	v_fma_f32 v48, v48, v228, v224
	v_fma_f32 v49, v49, v229, v225
	v_fma_f32 v50, v50, v230, v226
	v_fma_f32 v51, v51, v231, v227
	v_mul_f32_e32 v232, v49, v49
	v_mul_f32_e32 v233, v51, v51
	v_fmac_f32_e32 v232, v48, v48
	v_fmac_f32_e32 v233, v50, v50
	v_add_f32_e32 v249, v232, v233
	v_cvt_pk_bf16_f32 v52, v52, v53
	v_cvt_pk_bf16_f32 v53, v54, v55
	v_cvt_pk_bf16_f32 v54, v48, v49
	v_cvt_pk_bf16_f32 v55, v50, v51
	global_store_dwordx4 v250, v[52:55], s[0:1] offset:256
	v_add_f32_e32 v234, v234, v235
	v_add_f32_e32 v248, v248, v249
	v_add_f32_e32 v247, v234, v248
	ds_bpermute_b32 v252, v236, v247
	v_add_u32_e32 v251, 0x2000, v194
	s_waitcnt lgkmcnt(0)
	v_add_f32_e32 v247, v247, v252
	ds_bpermute_b32 v252, v237, v247
	s_waitcnt lgkmcnt(0)
	v_add_f32_e32 v247, v247, v252
	s_and_saveexec_b64 s[28:29], vcc
	global_store_dword v251, v247, s[12:13]
	s_or_b64 exec, exec, s[28:29]
	s_waitcnt vmcnt(19)
	v_add_f32_e32 v247, v160, v161
	v_add_f32_e32 v252, v162, v163
	v_add_f32_e32 v247, v247, v252
	ds_bpermute_b32 v252, v236, v247
	s_waitcnt lgkmcnt(0)
	v_add_f32_e32 v247, v247, v252
	ds_bpermute_b32 v252, v237, v247
	s_waitcnt lgkmcnt(0)
; __device__ __forceinline__ u32x4 pack8(const f32x4 v0, const f32x4 v1) { u32x4 w; w.x = cvt_pk_bf16(v0[0], v0[1]); w.y = cvt_pk_bf16(v0[2], v0[3]); w.z = cvt_pk_bf16(v1[0], v1[1]); w.w = cvt_pk_bf16(v1[2], v1[3]); return w; }
; __device__ __forceinline__ float sumsq8(const f32x4 a, const f32x4 b) { return ((a[0] * a[0] + a[1] * a[1]) + (a[2] * a[2] + a[3] * a[3])) + ((b[0] * b[0] + b[1] * b[1]) + (b[2] * b[2] + b[3] * b[3])); }
; __device__ __forceinline__ void unpack8(const u32x4 w, f32x4& a, f32x4& b) { a = (f32x4){bf_lo(w.x), bf_hi(w.x), bf_lo(w.y), bf_hi(w.y)}; b = (f32x4){bf_lo(w.z), bf_hi(w.z), bf_lo(w.w), bf_hi(w.w)}; }
;     __device__ __forceinline__ void operator()(const f32x4 (&acc)[2][2][4][2], const Unit& u, int wr, int wc, int fr, int fq) const {
;     ...
;             for (int mm = 0; mm < 2; ++mm) { const int rowl = row0 + ai * HALF + (2 * mh + mm) * 16; p[mm] = *(const f32x4*)(ssq_in + (size_t)rowl * 16 + 4 * fq);
; #pragma unroll
;                 for (int bj = 0; bj < 2; ++bj) { const size_t off = (size_t)rowl * DMODEL + col0 + bj * HALF; rv[mm][bj] = *(const u32x4*)(Rin + off); pw[mm][bj] = *(const u32x4*)(PP + off); } }
; #pragma unroll
;             for (int mm = 0; mm < 2; ++mm) { const int m = 2 * mh + mm; const int row = row0 + ai * HALF + m * 16; float part = 0.f;
;                 float sr = (p[mm][0] + p[mm][1]) + (p[mm][2] + p[mm][3]); sr += __shfl_xor(sr, 16); sr += __shfl_xor(sr, 32); const float r = __builtin_amdgcn_rsqf(sr * (1.0f / DMODEL) + RMS_EPS);
; #pragma unroll
;                 for (int bj = 0; bj < 2; ++bj) { f32x4 r0, r1, p0, p1; unpack8(rv[mm][bj], r0, r1); unpack8(pw[mm][bj], p0, p1);
;                     f32x4 g0 = acc[ai][bj][m][0] * r, g1 = acc[ai][bj][m][1] * r;
; #pragma unroll
;                     for (int e = 0; e < 4; ++e) { g0[e] = __builtin_amdgcn_rcpf(1.f + __builtin_amdgcn_exp2f(-1.4426950408889634f * g0[e])); g1[e] = __builtin_amdgcn_rcpf(1.f + __builtin_amdgcn_exp2f(-1.4426950408889634f * g1[e])); }
;                     const f32x4 h0 = r0 + g0 * p0, h1 = r1 + g1 * p1; part += sumsq8(h0, h1);
;                     *(u32x4*)(XBo + (size_t)row * DMODEL + col0 + bj * HALF) = pack8(h0, h1); }
;                 part += __shfl_xor(part, 16); part += __shfl_xor(part, 32);
;                 if (fq == 0) ssq_out[(size_t)row * 16 + u.pn * 4 + wc] = part; }
	v_add_f32_e32 v247, v247, v252
	v_fmamk_f32 v247, v247, 0x3a800000, v193
	v_rsq_f32_e32 v247, v247
	s_nop 0
	v_mul_f32_e32 v253, 0xbfb8aa3b, v247
	v_mul_f32_e32 v44, v44, v253
	v_mul_f32_e32 v45, v45, v253
	v_mul_f32_e32 v46, v46, v253
	v_mul_f32_e32 v47, v47, v253
	v_exp_f32_e32 v44, v44
	v_exp_f32_e32 v45, v45
	v_exp_f32_e32 v46, v46
	v_exp_f32_e32 v47, v47
	v_add_f32_e32 v44, 1.0, v44
	v_add_f32_e32 v45, 1.0, v45
	v_add_f32_e32 v46, 1.0, v46
	v_add_f32_e32 v47, 1.0, v47
	v_rcp_f32_e32 v44, v44
	v_rcp_f32_e32 v45, v45
	v_rcp_f32_e32 v46, v46
	v_rcp_f32_e32 v47, v47
	v_lshlrev_b32_e32 v224, 16, v164
	v_and_b32_e32 v225, 0xffff0000, v164
	v_lshlrev_b32_e32 v226, 16, v165
	v_and_b32_e32 v227, 0xffff0000, v165
	v_lshlrev_b32_e32 v228, 16, v176
	v_and_b32_e32 v229, 0xffff0000, v176
	v_lshlrev_b32_e32 v230, 16, v177
	v_and_b32_e32 v231, 0xffff0000, v177
	v_fma_f32 v44, v44, v228, v224
	v_fma_f32 v45, v45, v229, v225
	v_fma_f32 v46, v46, v230, v226
	v_fma_f32 v47, v47, v231, v227
	v_mul_f32_e32 v232, v45, v45
	v_mul_f32_e32 v233, v47, v47
	v_fmac_f32_e32 v232, v44, v44
	v_fmac_f32_e32 v233, v46, v46
	v_add_f32_e32 v234, v232, v233
	v_mul_f32_e32 v40, v40, v253
	v_mul_f32_e32 v41, v41, v253
	v_mul_f32_e32 v42, v42, v253
	v_mul_f32_e32 v43, v43, v253
	v_exp_f32_e32 v40, v40
	v_exp_f32_e32 v41, v41
	v_exp_f32_e32 v42, v42
	v_exp_f32_e32 v43, v43
	v_add_f32_e32 v40, 1.0, v40
	v_add_f32_e32 v41, 1.0, v41
	v_add_f32_e32 v42, 1.0, v42
	v_add_f32_e32 v43, 1.0, v43
	v_rcp_f32_e32 v40, v40
	v_rcp_f32_e32 v41, v41
	v_rcp_f32_e32 v42, v42
	v_rcp_f32_e32 v43, v43
	v_lshlrev_b32_e32 v224, 16, v166
	v_and_b32_e32 v225, 0xffff0000, v166
	v_lshlrev_b32_e32 v226, 16, v167
	v_and_b32_e32 v227, 0xffff0000, v167
	v_lshlrev_b32_e32 v228, 16, v178
	v_and_b32_e32 v229, 0xffff0000, v178
	v_lshlrev_b32_e32 v230, 16, v179
	v_and_b32_e32 v231, 0xffff0000, v179
	v_fma_f32 v40, v40, v228, v224
	v_fma_f32 v41, v41, v229, v225
	v_fma_f32 v42, v42, v230, v226
	v_fma_f32 v43, v43, v231, v227
	v_mul_f32_e32 v232, v41, v41
	v_mul_f32_e32 v233, v43, v43
	v_fmac_f32_e32 v232, v40, v40
	v_fmac_f32_e32 v233, v42, v42
	v_add_f32_e32 v235, v232, v233
	v_cvt_pk_bf16_f32 v44, v44, v45
	v_cvt_pk_bf16_f32 v45, v46, v47
	v_cvt_pk_bf16_f32 v46, v40, v41
	v_cvt_pk_bf16_f32 v47, v42, v43
	v_add_u32_e32 v250, 0x48000, v172
	global_store_dwordx4 v250, v[44:47], s[0:1]
	v_mul_f32_e32 v36, v36, v253
	v_mul_f32_e32 v37, v37, v253
	v_mul_f32_e32 v38, v38, v253
	v_mul_f32_e32 v39, v39, v253
	v_exp_f32_e32 v36, v36
	v_exp_f32_e32 v37, v37
	v_exp_f32_e32 v38, v38
	v_exp_f32_e32 v39, v39
	v_add_f32_e32 v36, 1.0, v36
	v_add_f32_e32 v37, 1.0, v37
	v_add_f32_e32 v38, 1.0, v38
	v_add_f32_e32 v39, 1.0, v39
	v_rcp_f32_e32 v36, v36
	v_rcp_f32_e32 v37, v37
	v_rcp_f32_e32 v38, v38
	v_rcp_f32_e32 v39, v39
	v_lshlrev_b32_e32 v224, 16, v168
	v_and_b32_e32 v225, 0xffff0000, v168
	v_lshlrev_b32_e32 v226, 16, v169
	v_and_b32_e32 v227, 0xffff0000, v169
	v_lshlrev_b32_e32 v228, 16, v180
	v_and_b32_e32 v229, 0xffff0000, v180
	v_lshlrev_b32_e32 v230, 16, v181
	v_and_b32_e32 v231, 0xffff0000, v181
	v_fma_f32 v36, v36, v228, v224
	v_fma_f32 v37, v37, v229, v225
	v_fma_f32 v38, v38, v230, v226
	v_fma_f32 v39, v39, v231, v227
	v_mul_f32_e32 v232, v37, v37
	v_mul_f32_e32 v233, v39, v39
	v_fmac_f32_e32 v232, v36, v36
	v_fmac_f32_e32 v233, v38, v38
	v_add_f32_e32 v248, v232, v233
	v_mul_f32_e32 v32, v32, v253
	v_mul_f32_e32 v33, v33, v253
	v_mul_f32_e32 v34, v34, v253
	v_mul_f32_e32 v35, v35, v253
	v_exp_f32_e32 v32, v32
	v_exp_f32_e32 v33, v33
	v_exp_f32_e32 v34, v34
	v_exp_f32_e32 v35, v35
	v_add_f32_e32 v32, 1.0, v32
	v_add_f32_e32 v33, 1.0, v33
	v_add_f32_e32 v34, 1.0, v34
	v_add_f32_e32 v35, 1.0, v35
	v_rcp_f32_e32 v32, v32
	v_rcp_f32_e32 v33, v33
	v_rcp_f32_e32 v34, v34
	v_rcp_f32_e32 v35, v35
	v_lshlrev_b32_e32 v224, 16, v170
	v_and_b32_e32 v225, 0xffff0000, v170
	v_lshlrev_b32_e32 v226, 16, v171
	v_and_b32_e32 v227, 0xffff0000, v171
	v_lshlrev_b32_e32 v228, 16, v182
	v_and_b32_e32 v229, 0xffff0000, v182
	v_lshlrev_b32_e32 v230, 16, v183
	v_and_b32_e32 v231, 0xffff0000, v183
	v_fma_f32 v32, v32, v228, v224
	v_fma_f32 v33, v33, v229, v225
	v_fma_f32 v34, v34, v230, v226
	v_fma_f32 v35, v35, v231, v227
	v_mul_f32_e32 v232, v33, v33
	v_mul_f32_e32 v233, v35, v35
	v_fmac_f32_e32 v232, v32, v32
	v_fmac_f32_e32 v233, v34, v34
	v_add_f32_e32 v249, v232, v233
	v_cvt_pk_bf16_f32 v36, v36, v37
	v_cvt_pk_bf16_f32 v37, v38, v39
	v_cvt_pk_bf16_f32 v38, v32, v33
	v_cvt_pk_bf16_f32 v39, v34, v35
	global_store_dwordx4 v250, v[36:39], s[0:1] offset:256
	v_add_f32_e32 v234, v234, v235
	v_add_f32_e32 v248, v248, v249
	v_add_f32_e32 v247, v234, v248
	ds_bpermute_b32 v252, v236, v247
	v_add_u32_e32 v251, 0x2400, v194
	s_waitcnt lgkmcnt(0)
	v_add_f32_e32 v247, v247, v252
	ds_bpermute_b32 v252, v237, v247
	s_waitcnt lgkmcnt(0)
	v_add_f32_e32 v247, v247, v252
	s_and_saveexec_b64 s[28:29], vcc
	global_store_dword v251, v247, s[12:13]
	s_or_b64 exec, exec, s[28:29]
	s_waitcnt vmcnt(17)
	v_add_f32_e32 v247, v108, v109
	v_add_f32_e32 v252, v110, v111
	v_add_f32_e32 v247, v247, v252
	ds_bpermute_b32 v252, v236, v247
	s_waitcnt lgkmcnt(0)
	v_add_f32_e32 v247, v247, v252
	ds_bpermute_b32 v252, v237, v247
	s_waitcnt lgkmcnt(0)
; __device__ __forceinline__ u32x4 pack8(const f32x4 v0, const f32x4 v1) { u32x4 w; w.x = cvt_pk_bf16(v0[0], v0[1]); w.y = cvt_pk_bf16(v0[2], v0[3]); w.z = cvt_pk_bf16(v1[0], v1[1]); w.w = cvt_pk_bf16(v1[2], v1[3]); return w; }
; __device__ __forceinline__ float sumsq8(const f32x4 a, const f32x4 b) { return ((a[0] * a[0] + a[1] * a[1]) + (a[2] * a[2] + a[3] * a[3])) + ((b[0] * b[0] + b[1] * b[1]) + (b[2] * b[2] + b[3] * b[3])); }
; __device__ __forceinline__ void unpack8(const u32x4 w, f32x4& a, f32x4& b) { a = (f32x4){bf_lo(w.x), bf_hi(w.x), bf_lo(w.y), bf_hi(w.y)}; b = (f32x4){bf_lo(w.z), bf_hi(w.z), bf_lo(w.w), bf_hi(w.w)}; }
;     __device__ __forceinline__ void operator()(const f32x4 (&acc)[2][2][4][2], const Unit& u, int wr, int wc, int fr, int fq) const {
;     ...
;             for (int mm = 0; mm < 2; ++mm) { const int m = 2 * mh + mm; const int row = row0 + ai * HALF + m * 16; float part = 0.f;
;                 float sr = (p[mm][0] + p[mm][1]) + (p[mm][2] + p[mm][3]); sr += __shfl_xor(sr, 16); sr += __shfl_xor(sr, 32); const float r = __builtin_amdgcn_rsqf(sr * (1.0f / DMODEL) + RMS_EPS);
; #pragma unroll
;                 for (int bj = 0; bj < 2; ++bj) { f32x4 r0, r1, p0, p1; unpack8(rv[mm][bj], r0, r1); unpack8(pw[mm][bj], p0, p1);
;                     f32x4 g0 = acc[ai][bj][m][0] * r, g1 = acc[ai][bj][m][1] * r;
; #pragma unroll
;                     for (int e = 0; e < 4; ++e) { g0[e] = __builtin_amdgcn_rcpf(1.f + __builtin_amdgcn_exp2f(-1.4426950408889634f * g0[e])); g1[e] = __builtin_amdgcn_rcpf(1.f + __builtin_amdgcn_exp2f(-1.4426950408889634f * g1[e])); }
;                     const f32x4 h0 = r0 + g0 * p0, h1 = r1 + g1 * p1; part += sumsq8(h0, h1);
;                     *(u32x4*)(XBo + (size_t)row * DMODEL + col0 + bj * HALF) = pack8(h0, h1); }
;                 part += __shfl_xor(part, 16); part += __shfl_xor(part, 32);
;                 if (fq == 0) ssq_out[(size_t)row * 16 + u.pn * 4 + wc] = part; }
	v_add_f32_e32 v247, v247, v252
	v_fmamk_f32 v247, v247, 0x3a800000, v193
	v_rsq_f32_e32 v247, v247
	s_nop 0
	v_mul_f32_e32 v253, 0xbfb8aa3b, v247
	v_mul_f32_e32 v28, v28, v253
	v_mul_f32_e32 v29, v29, v253
	v_mul_f32_e32 v30, v30, v253
	v_mul_f32_e32 v31, v31, v253
	v_exp_f32_e32 v28, v28
	v_exp_f32_e32 v29, v29
	v_exp_f32_e32 v30, v30
	v_exp_f32_e32 v31, v31
	v_add_f32_e32 v28, 1.0, v28
	v_add_f32_e32 v29, 1.0, v29
	v_add_f32_e32 v30, 1.0, v30
	v_add_f32_e32 v31, 1.0, v31
	v_rcp_f32_e32 v28, v28
	v_rcp_f32_e32 v29, v29
	v_rcp_f32_e32 v30, v30
	v_rcp_f32_e32 v31, v31
	v_lshlrev_b32_e32 v224, 16, v104
	v_and_b32_e32 v225, 0xffff0000, v104
	v_lshlrev_b32_e32 v226, 16, v105
	v_and_b32_e32 v227, 0xffff0000, v105
	v_lshlrev_b32_e32 v228, 16, v96
	v_and_b32_e32 v229, 0xffff0000, v96
	v_lshlrev_b32_e32 v230, 16, v97
	v_and_b32_e32 v231, 0xffff0000, v97
	v_fma_f32 v28, v28, v228, v224
	v_fma_f32 v29, v29, v229, v225
	v_fma_f32 v30, v30, v230, v226
	v_fma_f32 v31, v31, v231, v227
	v_mul_f32_e32 v232, v29, v29
	v_mul_f32_e32 v233, v31, v31
	v_fmac_f32_e32 v232, v28, v28
	v_fmac_f32_e32 v233, v30, v30
	v_add_f32_e32 v234, v232, v233
	v_mul_f32_e32 v24, v24, v253
	v_mul_f32_e32 v25, v25, v253
	v_mul_f32_e32 v26, v26, v253
	v_mul_f32_e32 v27, v27, v253
	v_exp_f32_e32 v24, v24
	v_exp_f32_e32 v25, v25
	v_exp_f32_e32 v26, v26
	v_exp_f32_e32 v27, v27
	v_add_f32_e32 v24, 1.0, v24
	v_add_f32_e32 v25, 1.0, v25
	v_add_f32_e32 v26, 1.0, v26
	v_add_f32_e32 v27, 1.0, v27
	v_rcp_f32_e32 v24, v24
	v_rcp_f32_e32 v25, v25
	v_rcp_f32_e32 v26, v26
	v_rcp_f32_e32 v27, v27
	v_lshlrev_b32_e32 v224, 16, v106
	v_and_b32_e32 v225, 0xffff0000, v106
	v_lshlrev_b32_e32 v226, 16, v107
	v_and_b32_e32 v227, 0xffff0000, v107
	v_lshlrev_b32_e32 v228, 16, v98
	v_and_b32_e32 v229, 0xffff0000, v98
	v_lshlrev_b32_e32 v230, 16, v99
	v_and_b32_e32 v231, 0xffff0000, v99
	v_fma_f32 v24, v24, v228, v224
	v_fma_f32 v25, v25, v229, v225
	v_fma_f32 v26, v26, v230, v226
	v_fma_f32 v27, v27, v231, v227
	v_mul_f32_e32 v232, v25, v25
	v_mul_f32_e32 v233, v27, v27
	v_fmac_f32_e32 v232, v24, v24
	v_fmac_f32_e32 v233, v26, v26
	v_add_f32_e32 v235, v232, v233
	v_cvt_pk_bf16_f32 v28, v28, v29
	v_cvt_pk_bf16_f32 v29, v30, v31
	v_cvt_pk_bf16_f32 v30, v24, v25
	v_cvt_pk_bf16_f32 v31, v26, v27
	v_add_u32_e32 v250, 0x50000, v172
	global_store_dwordx4 v250, v[28:31], s[0:1]
	v_mul_f32_e32 v20, v20, v253
	v_mul_f32_e32 v21, v21, v253
	v_mul_f32_e32 v22, v22, v253
	v_mul_f32_e32 v23, v23, v253
	v_exp_f32_e32 v20, v20
	v_exp_f32_e32 v21, v21
	v_exp_f32_e32 v22, v22
	v_exp_f32_e32 v23, v23
	v_add_f32_e32 v20, 1.0, v20
	v_add_f32_e32 v21, 1.0, v21
	v_add_f32_e32 v22, 1.0, v22
	v_add_f32_e32 v23, 1.0, v23
	v_rcp_f32_e32 v20, v20
	v_rcp_f32_e32 v21, v21
	v_rcp_f32_e32 v22, v22
	v_rcp_f32_e32 v23, v23
	v_lshlrev_b32_e32 v224, 16, v100
	v_and_b32_e32 v225, 0xffff0000, v100
	v_lshlrev_b32_e32 v226, 16, v101
	v_and_b32_e32 v227, 0xffff0000, v101
	v_lshlrev_b32_e32 v228, 16, v220
	v_and_b32_e32 v229, 0xffff0000, v220
	v_lshlrev_b32_e32 v230, 16, v221
	v_and_b32_e32 v231, 0xffff0000, v221
	v_fma_f32 v20, v20, v228, v224
	v_fma_f32 v21, v21, v229, v225
	v_fma_f32 v22, v22, v230, v226
	v_fma_f32 v23, v23, v231, v227
	v_mul_f32_e32 v232, v21, v21
	v_mul_f32_e32 v233, v23, v23
	v_fmac_f32_e32 v232, v20, v20
	v_fmac_f32_e32 v233, v22, v22
	v_add_f32_e32 v248, v232, v233
	v_mul_f32_e32 v16, v16, v253
	v_mul_f32_e32 v17, v17, v253
	v_mul_f32_e32 v18, v18, v253
	v_mul_f32_e32 v19, v19, v253
	v_exp_f32_e32 v16, v16
	v_exp_f32_e32 v17, v17
	v_exp_f32_e32 v18, v18
	v_exp_f32_e32 v19, v19
	v_add_f32_e32 v16, 1.0, v16
	v_add_f32_e32 v17, 1.0, v17
	v_add_f32_e32 v18, 1.0, v18
	v_add_f32_e32 v19, 1.0, v19
	v_rcp_f32_e32 v16, v16
	v_rcp_f32_e32 v17, v17
	v_rcp_f32_e32 v18, v18
	v_rcp_f32_e32 v19, v19
	v_lshlrev_b32_e32 v224, 16, v102
	v_and_b32_e32 v225, 0xffff0000, v102
	v_lshlrev_b32_e32 v226, 16, v103
	v_and_b32_e32 v227, 0xffff0000, v103
	v_lshlrev_b32_e32 v228, 16, v222
	v_and_b32_e32 v229, 0xffff0000, v222
	v_lshlrev_b32_e32 v230, 16, v223
	v_and_b32_e32 v231, 0xffff0000, v223
	v_fma_f32 v16, v16, v228, v224
	v_fma_f32 v17, v17, v229, v225
	v_fma_f32 v18, v18, v230, v226
	v_fma_f32 v19, v19, v231, v227
	v_mul_f32_e32 v232, v17, v17
	v_mul_f32_e32 v233, v19, v19
	v_fmac_f32_e32 v232, v16, v16
	v_fmac_f32_e32 v233, v18, v18
	v_add_f32_e32 v249, v232, v233
	v_cvt_pk_bf16_f32 v20, v20, v21
	v_cvt_pk_bf16_f32 v21, v22, v23
	v_cvt_pk_bf16_f32 v22, v16, v17
	v_cvt_pk_bf16_f32 v23, v18, v19
	global_store_dwordx4 v250, v[20:23], s[0:1] offset:256
	v_add_f32_e32 v234, v234, v235
	v_add_f32_e32 v248, v248, v249
	v_add_f32_e32 v247, v234, v248
	ds_bpermute_b32 v252, v236, v247
	v_add_u32_e32 v251, 0x2800, v194
	s_waitcnt lgkmcnt(0)
	v_add_f32_e32 v247, v247, v252
	ds_bpermute_b32 v252, v237, v247
	s_waitcnt lgkmcnt(0)
	v_add_f32_e32 v247, v247, v252
	s_and_saveexec_b64 s[28:29], vcc
	global_store_dword v251, v247, s[12:13]
	s_or_b64 exec, exec, s[28:29]
	s_waitcnt vmcnt(12)
	v_add_f32_e32 v247, v184, v185
	v_add_f32_e32 v252, v186, v187
	v_add_f32_e32 v247, v247, v252
	ds_bpermute_b32 v252, v236, v247
	s_waitcnt lgkmcnt(0)
; __device__ __forceinline__ u32x4 pack8(const f32x4 v0, const f32x4 v1) { u32x4 w; w.x = cvt_pk_bf16(v0[0], v0[1]); w.y = cvt_pk_bf16(v0[2], v0[3]); w.z = cvt_pk_bf16(v1[0], v1[1]); w.w = cvt_pk_bf16(v1[2], v1[3]); return w; }
; __device__ __forceinline__ float sumsq8(const f32x4 a, const f32x4 b) { return ((a[0] * a[0] + a[1] * a[1]) + (a[2] * a[2] + a[3] * a[3])) + ((b[0] * b[0] + b[1] * b[1]) + (b[2] * b[2] + b[3] * b[3])); }
; __device__ __forceinline__ void unpack8(const u32x4 w, f32x4& a, f32x4& b) { a = (f32x4){bf_lo(w.x), bf_hi(w.x), bf_lo(w.y), bf_hi(w.y)}; b = (f32x4){bf_lo(w.z), bf_hi(w.z), bf_lo(w.w), bf_hi(w.w)}; }
;     __device__ __forceinline__ void operator()(const f32x4 (&acc)[2][2][4][2], const Unit& u, int wr, int wc, int fr, int fq) const {
;     ...
;             for (int mm = 0; mm < 2; ++mm) { const int m = 2 * mh + mm; const int row = row0 + ai * HALF + m * 16; float part = 0.f;
;                 float sr = (p[mm][0] + p[mm][1]) + (p[mm][2] + p[mm][3]); sr += __shfl_xor(sr, 16); sr += __shfl_xor(sr, 32); const float r = __builtin_amdgcn_rsqf(sr * (1.0f / DMODEL) + RMS_EPS);
; #pragma unroll
;                 for (int bj = 0; bj < 2; ++bj) { f32x4 r0, r1, p0, p1; unpack8(rv[mm][bj], r0, r1); unpack8(pw[mm][bj], p0, p1);
;                     f32x4 g0 = acc[ai][bj][m][0] * r, g1 = acc[ai][bj][m][1] * r;
; #pragma unroll
;                     for (int e = 0; e < 4; ++e) { g0[e] = __builtin_amdgcn_rcpf(1.f + __builtin_amdgcn_exp2f(-1.4426950408889634f * g0[e])); g1[e] = __builtin_amdgcn_rcpf(1.f + __builtin_amdgcn_exp2f(-1.4426950408889634f * g1[e])); }
;                     const f32x4 h0 = r0 + g0 * p0, h1 = r1 + g1 * p1; part += sumsq8(h0, h1);
;                     *(u32x4*)(XBo + (size_t)row * DMODEL + col0 + bj * HALF) = pack8(h0, h1); }
;                 part += __shfl_xor(part, 16); part += __shfl_xor(part, 32);
;                 if (fq == 0) ssq_out[(size_t)row * 16 + u.pn * 4 + wc] = part; }
;             asm volatile("" ::: "memory"); }
	v_add_f32_e32 v247, v247, v252
	ds_bpermute_b32 v252, v237, v247
	s_waitcnt lgkmcnt(0)
	v_add_f32_e32 v247, v247, v252
	v_fmamk_f32 v247, v247, 0x3a800000, v193
	v_rsq_f32_e32 v247, v247
	s_nop 0
	v_mul_f32_e32 v253, 0xbfb8aa3b, v247
	v_mul_f32_e32 v12, v12, v253
	v_mul_f32_e32 v13, v13, v253
	v_mul_f32_e32 v14, v14, v253
	v_mul_f32_e32 v15, v15, v253
	v_exp_f32_e32 v12, v12
	v_exp_f32_e32 v13, v13
	v_exp_f32_e32 v14, v14
	v_exp_f32_e32 v15, v15
	v_add_f32_e32 v12, 1.0, v12
	v_add_f32_e32 v13, 1.0, v13
	v_add_f32_e32 v14, 1.0, v14
	v_add_f32_e32 v15, 1.0, v15
	v_rcp_f32_e32 v12, v12
	v_rcp_f32_e32 v13, v13
	v_rcp_f32_e32 v14, v14
	v_rcp_f32_e32 v15, v15
	v_lshlrev_b32_e32 v224, 16, v188
	v_and_b32_e32 v225, 0xffff0000, v188
	v_lshlrev_b32_e32 v226, 16, v189
	v_and_b32_e32 v227, 0xffff0000, v189
	v_lshlrev_b32_e32 v228, 16, v208
	v_and_b32_e32 v229, 0xffff0000, v208
	v_lshlrev_b32_e32 v230, 16, v209
	v_and_b32_e32 v231, 0xffff0000, v209
	v_fma_f32 v12, v12, v228, v224
	v_fma_f32 v13, v13, v229, v225
	v_fma_f32 v14, v14, v230, v226
	v_fma_f32 v15, v15, v231, v227
	v_mul_f32_e32 v232, v13, v13
	v_mul_f32_e32 v233, v15, v15
	v_fmac_f32_e32 v232, v12, v12
	v_fmac_f32_e32 v233, v14, v14
	v_add_f32_e32 v234, v232, v233
	v_mul_f32_e32 v8, v8, v253
	v_mul_f32_e32 v9, v9, v253
	v_mul_f32_e32 v10, v10, v253
	v_mul_f32_e32 v11, v11, v253
	v_exp_f32_e32 v8, v8
	v_exp_f32_e32 v9, v9
	v_exp_f32_e32 v10, v10
	v_exp_f32_e32 v11, v11
	v_add_f32_e32 v8, 1.0, v8
	v_add_f32_e32 v9, 1.0, v9
	v_add_f32_e32 v10, 1.0, v10
	v_add_f32_e32 v11, 1.0, v11
	v_rcp_f32_e32 v8, v8
	v_rcp_f32_e32 v9, v9
	v_rcp_f32_e32 v10, v10
	v_rcp_f32_e32 v11, v11
	v_lshlrev_b32_e32 v224, 16, v190
	v_and_b32_e32 v225, 0xffff0000, v190
	v_lshlrev_b32_e32 v226, 16, v191
	v_and_b32_e32 v227, 0xffff0000, v191
	v_lshlrev_b32_e32 v228, 16, v210
	v_and_b32_e32 v229, 0xffff0000, v210
	v_lshlrev_b32_e32 v230, 16, v211
	v_and_b32_e32 v231, 0xffff0000, v211
	v_fma_f32 v8, v8, v228, v224
	v_fma_f32 v9, v9, v229, v225
	v_fma_f32 v10, v10, v230, v226
	v_fma_f32 v11, v11, v231, v227
	v_mul_f32_e32 v232, v9, v9
	v_mul_f32_e32 v233, v11, v11
	v_fmac_f32_e32 v232, v8, v8
	v_fmac_f32_e32 v233, v10, v10
	v_add_f32_e32 v235, v232, v233
	v_cvt_pk_bf16_f32 v12, v12, v13
	v_cvt_pk_bf16_f32 v13, v14, v15
	v_cvt_pk_bf16_f32 v14, v8, v9
	v_cvt_pk_bf16_f32 v15, v10, v11
	v_add_u32_e32 v250, 0x58000, v172
	global_store_dwordx4 v250, v[12:15], s[0:1]
	v_mul_f32_e32 v4, v4, v253
	v_mul_f32_e32 v5, v5, v253
	v_mul_f32_e32 v6, v6, v253
	v_mul_f32_e32 v7, v7, v253
	v_exp_f32_e32 v4, v4
	v_exp_f32_e32 v5, v5
	v_exp_f32_e32 v6, v6
	v_exp_f32_e32 v7, v7
	v_add_f32_e32 v4, 1.0, v4
	v_add_f32_e32 v5, 1.0, v5
	v_add_f32_e32 v6, 1.0, v6
	v_add_f32_e32 v7, 1.0, v7
	v_rcp_f32_e32 v4, v4
	v_rcp_f32_e32 v5, v5
	v_rcp_f32_e32 v6, v6
	v_rcp_f32_e32 v7, v7
	v_lshlrev_b32_e32 v224, 16, v204
	v_and_b32_e32 v225, 0xffff0000, v204
	v_lshlrev_b32_e32 v226, 16, v205
	v_and_b32_e32 v227, 0xffff0000, v205
	v_lshlrev_b32_e32 v228, 16, v212
	v_and_b32_e32 v229, 0xffff0000, v212
	v_lshlrev_b32_e32 v230, 16, v213
	v_and_b32_e32 v231, 0xffff0000, v213
	v_fma_f32 v4, v4, v228, v224
	v_fma_f32 v5, v5, v229, v225
	v_fma_f32 v6, v6, v230, v226
	v_fma_f32 v7, v7, v231, v227
	v_mul_f32_e32 v232, v5, v5
	v_mul_f32_e32 v233, v7, v7
	v_fmac_f32_e32 v232, v4, v4
	v_fmac_f32_e32 v233, v6, v6
	v_add_f32_e32 v248, v232, v233
	v_mul_f32_e32 v0, v0, v253
	v_mul_f32_e32 v1, v1, v253
	v_mul_f32_e32 v2, v2, v253
	v_mul_f32_e32 v3, v3, v253
	v_exp_f32_e32 v0, v0
	v_exp_f32_e32 v1, v1
	v_exp_f32_e32 v2, v2
	v_exp_f32_e32 v3, v3
	v_add_f32_e32 v0, 1.0, v0
	v_add_f32_e32 v1, 1.0, v1
	v_add_f32_e32 v2, 1.0, v2
	v_add_f32_e32 v3, 1.0, v3
	v_rcp_f32_e32 v0, v0
	v_rcp_f32_e32 v1, v1
	v_rcp_f32_e32 v2, v2
	v_rcp_f32_e32 v3, v3
	v_lshlrev_b32_e32 v224, 16, v206
	v_and_b32_e32 v225, 0xffff0000, v206
	v_lshlrev_b32_e32 v226, 16, v207
	v_and_b32_e32 v227, 0xffff0000, v207
	v_lshlrev_b32_e32 v228, 16, v214
	v_and_b32_e32 v229, 0xffff0000, v214
	v_lshlrev_b32_e32 v230, 16, v215
	v_and_b32_e32 v231, 0xffff0000, v215
	v_fma_f32 v0, v0, v228, v224
	v_fma_f32 v1, v1, v229, v225
	v_fma_f32 v2, v2, v230, v226
	v_fma_f32 v3, v3, v231, v227
	v_mul_f32_e32 v232, v1, v1
	v_mul_f32_e32 v233, v3, v3
	v_fmac_f32_e32 v232, v0, v0
	v_fmac_f32_e32 v233, v2, v2
	v_add_f32_e32 v249, v232, v233
	v_cvt_pk_bf16_f32 v4, v4, v5
	v_cvt_pk_bf16_f32 v5, v6, v7
	v_cvt_pk_bf16_f32 v6, v0, v1
	v_cvt_pk_bf16_f32 v7, v2, v3
	global_store_dwordx4 v250, v[4:7], s[0:1] offset:256
	v_add_f32_e32 v234, v234, v235
	v_add_f32_e32 v248, v248, v249
	v_add_f32_e32 v247, v234, v248
	ds_bpermute_b32 v252, v236, v247
	v_add_u32_e32 v251, 0x2c00, v194
	s_waitcnt lgkmcnt(0)
	v_add_f32_e32 v247, v247, v252
	ds_bpermute_b32 v252, v237, v247
	s_waitcnt lgkmcnt(0)
	v_add_f32_e32 v247, v247, v252
	s_and_saveexec_b64 s[28:29], vcc
	global_store_dword v251, v247, s[12:13]
	s_or_b64 exec, exec, s[28:29]
	s_mov_b64 s[62:63], -1
	s_andn2_b64 vcc, exec, s[20:21]
	s_mov_b64 s[20:21], -1
	s_cbranch_vccnz .LBB0_1123
	s_andn2_b64 vcc, exec, s[8:9]
	s_cbranch_vccnz .LBB0_1122
	s_barrier
	s_branch .LBB0_1122
